# 4-phase GEMM loops (ph8 staging after M7), lgkmcnt(4) before first barrier in phases 1,3 and lgkmcnt(0) after
# speedup vs baseline: 1.0373x; 1.0081x over previous
; #define PG8_STAGE(bufoff, gbase, voff) do { _Pragma("unroll") for (int _i = 0; _i < 2; ++_i) \
;         __builtin_amdgcn_global_load_lds((const unsigned*)((const char*)(gbase) + (voff)[_i]), (LAS unsigned*)(lds + (bufoff) + ldsw + _i * 8192), 16, 0, 0); } while (0)
; #define PG8_LDA(dst, b, h) do { _Pragma("unroll") for (int m = 0; m < 4; ++m) _Pragma("unroll") for (int k = 0; k < 2; ++k) dst[m][k] = *(const LAS bf16x8*)(lds + PG8_SA(b, h) + aoff + m * 2048 + k * 1024); } while (0)
; #define PG8_LDB(dst, b, h) do { _Pragma("unroll") for (int n = 0; n < 2; ++n) _Pragma("unroll") for (int k = 0; k < 2; ++k) dst[n][k] = *(const LAS bf16x8*)(lds + PG8_SB(b, h) + boff + n * 2048 + k * 1024); } while (0)
; #define PG8_MMA(ai, bj, At, Bt) do { __builtin_amdgcn_s_setprio(1); _Pragma("unroll") for (int m = 0; m < 4; ++m) _Pragma("unroll") for (int n = 0; n < 2; ++n) _Pragma("unroll") for (int k = 0; k < 2; ++k) \
;         acc[ai][bj][m][n] = __builtin_amdgcn_mfma_f32_16x16x32_bf16(Bt[n][k], At[m][k], acc[ai][bj][m][n], 0, 0, 0); __builtin_amdgcn_s_setprio(0); } while (0)
; #define PG8_WAIT_V(n) asm volatile("s_waitcnt vmcnt(" #n ")" ::: "memory")
; #define PG8_WAIT_L(n) asm volatile("s_waitcnt lgkmcnt(" #n ")" ::: "memory")
; template <class Epi, class Sched>
; __device__ __forceinline__ void gemm_phase(LAS unsigned char* lds, const Gemm g, const Sched& S, const Epi& E) {
;     ...
;         for (int t = 0; t < nt; t += 2) {
;             const bool last = (t == nt - 2);
;             const char* a1 = cA + (size_t)(t + 1) * kstep;
;             const char* a2 = last ? nA : cA + (size_t)(t + 2) * kstep; const char* b2 = last ? nB : cB + (size_t)(t + 2) * kstep;
;             const char* a3 = a2 + kstep; const char* b3 = b2 + kstep;
;             PG8_LDB(B0, 0, 0); PG8_SCHED; PG8_LDA(At, 0, 0); PG8_STAGE(PG8_SA(1, 1), a1 + hstep, voffA);
;             PG8_WAIT_L(8); PG8_BAR; PG8_WAIT_L(0); PG8_MMA(0, 0, At, B0); PG8_BAR; PG8_SCHED;
;             PG8_LDB(B1, 0, 1); PG8_STAGE(PG8_SB(0, 0), b2, voffB);
;             PG8_BAR; PG8_WAIT_L(0); PG8_MMA(0, 1, At, B1); PG8_BAR;
;             PG8_LDA(At, 0, 1); PG8_STAGE(PG8_SA(0, 0), a2, voffA);
;             PG8_BAR; PG8_WAIT_L(0); PG8_MMA(1, 0, At, B0); PG8_BAR; PG8_SCHED;
;             PG8_STAGE(PG8_SB(0, 1), b2 + hstep, voffB);
;             PG8_WAIT_V(6); PG8_BAR; PG8_MMA(1, 1, At, B1); PG8_BAR;
.LBB0_44:
	s_add_u32 s50, s28, 0x100
	s_addc_u32 s51, s29, 0
	s_cmpk_eq_i32 s75, 0x7c
	s_cselect_b32 s55, s27, s51
	s_cselect_b32 s54, s71, s50
	s_cselect_b32 s53, s25, s74
	s_cselect_b32 s52, s72, s73
	v_lshl_add_u64 v[156:157], s[28:29], 0, v[150:151]
	s_add_i32 m0, s9, 0xc000
	s_nop 0
	global_load_lds_dwordx4 v[156:157], off
	v_lshl_add_u64 v[156:157], s[28:29], 0, v[148:149]
	s_add_i32 m0, s9, 0xe000
	s_nop 0
	global_load_lds_dwordx4 v[156:157], off
	s_add_i32 s38, 0, 0x10000
	v_add_u32_e32 v78, s38, v163
	ds_read_b128 v[66:69], v78
	ds_read_b128 v[70:73], v78 offset:1024
	ds_read_b128 v[74:77], v78 offset:2048
	ds_read_b128 v[78:81], v78 offset:3072
	ds_read_b128 v[152:155], v165
	ds_read_b128 v[166:169], v165 offset:1024
	ds_read_b128 v[170:173], v165 offset:2048
	ds_read_b128 v[174:177], v165 offset:3072
	ds_read_b128 v[178:181], v165 offset:4096
	ds_read_b128 v[182:185], v165 offset:5120
	ds_read_b128 v[186:189], v165 offset:6144
	ds_read_b128 v[190:193], v165 offset:7168
	s_add_i32 s39, 0, 0x14000
	v_add_u32_e32 v156, s39, v163
	ds_read_b128 v[194:197], v156
	ds_read_b128 v[198:201], v156 offset:1024
	ds_read_b128 v[202:205], v156 offset:2048
	ds_read_b128 v[210:213], v156 offset:3072
	s_waitcnt lgkmcnt(4)
	s_barrier
	s_waitcnt lgkmcnt(0)
	s_setprio 1
	v_mfma_f32_16x16x32_bf16 v[142:145], v[66:69], v[152:155], v[142:145]
	v_mfma_f32_16x16x32_bf16 v[138:141], v[74:77], v[152:155], v[138:141]
	v_mfma_f32_16x16x32_bf16 v[126:129], v[66:69], v[170:173], v[126:129]
	v_mfma_f32_16x16x32_bf16 v[122:125], v[74:77], v[170:173], v[122:125]
	v_mfma_f32_16x16x32_bf16 v[110:113], v[66:69], v[178:181], v[110:113]
	v_mfma_f32_16x16x32_bf16 v[106:109], v[74:77], v[178:181], v[106:109]
	v_mfma_f32_16x16x32_bf16 v[102:105], v[66:69], v[186:189], v[102:105]
	v_mfma_f32_16x16x32_bf16 v[98:101], v[74:77], v[186:189], v[98:101]
	v_mfma_f32_16x16x32_bf16 v[142:145], v[70:73], v[166:169], v[142:145]
	v_mfma_f32_16x16x32_bf16 v[138:141], v[78:81], v[166:169], v[138:141]
	v_mfma_f32_16x16x32_bf16 v[126:129], v[70:73], v[174:177], v[126:129]
	v_mfma_f32_16x16x32_bf16 v[122:125], v[78:81], v[174:177], v[122:125]
	v_mfma_f32_16x16x32_bf16 v[110:113], v[70:73], v[182:185], v[110:113]
	v_mfma_f32_16x16x32_bf16 v[106:109], v[78:81], v[182:185], v[106:109]
	v_mfma_f32_16x16x32_bf16 v[102:105], v[70:73], v[190:193], v[102:105]
	v_mfma_f32_16x16x32_bf16 v[98:101], v[78:81], v[190:193], v[98:101]
	v_mfma_f32_16x16x32_bf16 v[134:137], v[194:197], v[152:155], v[134:137]
	v_mfma_f32_16x16x32_bf16 v[130:133], v[202:205], v[152:155], v[130:133]
	v_mfma_f32_16x16x32_bf16 v[118:121], v[194:197], v[170:173], v[118:121]
	v_mfma_f32_16x16x32_bf16 v[114:117], v[202:205], v[170:173], v[114:117]
	v_mfma_f32_16x16x32_bf16 v[94:97], v[194:197], v[178:181], v[94:97]
	v_mfma_f32_16x16x32_bf16 v[90:93], v[202:205], v[178:181], v[90:93]
	v_mfma_f32_16x16x32_bf16 v[86:89], v[194:197], v[186:189], v[86:89]
	v_mfma_f32_16x16x32_bf16 v[82:85], v[202:205], v[186:189], v[82:85]
	v_mfma_f32_16x16x32_bf16 v[134:137], v[198:201], v[166:169], v[134:137]
	v_mfma_f32_16x16x32_bf16 v[130:133], v[210:213], v[166:169], v[130:133]
	v_mfma_f32_16x16x32_bf16 v[118:121], v[198:201], v[174:177], v[118:121]
	v_mfma_f32_16x16x32_bf16 v[114:117], v[210:213], v[174:177], v[114:117]
	v_mfma_f32_16x16x32_bf16 v[94:97], v[198:201], v[182:185], v[94:97]
	v_mfma_f32_16x16x32_bf16 v[90:93], v[210:213], v[182:185], v[90:93]
	v_mfma_f32_16x16x32_bf16 v[86:89], v[198:201], v[190:193], v[86:89]
	v_mfma_f32_16x16x32_bf16 v[82:85], v[210:213], v[190:193], v[82:85]
	s_setprio 0
	s_barrier
	s_add_i32 s28, s38, s60
	v_lshl_add_u64 v[156:157], s[52:53], 0, v[0:1]
	s_mov_b32 m0, s28
	v_lshl_add_u64 v[160:161], s[52:53], 0, v[146:147]
	global_load_lds_dwordx4 v[156:157], off
	s_add_i32 m0, s28, 0x2000
	s_nop 0
	global_load_lds_dwordx4 v[160:161], off
	s_mov_b32 m0, s9
	v_lshl_add_u64 v[206:207], s[54:55], 0, v[0:1]
	global_load_lds_dwordx4 v[206:207], off
	v_lshl_add_u64 v[214:215], s[54:55], 0, v[146:147]
	s_mov_b32 m0, s61
	s_nop 0
	global_load_lds_dwordx4 v[214:215], off
	ds_read_b128 v[152:155], v165 offset:16384
	ds_read_b128 v[166:169], v165 offset:17408
	ds_read_b128 v[170:173], v165 offset:18432
	ds_read_b128 v[174:177], v165 offset:19456
	ds_read_b128 v[178:181], v165 offset:20480
	ds_read_b128 v[182:185], v165 offset:21504
	ds_read_b128 v[186:189], v165 offset:22528
	ds_read_b128 v[190:193], v165 offset:23552
	s_waitcnt vmcnt(4)
	s_waitcnt lgkmcnt(0)
	s_barrier
	s_setprio 1
	v_mfma_f32_16x16x32_bf16 v[62:65], v[66:69], v[152:155], v[62:65]
	v_mfma_f32_16x16x32_bf16 v[58:61], v[74:77], v[152:155], v[58:61]
	v_mfma_f32_16x16x32_bf16 v[46:49], v[66:69], v[170:173], v[46:49]
	v_mfma_f32_16x16x32_bf16 v[42:45], v[74:77], v[170:173], v[42:45]
	v_mfma_f32_16x16x32_bf16 v[30:33], v[66:69], v[178:181], v[30:33]
	v_mfma_f32_16x16x32_bf16 v[26:29], v[74:77], v[178:181], v[26:29]
	v_mfma_f32_16x16x32_bf16 v[22:25], v[66:69], v[186:189], v[22:25]
	v_mfma_f32_16x16x32_bf16 v[14:17], v[74:77], v[186:189], v[14:17]
	v_mfma_f32_16x16x32_bf16 v[62:65], v[70:73], v[166:169], v[62:65]
	v_mfma_f32_16x16x32_bf16 v[58:61], v[78:81], v[166:169], v[58:61]
	v_mfma_f32_16x16x32_bf16 v[46:49], v[70:73], v[174:177], v[46:49]
	v_mfma_f32_16x16x32_bf16 v[42:45], v[78:81], v[174:177], v[42:45]
	v_mfma_f32_16x16x32_bf16 v[30:33], v[70:73], v[182:185], v[30:33]
	v_mfma_f32_16x16x32_bf16 v[26:29], v[78:81], v[182:185], v[26:29]
	v_mfma_f32_16x16x32_bf16 v[22:25], v[70:73], v[190:193], v[22:25]
	v_mfma_f32_16x16x32_bf16 v[14:17], v[78:81], v[190:193], v[14:17]
	v_mfma_f32_16x16x32_bf16 v[54:57], v[194:197], v[152:155], v[54:57]
	v_mfma_f32_16x16x32_bf16 v[50:53], v[202:205], v[152:155], v[50:53]
	v_mfma_f32_16x16x32_bf16 v[38:41], v[194:197], v[170:173], v[38:41]
	v_mfma_f32_16x16x32_bf16 v[34:37], v[202:205], v[170:173], v[34:37]
	v_mfma_f32_16x16x32_bf16 v[18:21], v[194:197], v[178:181], v[18:21]
	v_mfma_f32_16x16x32_bf16 v[10:13], v[202:205], v[178:181], v[10:13]
	v_mfma_f32_16x16x32_bf16 v[6:9], v[194:197], v[186:189], v[6:9]
	v_mfma_f32_16x16x32_bf16 v[2:5], v[202:205], v[186:189], v[2:5]
	v_mfma_f32_16x16x32_bf16 v[54:57], v[198:201], v[166:169], v[54:57]
	v_mfma_f32_16x16x32_bf16 v[50:53], v[210:213], v[166:169], v[50:53]
	v_mfma_f32_16x16x32_bf16 v[38:41], v[198:201], v[174:177], v[38:41]
	v_mfma_f32_16x16x32_bf16 v[34:37], v[210:213], v[174:177], v[34:37]
	v_mfma_f32_16x16x32_bf16 v[18:21], v[198:201], v[182:185], v[18:21]
	v_mfma_f32_16x16x32_bf16 v[10:13], v[210:213], v[182:185], v[10:13]
	v_mfma_f32_16x16x32_bf16 v[6:9], v[198:201], v[190:193], v[6:9]
	v_mfma_f32_16x16x32_bf16 v[2:5], v[210:213], v[190:193], v[2:5]
	s_setprio 0
	s_barrier
; #define PG8_STAGE(bufoff, gbase, voff) do { _Pragma("unroll") for (int _i = 0; _i < 2; ++_i) \
;         __builtin_amdgcn_global_load_lds((const unsigned*)((const char*)(gbase) + (voff)[_i]), (LAS unsigned*)(lds + (bufoff) + ldsw + _i * 8192), 16, 0, 0); } while (0)
; #define PG8_LDA(dst, b, h) do { _Pragma("unroll") for (int m = 0; m < 4; ++m) _Pragma("unroll") for (int k = 0; k < 2; ++k) dst[m][k] = *(const LAS bf16x8*)(lds + PG8_SA(b, h) + aoff + m * 2048 + k * 1024); } while (0)
; #define PG8_LDB(dst, b, h) do { _Pragma("unroll") for (int n = 0; n < 2; ++n) _Pragma("unroll") for (int k = 0; k < 2; ++k) dst[n][k] = *(const LAS bf16x8*)(lds + PG8_SB(b, h) + boff + n * 2048 + k * 1024); } while (0)
; #define PG8_MMA(ai, bj, At, Bt) do { __builtin_amdgcn_s_setprio(1); _Pragma("unroll") for (int m = 0; m < 4; ++m) _Pragma("unroll") for (int n = 0; n < 2; ++n) _Pragma("unroll") for (int k = 0; k < 2; ++k) \
;         acc[ai][bj][m][n] = __builtin_amdgcn_mfma_f32_16x16x32_bf16(Bt[n][k], At[m][k], acc[ai][bj][m][n], 0, 0, 0); __builtin_amdgcn_s_setprio(0); } while (0)
; #define PG8_WAIT_L(n) asm volatile("s_waitcnt lgkmcnt(" #n ")" ::: "memory")
; #define PG8_BAR __builtin_amdgcn_s_barrier()
; #define PG8_SCHED __builtin_amdgcn_sched_barrier(0)
; template <class Epi, class Sched>
; __device__ __forceinline__ void gemm_phase(LAS unsigned char* lds, const Gemm g, const Sched& S, const Epi& E) {
;     ...
;             PG8_LDB(B0, 1, 0); PG8_SCHED; PG8_LDA(At, 1, 0); PG8_STAGE(PG8_SA(0, 1), a2 + hstep, voffA);
;             PG8_WAIT_L(8); PG8_BAR; PG8_WAIT_L(0); PG8_MMA(0, 0, At, B0); PG8_BAR; PG8_SCHED;
;             PG8_LDB(B1, 1, 1); PG8_STAGE(PG8_SB(1, 0), b3, voffB);
;             PG8_BAR; PG8_WAIT_L(0); PG8_MMA(0, 1, At, B1); PG8_BAR;
;             PG8_LDA(At, 1, 1); PG8_STAGE(PG8_SA(1, 0), a3, voffA);
;             PG8_BAR; PG8_WAIT_L(0); PG8_MMA(1, 0, At, B0); PG8_BAR; PG8_SCHED;
	s_add_u32 s28, s52, 0x200000
	s_addc_u32 s29, s53, 0
	s_add_i32 s38, s39, s60
	v_lshl_add_u64 v[66:67], s[28:29], 0, v[0:1]
	s_mov_b32 m0, s38
	s_nop 0
	global_load_lds_dwordx4 v[66:67], off
	v_lshl_add_u64 v[66:67], s[28:29], 0, v[146:147]
	s_add_i32 m0, s38, 0x2000
	s_nop 0
	global_load_lds_dwordx4 v[66:67], off
	s_add_u32 s28, s54, 0x200000
	s_addc_u32 s29, s55, 0
	s_mov_b32 m0, s62
	v_lshl_add_u64 v[194:195], s[28:29], 0, v[0:1]
	global_load_lds_dwordx4 v[194:195], off
	v_lshl_add_u64 v[194:195], s[28:29], 0, v[146:147]
	s_mov_b32 m0, s63
	s_nop 0
	global_load_lds_dwordx4 v[194:195], off
	s_add_i32 s38, 0, 0x18000
	v_add_u32_e32 v78, s38, v163
	ds_read_b128 v[66:69], v78
	ds_read_b128 v[70:73], v78 offset:1024
	ds_read_b128 v[74:77], v78 offset:2048
	ds_read_b128 v[78:81], v78 offset:3072
	ds_read_b128 v[152:155], v165 offset:32768
	ds_read_b128 v[166:169], v165 offset:33792
	ds_read_b128 v[170:173], v165 offset:34816
	ds_read_b128 v[174:177], v165 offset:35840
	ds_read_b128 v[178:181], v165 offset:36864
	ds_read_b128 v[182:185], v165 offset:37888
	ds_read_b128 v[186:189], v165 offset:38912
	ds_read_b128 v[190:193], v165 offset:39936
	s_add_i32 s39, 0, 0x1c000
	v_add_u32_e32 v210, s39, v163
	ds_read_b128 v[194:197], v210
	ds_read_b128 v[198:201], v210 offset:1024
	ds_read_b128 v[202:205], v210 offset:2048
	ds_read_b128 v[210:213], v210 offset:3072
	s_waitcnt lgkmcnt(4)
	s_barrier
	s_waitcnt lgkmcnt(0)
	s_setprio 1
	v_mfma_f32_16x16x32_bf16 v[142:145], v[66:69], v[152:155], v[142:145]
	v_mfma_f32_16x16x32_bf16 v[138:141], v[74:77], v[152:155], v[138:141]
	v_mfma_f32_16x16x32_bf16 v[126:129], v[66:69], v[170:173], v[126:129]
	v_mfma_f32_16x16x32_bf16 v[122:125], v[74:77], v[170:173], v[122:125]
	v_mfma_f32_16x16x32_bf16 v[110:113], v[66:69], v[178:181], v[110:113]
	v_mfma_f32_16x16x32_bf16 v[106:109], v[74:77], v[178:181], v[106:109]
	v_mfma_f32_16x16x32_bf16 v[102:105], v[66:69], v[186:189], v[102:105]
	v_mfma_f32_16x16x32_bf16 v[98:101], v[74:77], v[186:189], v[98:101]
	v_mfma_f32_16x16x32_bf16 v[142:145], v[70:73], v[166:169], v[142:145]
	v_mfma_f32_16x16x32_bf16 v[138:141], v[78:81], v[166:169], v[138:141]
	v_mfma_f32_16x16x32_bf16 v[126:129], v[70:73], v[174:177], v[126:129]
	v_mfma_f32_16x16x32_bf16 v[122:125], v[78:81], v[174:177], v[122:125]
	v_mfma_f32_16x16x32_bf16 v[110:113], v[70:73], v[182:185], v[110:113]
	v_mfma_f32_16x16x32_bf16 v[106:109], v[78:81], v[182:185], v[106:109]
	v_mfma_f32_16x16x32_bf16 v[102:105], v[70:73], v[190:193], v[102:105]
	v_mfma_f32_16x16x32_bf16 v[98:101], v[78:81], v[190:193], v[98:101]
	v_mfma_f32_16x16x32_bf16 v[134:137], v[194:197], v[152:155], v[134:137]
	v_mfma_f32_16x16x32_bf16 v[130:133], v[202:205], v[152:155], v[130:133]
	v_mfma_f32_16x16x32_bf16 v[118:121], v[194:197], v[170:173], v[118:121]
	v_mfma_f32_16x16x32_bf16 v[114:117], v[202:205], v[170:173], v[114:117]
	v_mfma_f32_16x16x32_bf16 v[94:97], v[194:197], v[178:181], v[94:97]
	v_mfma_f32_16x16x32_bf16 v[90:93], v[202:205], v[178:181], v[90:93]
	v_mfma_f32_16x16x32_bf16 v[86:89], v[194:197], v[186:189], v[86:89]
	v_mfma_f32_16x16x32_bf16 v[82:85], v[202:205], v[186:189], v[82:85]
	v_mfma_f32_16x16x32_bf16 v[134:137], v[198:201], v[166:169], v[134:137]
	v_mfma_f32_16x16x32_bf16 v[130:133], v[210:213], v[166:169], v[130:133]
	v_mfma_f32_16x16x32_bf16 v[118:121], v[198:201], v[174:177], v[118:121]
	v_mfma_f32_16x16x32_bf16 v[114:117], v[210:213], v[174:177], v[114:117]
	v_mfma_f32_16x16x32_bf16 v[94:97], v[198:201], v[182:185], v[94:97]
	v_mfma_f32_16x16x32_bf16 v[90:93], v[210:213], v[182:185], v[90:93]
	v_mfma_f32_16x16x32_bf16 v[86:89], v[198:201], v[190:193], v[86:89]
	v_mfma_f32_16x16x32_bf16 v[82:85], v[210:213], v[190:193], v[82:85]
	s_setprio 0
	s_barrier
; #define PG8_STAGE(bufoff, gbase, voff) do { _Pragma("unroll") for (int _i = 0; _i < 2; ++_i) \
;         __builtin_amdgcn_global_load_lds((const unsigned*)((const char*)(gbase) + (voff)[_i]), (LAS unsigned*)(lds + (bufoff) + ldsw + _i * 8192), 16, 0, 0); } while (0)
; #define PG8_MMA(ai, bj, At, Bt) do { __builtin_amdgcn_s_setprio(1); _Pragma("unroll") for (int m = 0; m < 4; ++m) _Pragma("unroll") for (int n = 0; n < 2; ++n) _Pragma("unroll") for (int k = 0; k < 2; ++k) \
;         acc[ai][bj][m][n] = __builtin_amdgcn_mfma_f32_16x16x32_bf16(Bt[n][k], At[m][k], acc[ai][bj][m][n], 0, 0, 0); __builtin_amdgcn_s_setprio(0); } while (0)
; #define PG8_WAIT_V(n) asm volatile("s_waitcnt vmcnt(" #n ")" ::: "memory")
; #define PG8_BAR __builtin_amdgcn_s_barrier()
;     __device__ __forceinline__ void operator()(const f32x4 (&acc)[2][2][4][2], const Unit& u, int wr, int wc, int fr, int fq) const {
;         const bool lat = u.pm < 64; const int r = lat ? (u.pm >> 3) : 8;
;         const float* s = lat ? src_lat : src_ctx; float* d = lat ? dst_lat : dst_ctx;
;         const int row0 = (lat ? u.pm : u.pm - 64) * BM + wr * 64 + fr, col0 = u.pn * BM + wc * 32 + 4 * fq;
; template <class Epi, class Sched>
; __device__ __forceinline__ void gemm_phase(LAS unsigned char* lds, const Gemm g, const Sched& S, const Epi& E) {
;     ...
;             PG8_STAGE(PG8_SB(1, 1), b3 + hstep, voffB);
;             PG8_WAIT_V(6); PG8_BAR; PG8_MMA(1, 1, At, B1); PG8_BAR;
;         }
	s_add_i32 s28, s38, s60
	v_lshl_add_u64 v[156:157], v[156:157], 0, s[36:37]
	s_mov_b32 m0, s28
	s_nop 0
	global_load_lds_dwordx4 v[156:157], off
	v_lshl_add_u64 v[156:157], v[160:161], 0, s[36:37]
	s_add_i32 m0, s28, 0x2000
	s_nop 0
	global_load_lds_dwordx4 v[156:157], off
	s_mov_b32 m0, s66
	v_lshl_add_u64 v[156:157], v[206:207], 0, s[36:37]
	global_load_lds_dwordx4 v[156:157], off
	v_lshl_add_u64 v[156:157], v[214:215], 0, s[36:37]
	s_mov_b32 m0, s67
	s_nop 0
	global_load_lds_dwordx4 v[156:157], off
	ds_read_b128 v[152:155], v165 offset:49152
	ds_read_b128 v[166:169], v165 offset:50176
	ds_read_b128 v[170:173], v165 offset:51200
	ds_read_b128 v[174:177], v165 offset:52224
	ds_read_b128 v[178:181], v165 offset:53248
	ds_read_b128 v[182:185], v165 offset:54272
	ds_read_b128 v[186:189], v165 offset:55296
	ds_read_b128 v[190:193], v165 offset:56320
	s_waitcnt vmcnt(4)
	s_waitcnt lgkmcnt(0)
	s_barrier
	s_setprio 1
	v_mfma_f32_16x16x32_bf16 v[62:65], v[66:69], v[152:155], v[62:65]
	v_mfma_f32_16x16x32_bf16 v[58:61], v[74:77], v[152:155], v[58:61]
	v_mfma_f32_16x16x32_bf16 v[46:49], v[66:69], v[170:173], v[46:49]
	v_mfma_f32_16x16x32_bf16 v[42:45], v[74:77], v[170:173], v[42:45]
	v_mfma_f32_16x16x32_bf16 v[30:33], v[66:69], v[178:181], v[30:33]
	v_mfma_f32_16x16x32_bf16 v[26:29], v[74:77], v[178:181], v[26:29]
	v_mfma_f32_16x16x32_bf16 v[22:25], v[66:69], v[186:189], v[22:25]
	v_mfma_f32_16x16x32_bf16 v[14:17], v[74:77], v[186:189], v[14:17]
	v_mfma_f32_16x16x32_bf16 v[62:65], v[70:73], v[166:169], v[62:65]
	v_mfma_f32_16x16x32_bf16 v[58:61], v[78:81], v[166:169], v[58:61]
	v_mfma_f32_16x16x32_bf16 v[46:49], v[70:73], v[174:177], v[46:49]
	v_mfma_f32_16x16x32_bf16 v[42:45], v[78:81], v[174:177], v[42:45]
	v_mfma_f32_16x16x32_bf16 v[30:33], v[70:73], v[182:185], v[30:33]
	v_mfma_f32_16x16x32_bf16 v[26:29], v[78:81], v[182:185], v[26:29]
	v_mfma_f32_16x16x32_bf16 v[22:25], v[70:73], v[190:193], v[22:25]
	v_mfma_f32_16x16x32_bf16 v[14:17], v[78:81], v[190:193], v[14:17]
	s_add_u32 s28, s52, 0x200080
	s_addc_u32 s29, s53, 0
	s_add_i32 s38, s39, s60
	v_lshl_add_u64 v[66:67], s[28:29], 0, v[0:1]
	s_mov_b32 m0, s38
	s_nop 0
	global_load_lds_dwordx4 v[66:67], off
	v_lshl_add_u64 v[66:67], s[28:29], 0, v[146:147]
	s_add_i32 m0, s38, 0x2000
	s_nop 0
	global_load_lds_dwordx4 v[66:67], off
	v_mfma_f32_16x16x32_bf16 v[54:57], v[194:197], v[152:155], v[54:57]
	v_mfma_f32_16x16x32_bf16 v[50:53], v[202:205], v[152:155], v[50:53]
	v_mfma_f32_16x16x32_bf16 v[38:41], v[194:197], v[170:173], v[38:41]
	v_mfma_f32_16x16x32_bf16 v[34:37], v[202:205], v[170:173], v[34:37]
	v_mfma_f32_16x16x32_bf16 v[18:21], v[194:197], v[178:181], v[18:21]
	v_mfma_f32_16x16x32_bf16 v[10:13], v[202:205], v[178:181], v[10:13]
	v_mfma_f32_16x16x32_bf16 v[6:9], v[194:197], v[186:189], v[6:9]
	v_mfma_f32_16x16x32_bf16 v[2:5], v[202:205], v[186:189], v[2:5]
	v_mfma_f32_16x16x32_bf16 v[54:57], v[198:201], v[166:169], v[54:57]
	v_mfma_f32_16x16x32_bf16 v[50:53], v[210:213], v[166:169], v[50:53]
	v_mfma_f32_16x16x32_bf16 v[38:41], v[198:201], v[174:177], v[38:41]
	v_mfma_f32_16x16x32_bf16 v[34:37], v[210:213], v[174:177], v[34:37]
	v_mfma_f32_16x16x32_bf16 v[18:21], v[198:201], v[182:185], v[18:21]
	v_mfma_f32_16x16x32_bf16 v[10:13], v[210:213], v[182:185], v[10:13]
	v_mfma_f32_16x16x32_bf16 v[6:9], v[198:201], v[190:193], v[6:9]
	v_mfma_f32_16x16x32_bf16 v[2:5], v[210:213], v[190:193], v[2:5]
	s_setprio 0
	s_add_i32 s75, s75, 2
	s_add_u32 s73, s73, 0x100
	s_addc_u32 s74, s74, 0
	s_cmpk_gt_u32 s75, 0x7d
	s_mov_b64 s[28:29], s[50:51]
	s_barrier
	s_cbranch_scc0 .LBB0_44
	s_cmp_lt_i32 s8, 64
	s_cselect_b64 s[50:51], -1, 0
	s_cmp_gt_i32 s8, 63
	s_cbranch_scc0 .LBB0_35
	s_mov_b64 s[52:53], 0x18000
	s_mov_b64 s[28:29], s[46:47]
	s_branch .LBB0_36

; #define PG8_STAGE(bufoff, gbase, voff) do { _Pragma("unroll") for (int _i = 0; _i < 2; ++_i) \
;         __builtin_amdgcn_global_load_lds((const unsigned*)((const char*)(gbase) + (voff)[_i]), (LAS unsigned*)(lds + (bufoff) + ldsw + _i * 8192), 16, 0, 0); } while (0)
; #define PG8_LDA(dst, b, h) do { _Pragma("unroll") for (int m = 0; m < 4; ++m) _Pragma("unroll") for (int k = 0; k < 2; ++k) dst[m][k] = *(const LAS bf16x8*)(lds + PG8_SA(b, h) + aoff + m * 2048 + k * 1024); } while (0)
; #define PG8_LDB(dst, b, h) do { _Pragma("unroll") for (int n = 0; n < 2; ++n) _Pragma("unroll") for (int k = 0; k < 2; ++k) dst[n][k] = *(const LAS bf16x8*)(lds + PG8_SB(b, h) + boff + n * 2048 + k * 1024); } while (0)
; #define PG8_MMA(ai, bj, At, Bt) do { __builtin_amdgcn_s_setprio(1); _Pragma("unroll") for (int m = 0; m < 4; ++m) _Pragma("unroll") for (int n = 0; n < 2; ++n) _Pragma("unroll") for (int k = 0; k < 2; ++k) \
;         acc[ai][bj][m][n] = __builtin_amdgcn_mfma_f32_16x16x32_bf16(Bt[n][k], At[m][k], acc[ai][bj][m][n], 0, 0, 0); __builtin_amdgcn_s_setprio(0); } while (0)
; #define PG8_WAIT_V(n) asm volatile("s_waitcnt vmcnt(" #n ")" ::: "memory")
; #define PG8_WAIT_L(n) asm volatile("s_waitcnt lgkmcnt(" #n ")" ::: "memory")
; template <class Epi, class Sched>
; __device__ __forceinline__ void gemm_phase(LAS unsigned char* lds, const Gemm g, const Sched& S, const Epi& E) {
;     ...
;         for (int t = 0; t < nt; t += 2) {
;             const bool last = (t == nt - 2);
;             const char* a1 = cA + (size_t)(t + 1) * kstep;
;             const char* a2 = last ? nA : cA + (size_t)(t + 2) * kstep; const char* b2 = last ? nB : cB + (size_t)(t + 2) * kstep;
;             const char* a3 = a2 + kstep; const char* b3 = b2 + kstep;
;             PG8_LDB(B0, 0, 0); PG8_SCHED; PG8_LDA(At, 0, 0); PG8_STAGE(PG8_SA(1, 1), a1 + hstep, voffA);
;             PG8_WAIT_L(8); PG8_BAR; PG8_WAIT_L(0); PG8_MMA(0, 0, At, B0); PG8_BAR; PG8_SCHED;
;             PG8_LDB(B1, 0, 1); PG8_STAGE(PG8_SB(0, 0), b2, voffB);
;             PG8_BAR; PG8_WAIT_L(0); PG8_MMA(0, 1, At, B1); PG8_BAR;
;             PG8_LDA(At, 0, 1); PG8_STAGE(PG8_SA(0, 0), a2, voffA);
;             PG8_BAR; PG8_WAIT_L(0); PG8_MMA(1, 0, At, B0); PG8_BAR; PG8_SCHED;
;             PG8_STAGE(PG8_SB(0, 1), b2 + hstep, voffB);
;             PG8_WAIT_V(6); PG8_BAR; PG8_MMA(1, 1, At, B1); PG8_BAR;
.LBB0_58:
	s_add_u32 s52, s50, 0x100
	s_addc_u32 s53, s51, 0
	s_cmp_eq_u32 s71, 28
	s_cselect_b32 s57, s11, s53
	s_cselect_b32 s56, s29, s52
	s_cselect_b32 s55, s41, s70
	s_cselect_b32 s54, s43, s69
	v_lshl_add_u64 v[156:157], s[50:51], 0, v[134:135]
	s_add_i32 m0, s25, 0xc000
	s_nop 0
	global_load_lds_dwordx4 v[156:157], off
	v_lshl_add_u64 v[156:157], s[50:51], 0, v[132:133]
	s_add_i32 m0, s25, 0xe000
	s_nop 0
	global_load_lds_dwordx4 v[156:157], off
	s_add_i32 s38, 0, 0x10000
	v_add_u32_e32 v152, s38, v137
	ds_read_b128 v[140:143], v152
	ds_read_b128 v[144:147], v152 offset:1024
	ds_read_b128 v[148:151], v152 offset:2048
	ds_read_b128 v[152:155], v152 offset:3072
	ds_read_b128 v[160:163], v139
	ds_read_b128 v[164:167], v139 offset:1024
	ds_read_b128 v[168:171], v139 offset:2048
	ds_read_b128 v[172:175], v139 offset:3072
	ds_read_b128 v[176:179], v139 offset:4096
	ds_read_b128 v[180:183], v139 offset:5120
	ds_read_b128 v[184:187], v139 offset:6144
	ds_read_b128 v[188:191], v139 offset:7168
	s_add_i32 s50, 0, 0x14000
	v_add_u32_e32 v156, s50, v137
	ds_read_b128 v[192:195], v156
	ds_read_b128 v[196:199], v156 offset:1024
	ds_read_b128 v[200:203], v156 offset:2048
	ds_read_b128 v[204:207], v156 offset:3072
	s_waitcnt lgkmcnt(4)
	s_barrier
	s_waitcnt lgkmcnt(0)
	s_setprio 1
	v_mfma_f32_16x16x32_bf16 v[126:129], v[140:143], v[160:163], v[126:129]
	v_mfma_f32_16x16x32_bf16 v[122:125], v[148:151], v[160:163], v[122:125]
	v_mfma_f32_16x16x32_bf16 v[118:121], v[140:143], v[168:171], v[118:121]
	v_mfma_f32_16x16x32_bf16 v[114:117], v[148:151], v[168:171], v[114:117]
	v_mfma_f32_16x16x32_bf16 v[106:109], v[140:143], v[176:179], v[106:109]
	v_mfma_f32_16x16x32_bf16 v[98:101], v[148:151], v[176:179], v[98:101]
	v_mfma_f32_16x16x32_bf16 v[90:93], v[140:143], v[184:187], v[90:93]
	v_mfma_f32_16x16x32_bf16 v[82:85], v[148:151], v[184:187], v[82:85]
	v_mfma_f32_16x16x32_bf16 v[126:129], v[144:147], v[164:167], v[126:129]
	v_mfma_f32_16x16x32_bf16 v[122:125], v[152:155], v[164:167], v[122:125]
	v_mfma_f32_16x16x32_bf16 v[118:121], v[144:147], v[172:175], v[118:121]
	v_mfma_f32_16x16x32_bf16 v[114:117], v[152:155], v[172:175], v[114:117]
	v_mfma_f32_16x16x32_bf16 v[106:109], v[144:147], v[180:183], v[106:109]
	v_mfma_f32_16x16x32_bf16 v[98:101], v[152:155], v[180:183], v[98:101]
	v_mfma_f32_16x16x32_bf16 v[90:93], v[144:147], v[188:191], v[90:93]
	v_mfma_f32_16x16x32_bf16 v[82:85], v[152:155], v[188:191], v[82:85]
	v_mfma_f32_16x16x32_bf16 v[110:113], v[192:195], v[160:163], v[110:113]
	v_mfma_f32_16x16x32_bf16 v[102:105], v[200:203], v[160:163], v[102:105]
	v_mfma_f32_16x16x32_bf16 v[94:97], v[192:195], v[168:171], v[94:97]
	v_mfma_f32_16x16x32_bf16 v[86:89], v[200:203], v[168:171], v[86:89]
	v_mfma_f32_16x16x32_bf16 v[78:81], v[192:195], v[176:179], v[78:81]
	v_mfma_f32_16x16x32_bf16 v[74:77], v[200:203], v[176:179], v[74:77]
	v_mfma_f32_16x16x32_bf16 v[70:73], v[192:195], v[184:187], v[70:73]
	v_mfma_f32_16x16x32_bf16 v[66:69], v[200:203], v[184:187], v[66:69]
	v_mfma_f32_16x16x32_bf16 v[110:113], v[196:199], v[164:167], v[110:113]
	v_mfma_f32_16x16x32_bf16 v[102:105], v[204:207], v[164:167], v[102:105]
	v_mfma_f32_16x16x32_bf16 v[94:97], v[196:199], v[172:175], v[94:97]
	v_mfma_f32_16x16x32_bf16 v[86:89], v[204:207], v[172:175], v[86:89]
	v_mfma_f32_16x16x32_bf16 v[78:81], v[196:199], v[180:183], v[78:81]
	v_mfma_f32_16x16x32_bf16 v[74:77], v[204:207], v[180:183], v[74:77]
	v_mfma_f32_16x16x32_bf16 v[70:73], v[196:199], v[188:191], v[70:73]
	v_mfma_f32_16x16x32_bf16 v[66:69], v[204:207], v[188:191], v[66:69]
	s_setprio 0
	s_barrier
	s_add_i32 s38, s38, s63
	v_lshl_add_u64 v[156:157], s[54:55], 0, v[0:1]
	s_mov_b32 m0, s38
	v_lshl_add_u64 v[210:211], s[54:55], 0, v[130:131]
	global_load_lds_dwordx4 v[156:157], off
	s_add_i32 m0, s38, 0x2000
	s_nop 0
	global_load_lds_dwordx4 v[210:211], off
	s_mov_b32 m0, s25
	v_lshl_add_u64 v[212:213], s[56:57], 0, v[0:1]
	global_load_lds_dwordx4 v[212:213], off
	v_lshl_add_u64 v[214:215], s[56:57], 0, v[130:131]
	s_mov_b32 m0, s27
	s_nop 0
	global_load_lds_dwordx4 v[214:215], off
	ds_read_b128 v[160:163], v139 offset:16384
	ds_read_b128 v[164:167], v139 offset:17408
	ds_read_b128 v[168:171], v139 offset:18432
	ds_read_b128 v[172:175], v139 offset:19456
	ds_read_b128 v[176:179], v139 offset:20480
	ds_read_b128 v[180:183], v139 offset:21504
	ds_read_b128 v[184:187], v139 offset:22528
	ds_read_b128 v[188:191], v139 offset:23552
	s_waitcnt vmcnt(4)
	s_waitcnt lgkmcnt(0)
	s_barrier
	s_setprio 1
	v_mfma_f32_16x16x32_bf16 v[62:65], v[140:143], v[160:163], v[62:65]
	v_mfma_f32_16x16x32_bf16 v[58:61], v[148:151], v[160:163], v[58:61]
	v_mfma_f32_16x16x32_bf16 v[54:57], v[140:143], v[168:171], v[54:57]
	v_mfma_f32_16x16x32_bf16 v[50:53], v[148:151], v[168:171], v[50:53]
	v_mfma_f32_16x16x32_bf16 v[38:41], v[140:143], v[176:179], v[38:41]
	v_mfma_f32_16x16x32_bf16 v[34:37], v[148:151], v[176:179], v[34:37]
	v_mfma_f32_16x16x32_bf16 v[22:25], v[140:143], v[184:187], v[22:25]
	v_mfma_f32_16x16x32_bf16 v[18:21], v[148:151], v[184:187], v[18:21]
	v_mfma_f32_16x16x32_bf16 v[62:65], v[144:147], v[164:167], v[62:65]
	v_mfma_f32_16x16x32_bf16 v[58:61], v[152:155], v[164:167], v[58:61]
	v_mfma_f32_16x16x32_bf16 v[54:57], v[144:147], v[172:175], v[54:57]
	v_mfma_f32_16x16x32_bf16 v[50:53], v[152:155], v[172:175], v[50:53]
	v_mfma_f32_16x16x32_bf16 v[38:41], v[144:147], v[180:183], v[38:41]
	v_mfma_f32_16x16x32_bf16 v[34:37], v[152:155], v[180:183], v[34:37]
	v_mfma_f32_16x16x32_bf16 v[22:25], v[144:147], v[188:191], v[22:25]
	v_mfma_f32_16x16x32_bf16 v[18:21], v[152:155], v[188:191], v[18:21]
	v_mfma_f32_16x16x32_bf16 v[46:49], v[192:195], v[160:163], v[46:49]
	v_mfma_f32_16x16x32_bf16 v[42:45], v[200:203], v[160:163], v[42:45]
	v_mfma_f32_16x16x32_bf16 v[30:33], v[192:195], v[168:171], v[30:33]
	v_mfma_f32_16x16x32_bf16 v[26:29], v[200:203], v[168:171], v[26:29]
	v_mfma_f32_16x16x32_bf16 v[14:17], v[192:195], v[176:179], v[14:17]
	v_mfma_f32_16x16x32_bf16 v[10:13], v[200:203], v[176:179], v[10:13]
	v_mfma_f32_16x16x32_bf16 v[6:9], v[192:195], v[184:187], v[6:9]
	v_mfma_f32_16x16x32_bf16 v[2:5], v[200:203], v[184:187], v[2:5]
	v_mfma_f32_16x16x32_bf16 v[46:49], v[196:199], v[164:167], v[46:49]
	v_mfma_f32_16x16x32_bf16 v[42:45], v[204:207], v[164:167], v[42:45]
	v_mfma_f32_16x16x32_bf16 v[30:33], v[196:199], v[172:175], v[30:33]
	v_mfma_f32_16x16x32_bf16 v[26:29], v[204:207], v[172:175], v[26:29]
	v_mfma_f32_16x16x32_bf16 v[14:17], v[196:199], v[180:183], v[14:17]
	v_mfma_f32_16x16x32_bf16 v[10:13], v[204:207], v[180:183], v[10:13]
	v_mfma_f32_16x16x32_bf16 v[6:9], v[196:199], v[188:191], v[6:9]
	v_mfma_f32_16x16x32_bf16 v[2:5], v[204:207], v[188:191], v[2:5]
	s_setprio 0
	s_barrier
; #define PG8_STAGE(bufoff, gbase, voff) do { _Pragma("unroll") for (int _i = 0; _i < 2; ++_i) \
;         __builtin_amdgcn_global_load_lds((const unsigned*)((const char*)(gbase) + (voff)[_i]), (LAS unsigned*)(lds + (bufoff) + ldsw + _i * 8192), 16, 0, 0); } while (0)
; #define PG8_LDA(dst, b, h) do { _Pragma("unroll") for (int m = 0; m < 4; ++m) _Pragma("unroll") for (int k = 0; k < 2; ++k) dst[m][k] = *(const LAS bf16x8*)(lds + PG8_SA(b, h) + aoff + m * 2048 + k * 1024); } while (0)
; #define PG8_LDB(dst, b, h) do { _Pragma("unroll") for (int n = 0; n < 2; ++n) _Pragma("unroll") for (int k = 0; k < 2; ++k) dst[n][k] = *(const LAS bf16x8*)(lds + PG8_SB(b, h) + boff + n * 2048 + k * 1024); } while (0)
; #define PG8_MMA(ai, bj, At, Bt) do { __builtin_amdgcn_s_setprio(1); _Pragma("unroll") for (int m = 0; m < 4; ++m) _Pragma("unroll") for (int n = 0; n < 2; ++n) _Pragma("unroll") for (int k = 0; k < 2; ++k) \
;         acc[ai][bj][m][n] = __builtin_amdgcn_mfma_f32_16x16x32_bf16(Bt[n][k], At[m][k], acc[ai][bj][m][n], 0, 0, 0); __builtin_amdgcn_s_setprio(0); } while (0)
; #define PG8_WAIT_V(n) asm volatile("s_waitcnt vmcnt(" #n ")" ::: "memory")
; #define PG8_WAIT_L(n) asm volatile("s_waitcnt lgkmcnt(" #n ")" ::: "memory")
; #define PG8_BAR __builtin_amdgcn_s_barrier()
; #define PG8_SCHED __builtin_amdgcn_sched_barrier(0)
; template <class Epi, class Sched>
; __device__ __forceinline__ void gemm_phase(LAS unsigned char* lds, const Gemm g, const Sched& S, const Epi& E) {
;     ...
;             PG8_LDB(B0, 1, 0); PG8_SCHED; PG8_LDA(At, 1, 0); PG8_STAGE(PG8_SA(0, 1), a2 + hstep, voffA);
;             PG8_WAIT_L(8); PG8_BAR; PG8_WAIT_L(0); PG8_MMA(0, 0, At, B0); PG8_BAR; PG8_SCHED;
;             PG8_LDB(B1, 1, 1); PG8_STAGE(PG8_SB(1, 0), b3, voffB);
;             PG8_BAR; PG8_WAIT_L(0); PG8_MMA(0, 1, At, B1); PG8_BAR;
;             PG8_LDA(At, 1, 1); PG8_STAGE(PG8_SA(1, 0), a3, voffA);
;             PG8_BAR; PG8_WAIT_L(0); PG8_MMA(1, 0, At, B0); PG8_BAR; PG8_SCHED;
;             PG8_STAGE(PG8_SB(1, 1), b3 + hstep, voffB);
;             PG8_WAIT_V(6); PG8_BAR; PG8_MMA(1, 1, At, B1); PG8_BAR;
	s_add_u32 s38, s54, 0x200000
	s_addc_u32 s39, s55, 0
	s_add_i32 s50, s50, s63
	v_lshl_add_u64 v[140:141], s[38:39], 0, v[0:1]
	s_mov_b32 m0, s50
	s_nop 0
	global_load_lds_dwordx4 v[140:141], off
	v_lshl_add_u64 v[140:141], s[38:39], 0, v[130:131]
	s_add_i32 m0, s50, 0x2000
	s_nop 0
	global_load_lds_dwordx4 v[140:141], off
	s_add_u32 s38, s56, 0x200000
	s_addc_u32 s39, s57, 0
	s_mov_b32 m0, s64
	v_lshl_add_u64 v[192:193], s[38:39], 0, v[0:1]
	global_load_lds_dwordx4 v[192:193], off
	v_lshl_add_u64 v[192:193], s[38:39], 0, v[130:131]
	s_mov_b32 m0, s65
	s_nop 0
	global_load_lds_dwordx4 v[192:193], off
	s_add_i32 s50, 0, 0x18000
	v_add_u32_e32 v152, s50, v137
	ds_read_b128 v[140:143], v152
	ds_read_b128 v[144:147], v152 offset:1024
	ds_read_b128 v[148:151], v152 offset:2048
	ds_read_b128 v[152:155], v152 offset:3072
	ds_read_b128 v[160:163], v139 offset:32768
	ds_read_b128 v[164:167], v139 offset:33792
	ds_read_b128 v[168:171], v139 offset:34816
	ds_read_b128 v[172:175], v139 offset:35840
	ds_read_b128 v[176:179], v139 offset:36864
	ds_read_b128 v[180:183], v139 offset:37888
	ds_read_b128 v[184:187], v139 offset:38912
	ds_read_b128 v[188:191], v139 offset:39936
	s_add_i32 s51, 0, 0x1c000
	v_add_u32_e32 v204, s51, v137
	ds_read_b128 v[192:195], v204
	ds_read_b128 v[196:199], v204 offset:1024
	ds_read_b128 v[200:203], v204 offset:2048
	ds_read_b128 v[204:207], v204 offset:3072
	s_waitcnt lgkmcnt(4)
	s_barrier
	s_waitcnt lgkmcnt(0)
	s_setprio 1
	v_mfma_f32_16x16x32_bf16 v[126:129], v[140:143], v[160:163], v[126:129]
	v_mfma_f32_16x16x32_bf16 v[122:125], v[148:151], v[160:163], v[122:125]
	v_mfma_f32_16x16x32_bf16 v[118:121], v[140:143], v[168:171], v[118:121]
	v_mfma_f32_16x16x32_bf16 v[114:117], v[148:151], v[168:171], v[114:117]
	v_mfma_f32_16x16x32_bf16 v[106:109], v[140:143], v[176:179], v[106:109]
	v_mfma_f32_16x16x32_bf16 v[98:101], v[148:151], v[176:179], v[98:101]
	v_mfma_f32_16x16x32_bf16 v[90:93], v[140:143], v[184:187], v[90:93]
	v_mfma_f32_16x16x32_bf16 v[82:85], v[148:151], v[184:187], v[82:85]
	v_mfma_f32_16x16x32_bf16 v[126:129], v[144:147], v[164:167], v[126:129]
	v_mfma_f32_16x16x32_bf16 v[122:125], v[152:155], v[164:167], v[122:125]
	v_mfma_f32_16x16x32_bf16 v[118:121], v[144:147], v[172:175], v[118:121]
	v_mfma_f32_16x16x32_bf16 v[114:117], v[152:155], v[172:175], v[114:117]
	v_mfma_f32_16x16x32_bf16 v[106:109], v[144:147], v[180:183], v[106:109]
	v_mfma_f32_16x16x32_bf16 v[98:101], v[152:155], v[180:183], v[98:101]
	v_mfma_f32_16x16x32_bf16 v[90:93], v[144:147], v[188:191], v[90:93]
	v_mfma_f32_16x16x32_bf16 v[82:85], v[152:155], v[188:191], v[82:85]
	v_mfma_f32_16x16x32_bf16 v[110:113], v[192:195], v[160:163], v[110:113]
	v_mfma_f32_16x16x32_bf16 v[102:105], v[200:203], v[160:163], v[102:105]
	v_mfma_f32_16x16x32_bf16 v[94:97], v[192:195], v[168:171], v[94:97]
	v_mfma_f32_16x16x32_bf16 v[86:89], v[200:203], v[168:171], v[86:89]
	v_mfma_f32_16x16x32_bf16 v[78:81], v[192:195], v[176:179], v[78:81]
	v_mfma_f32_16x16x32_bf16 v[74:77], v[200:203], v[176:179], v[74:77]
	v_mfma_f32_16x16x32_bf16 v[70:73], v[192:195], v[184:187], v[70:73]
	v_mfma_f32_16x16x32_bf16 v[66:69], v[200:203], v[184:187], v[66:69]
	v_mfma_f32_16x16x32_bf16 v[110:113], v[196:199], v[164:167], v[110:113]
	v_mfma_f32_16x16x32_bf16 v[102:105], v[204:207], v[164:167], v[102:105]
	v_mfma_f32_16x16x32_bf16 v[94:97], v[196:199], v[172:175], v[94:97]
	v_mfma_f32_16x16x32_bf16 v[86:89], v[204:207], v[172:175], v[86:89]
	v_mfma_f32_16x16x32_bf16 v[78:81], v[196:199], v[180:183], v[78:81]
	v_mfma_f32_16x16x32_bf16 v[74:77], v[204:207], v[180:183], v[74:77]
	v_mfma_f32_16x16x32_bf16 v[70:73], v[196:199], v[188:191], v[70:73]
	v_mfma_f32_16x16x32_bf16 v[66:69], v[204:207], v[188:191], v[66:69]
	s_setprio 0
	s_barrier
	s_add_i32 s38, s50, s63
	v_lshl_add_u64 v[156:157], v[156:157], 0, s[36:37]
	s_mov_b32 m0, s38
	s_nop 0
	global_load_lds_dwordx4 v[156:157], off
	v_lshl_add_u64 v[156:157], v[210:211], 0, s[36:37]
	s_add_i32 m0, s38, 0x2000
	s_nop 0
	global_load_lds_dwordx4 v[156:157], off
	s_mov_b32 m0, s66
	v_lshl_add_u64 v[156:157], v[212:213], 0, s[36:37]
	global_load_lds_dwordx4 v[156:157], off
	v_lshl_add_u64 v[156:157], v[214:215], 0, s[36:37]
	s_mov_b32 m0, s67
	s_nop 0
	global_load_lds_dwordx4 v[156:157], off
	ds_read_b128 v[160:163], v139 offset:49152
	ds_read_b128 v[164:167], v139 offset:50176
	ds_read_b128 v[168:171], v139 offset:51200
	ds_read_b128 v[172:175], v139 offset:52224
	ds_read_b128 v[176:179], v139 offset:53248
	ds_read_b128 v[180:183], v139 offset:54272
	ds_read_b128 v[184:187], v139 offset:55296
	ds_read_b128 v[188:191], v139 offset:56320
	s_waitcnt vmcnt(4)
	s_waitcnt lgkmcnt(0)
	s_barrier
; #define PG8_MMA(ai, bj, At, Bt) do { __builtin_amdgcn_s_setprio(1); _Pragma("unroll") for (int m = 0; m < 4; ++m) _Pragma("unroll") for (int n = 0; n < 2; ++n) _Pragma("unroll") for (int k = 0; k < 2; ++k) \
;         acc[ai][bj][m][n] = __builtin_amdgcn_mfma_f32_16x16x32_bf16(Bt[n][k], At[m][k], acc[ai][bj][m][n], 0, 0, 0); __builtin_amdgcn_s_setprio(0); } while (0)
; #define PG8_WAIT_V(n) asm volatile("s_waitcnt vmcnt(" #n ")" ::: "memory")
; #define PG8_BAR __builtin_amdgcn_s_barrier()
;     __device__ __forceinline__ void operator()(const f32x4 (&acc)[2][2][4][2], const Unit& u, int wr, int wc, int fr, int fq) const {
;         const int row0 = u.pm * BM + wr * 64 + fr, col0 = u.pn * BM + wc * 32 + 4 * fq;
;         float* base = part + (size_t)u.ks * Mp * ldc;
; #pragma unroll
;         for (int ai = 0; ai < 2; ++ai)
; #pragma unroll
;             for (int m = 0; m < 4; ++m) { float* rowp = base + (size_t)(row0 + ai * HALF + m * 16) * ldc + col0;
; #pragma unroll
;                 for (int bj = 0; bj < 2; ++bj)
; #pragma unroll
;                     for (int n = 0; n < 2; ++n) *(f32x4*)(rowp + bj * HALF + n * 16) = acc[ai][bj][m][n]; }
; template <class Epi, class Sched>
; __device__ __forceinline__ void gemm_phase(LAS unsigned char* lds, const Gemm g, const Sched& S, const Epi& E) {
;     ...
;             PG8_WAIT_V(6); PG8_BAR; PG8_MMA(1, 1, At, B1); PG8_BAR;
;         }
;         E(acc, cur, wr, wc, fr, fq);
	s_setprio 1
	v_mfma_f32_16x16x32_bf16 v[62:65], v[140:143], v[160:163], v[62:65]
	v_mfma_f32_16x16x32_bf16 v[58:61], v[148:151], v[160:163], v[58:61]
	v_mfma_f32_16x16x32_bf16 v[54:57], v[140:143], v[168:171], v[54:57]
	v_mfma_f32_16x16x32_bf16 v[50:53], v[148:151], v[168:171], v[50:53]
	v_mfma_f32_16x16x32_bf16 v[38:41], v[140:143], v[176:179], v[38:41]
	v_mfma_f32_16x16x32_bf16 v[34:37], v[148:151], v[176:179], v[34:37]
	v_mfma_f32_16x16x32_bf16 v[22:25], v[140:143], v[184:187], v[22:25]
	v_mfma_f32_16x16x32_bf16 v[18:21], v[148:151], v[184:187], v[18:21]
	v_mfma_f32_16x16x32_bf16 v[62:65], v[144:147], v[164:167], v[62:65]
	v_mfma_f32_16x16x32_bf16 v[58:61], v[152:155], v[164:167], v[58:61]
	v_mfma_f32_16x16x32_bf16 v[54:57], v[144:147], v[172:175], v[54:57]
	v_mfma_f32_16x16x32_bf16 v[50:53], v[152:155], v[172:175], v[50:53]
	v_mfma_f32_16x16x32_bf16 v[38:41], v[144:147], v[180:183], v[38:41]
	v_mfma_f32_16x16x32_bf16 v[34:37], v[152:155], v[180:183], v[34:37]
	v_mfma_f32_16x16x32_bf16 v[22:25], v[144:147], v[188:191], v[22:25]
	v_mfma_f32_16x16x32_bf16 v[18:21], v[152:155], v[188:191], v[18:21]
	s_add_u32 s38, s54, 0x200080
	s_addc_u32 s39, s55, 0
	s_add_i32 s50, s51, s63
	v_lshl_add_u64 v[140:141], s[38:39], 0, v[0:1]
	s_mov_b32 m0, s50
	s_nop 0
	global_load_lds_dwordx4 v[140:141], off
	v_lshl_add_u64 v[140:141], s[38:39], 0, v[130:131]
	s_add_i32 m0, s50, 0x2000
	s_nop 0
	global_load_lds_dwordx4 v[140:141], off
	v_mfma_f32_16x16x32_bf16 v[46:49], v[192:195], v[160:163], v[46:49]
	v_mfma_f32_16x16x32_bf16 v[42:45], v[200:203], v[160:163], v[42:45]
	v_mfma_f32_16x16x32_bf16 v[30:33], v[192:195], v[168:171], v[30:33]
	v_mfma_f32_16x16x32_bf16 v[26:29], v[200:203], v[168:171], v[26:29]
	v_mfma_f32_16x16x32_bf16 v[14:17], v[192:195], v[176:179], v[14:17]
	v_mfma_f32_16x16x32_bf16 v[10:13], v[200:203], v[176:179], v[10:13]
	v_mfma_f32_16x16x32_bf16 v[6:9], v[192:195], v[184:187], v[6:9]
	v_mfma_f32_16x16x32_bf16 v[2:5], v[200:203], v[184:187], v[2:5]
	v_mfma_f32_16x16x32_bf16 v[46:49], v[196:199], v[164:167], v[46:49]
	v_mfma_f32_16x16x32_bf16 v[42:45], v[204:207], v[164:167], v[42:45]
	v_mfma_f32_16x16x32_bf16 v[30:33], v[196:199], v[172:175], v[30:33]
	v_mfma_f32_16x16x32_bf16 v[26:29], v[204:207], v[172:175], v[26:29]
	v_mfma_f32_16x16x32_bf16 v[14:17], v[196:199], v[180:183], v[14:17]
	v_mfma_f32_16x16x32_bf16 v[10:13], v[204:207], v[180:183], v[10:13]
	v_mfma_f32_16x16x32_bf16 v[6:9], v[196:199], v[188:191], v[6:9]
	v_mfma_f32_16x16x32_bf16 v[2:5], v[204:207], v[188:191], v[2:5]
	s_setprio 0
	s_add_i32 s71, s71, 2
	s_add_u32 s69, s69, 0x100
	s_addc_u32 s70, s70, 0
	s_cmp_gt_u32 s71, 29
	s_mov_b64 s[50:51], s[52:53]
	s_barrier
	s_cbranch_scc0 .LBB0_58
	s_ashr_i32 s11, s10, 31
	s_lshl_b64 s[10:11], s[10:11], 24
	v_lshl_or_b32 v140, s26, 8, v138
	s_add_u32 s10, s8, s10
	v_lshl_add_u32 v142, s24, 8, v136
	s_addc_u32 s11, s9, s11
	v_ashrrev_i32_e32 v141, 31, v140
	v_ashrrev_i32_e32 v143, 31, v142
	v_lshl_add_u64 v[140:141], v[140:141], 2, s[10:11]
	v_lshlrev_b64 v[144:145], 13, v[142:143]
	v_lshl_add_u64 v[144:145], v[140:141], 0, v[144:145]
	global_store_dwordx4 v[144:145], v[126:129], off
	global_store_dwordx4 v[144:145], v[122:125], off offset:64
	global_store_dwordx4 v[144:145], v[110:113], off offset:512
	global_store_dwordx4 v[144:145], v[102:105], off offset:576
	s_mov_b64 s[10:11], 0x100000
	s_mov_b32 s26, s40
	v_or_b32_e32 v102, 16, v142
	v_ashrrev_i32_e32 v103, 31, v102
	v_lshlrev_b64 v[102:103], 13, v[102:103]
	v_lshl_add_u64 v[102:103], v[140:141], 0, v[102:103]
	global_store_dwordx4 v[102:103], v[118:121], off
	global_store_dwordx4 v[102:103], v[114:117], off offset:64
	global_store_dwordx4 v[102:103], v[94:97], off offset:512
	global_store_dwordx4 v[102:103], v[86:89], off offset:576
	s_mov_b32 s24, s42
	s_mov_b64 s[52:53], s[48:49]
	v_or_b32_e32 v86, 32, v142
	v_ashrrev_i32_e32 v87, 31, v86
	v_lshlrev_b64 v[86:87], 13, v[86:87]
	v_lshl_add_u64 v[86:87], v[140:141], 0, v[86:87]
	global_store_dwordx4 v[86:87], v[106:109], off
	global_store_dwordx4 v[86:87], v[98:101], off offset:64
	global_store_dwordx4 v[86:87], v[78:81], off offset:512
	global_store_dwordx4 v[86:87], v[74:77], off offset:576
	s_mov_b64 s[50:51], s[46:47]
	s_nop 0
	v_or_b32_e32 v74, 48, v142
	v_ashrrev_i32_e32 v75, 31, v74
	v_lshlrev_b64 v[74:75], 13, v[74:75]
	v_lshl_add_u64 v[74:75], v[140:141], 0, v[74:75]
	global_store_dwordx4 v[74:75], v[90:93], off
	global_store_dwordx4 v[74:75], v[82:85], off offset:64
	global_store_dwordx4 v[74:75], v[70:73], off offset:512
	global_store_dwordx4 v[74:75], v[66:69], off offset:576
	s_nop 1
	v_add_co_u32_e32 v68, vcc, s93, v144
	v_lshl_add_u64 v[66:67], v[144:145], 0, s[10:11]
	s_nop 0
	v_addc_co_u32_e32 v69, vcc, 0, v145, vcc
	s_mov_b64 s[10:11], 0x120000
	global_store_dwordx4 v[68:69], v[62:65], off
	global_store_dwordx4 v[66:67], v[58:61], off offset:64
	global_store_dwordx4 v[66:67], v[46:49], off offset:512
	global_store_dwordx4 v[66:67], v[42:45], off offset:576
	s_nop 1
	v_lshl_add_u64 v[42:43], v[144:145], 0, s[10:11]
	s_mov_b32 s10, 0x120000
	v_add_co_u32_e32 v44, vcc, s10, v144
	s_mov_b64 s[10:11], 0x140000
	s_nop 0
	v_addc_co_u32_e32 v45, vcc, 0, v145, vcc
	global_store_dwordx4 v[44:45], v[54:57], off
	global_store_dwordx4 v[42:43], v[50:53], off offset:64
	global_store_dwordx4 v[42:43], v[30:33], off offset:512
	global_store_dwordx4 v[42:43], v[26:29], off offset:576
	s_nop 1
	v_lshl_add_u64 v[26:27], v[144:145], 0, s[10:11]
	s_mov_b32 s10, 0x140000
	v_add_co_u32_e32 v28, vcc, s10, v144
	s_mov_b64 s[10:11], 0x160000
	s_nop 0
	v_addc_co_u32_e32 v29, vcc, 0, v145, vcc
	global_store_dwordx4 v[28:29], v[38:41], off
	global_store_dwordx4 v[26:27], v[34:37], off offset:64
	global_store_dwordx4 v[26:27], v[14:17], off offset:512
	global_store_dwordx4 v[26:27], v[10:13], off offset:576
	s_nop 1
	v_add_co_u32_e32 v12, vcc, 0x160000, v144
	v_lshl_add_u64 v[10:11], v[144:145], 0, s[10:11]
	s_nop 0
	v_addc_co_u32_e32 v13, vcc, 0, v145, vcc
	s_and_b64 vcc, exec, s[44:45]
	s_mov_b32 s10, s28
	global_store_dwordx4 v[12:13], v[22:25], off
	global_store_dwordx4 v[10:11], v[18:21], off offset:64
	global_store_dwordx4 v[10:11], v[6:9], off offset:512
	global_store_dwordx4 v[10:11], v[2:5], off offset:576
	s_cbranch_vccz .LBB0_55
	s_waitcnt vmcnt(0)
	s_cmpk_gt_u32 s60, 0xff
	s_cbranch_scc1 .LBB0_62
	s_barrier

; #define PG8_STAGE(bufoff, gbase, voff) do { _Pragma("unroll") for (int _i = 0; _i < 2; ++_i) \
;         __builtin_amdgcn_global_load_lds((const unsigned*)((const char*)(gbase) + (voff)[_i]), (LAS unsigned*)(lds + (bufoff) + ldsw + _i * 8192), 16, 0, 0); } while (0)
; #define PG8_LDA(dst, b, h) do { _Pragma("unroll") for (int m = 0; m < 4; ++m) _Pragma("unroll") for (int k = 0; k < 2; ++k) dst[m][k] = *(const LAS bf16x8*)(lds + PG8_SA(b, h) + aoff + m * 2048 + k * 1024); } while (0)
; #define PG8_LDB(dst, b, h) do { _Pragma("unroll") for (int n = 0; n < 2; ++n) _Pragma("unroll") for (int k = 0; k < 2; ++k) dst[n][k] = *(const LAS bf16x8*)(lds + PG8_SB(b, h) + boff + n * 2048 + k * 1024); } while (0)
; #define PG8_MMA(ai, bj, At, Bt) do { __builtin_amdgcn_s_setprio(1); _Pragma("unroll") for (int m = 0; m < 4; ++m) _Pragma("unroll") for (int n = 0; n < 2; ++n) _Pragma("unroll") for (int k = 0; k < 2; ++k) \
;         acc[ai][bj][m][n] = __builtin_amdgcn_mfma_f32_16x16x32_bf16(Bt[n][k], At[m][k], acc[ai][bj][m][n], 0, 0, 0); __builtin_amdgcn_s_setprio(0); } while (0)
; #define PG8_WAIT_V(n) asm volatile("s_waitcnt vmcnt(" #n ")" ::: "memory")
; #define PG8_WAIT_L(n) asm volatile("s_waitcnt lgkmcnt(" #n ")" ::: "memory")
; template <class Epi, class Sched>
; __device__ __forceinline__ void gemm_phase(LAS unsigned char* lds, const Gemm g, const Sched& S, const Epi& E) {
;     ...
;         for (int t = 0; t < nt; t += 2) {
;             const bool last = (t == nt - 2);
;             const char* a1 = cA + (size_t)(t + 1) * kstep;
;             const char* a2 = last ? nA : cA + (size_t)(t + 2) * kstep; const char* b2 = last ? nB : cB + (size_t)(t + 2) * kstep;
;             const char* a3 = a2 + kstep; const char* b3 = b2 + kstep;
;             PG8_LDB(B0, 0, 0); PG8_SCHED; PG8_LDA(At, 0, 0); PG8_STAGE(PG8_SA(1, 1), a1 + hstep, voffA);
;             PG8_WAIT_L(8); PG8_BAR; PG8_WAIT_L(0); PG8_MMA(0, 0, At, B0); PG8_BAR; PG8_SCHED;
;             PG8_LDB(B1, 0, 1); PG8_STAGE(PG8_SB(0, 0), b2, voffB);
;             PG8_BAR; PG8_WAIT_L(0); PG8_MMA(0, 1, At, B1); PG8_BAR;
;             PG8_LDA(At, 0, 1); PG8_STAGE(PG8_SA(0, 0), a2, voffA);
;             PG8_BAR; PG8_WAIT_L(0); PG8_MMA(1, 0, At, B0); PG8_BAR; PG8_SCHED;
;             PG8_STAGE(PG8_SB(0, 1), b2 + hstep, voffB);
;             PG8_WAIT_V(6); PG8_BAR; PG8_MMA(1, 1, At, B1); PG8_BAR;
.LBB0_73:
	s_add_u32 s38, s46, 0xfff80080
	s_addc_u32 s39, s47, -1
	s_cmp_eq_u32 s73, 28
	s_cselect_b32 s51, s29, s39
	s_cselect_b32 s50, s69, s38
	s_cselect_b32 s49, s27, s72
	s_cselect_b32 s48, s70, s71
	v_lshl_add_u64 v[140:141], s[46:47], 0, v[138:139]
	s_add_i32 m0, s9, 0xc000
	s_nop 0
	global_load_lds_dwordx4 v[140:141], off
	v_lshl_add_u64 v[140:141], s[46:47], 0, v[136:137]
	s_add_i32 m0, s9, 0xe000
	s_nop 0
	global_load_lds_dwordx4 v[140:141], off
	s_add_i32 s74, 0, 0x10000
	v_add_u32_e32 v140, s74, v143
	ds_read_b128 v[146:149], v140
	ds_read_b128 v[150:153], v140 offset:1024
	ds_read_b128 v[154:157], v140 offset:2048
	ds_read_b128 v[160:163], v140 offset:3072
	ds_read_b128 v[164:167], v145
	ds_read_b128 v[168:171], v145 offset:1024
	ds_read_b128 v[172:175], v145 offset:2048
	ds_read_b128 v[176:179], v145 offset:3072
	ds_read_b128 v[180:183], v145 offset:4096
	ds_read_b128 v[184:187], v145 offset:5120
	ds_read_b128 v[188:191], v145 offset:6144
	ds_read_b128 v[192:195], v145 offset:7168
	s_add_i32 s75, 0, 0x14000
	v_add_u32_e32 v140, s75, v143
	ds_read_b128 v[196:199], v140
	ds_read_b128 v[200:203], v140 offset:1024
	ds_read_b128 v[204:207], v140 offset:2048
	ds_read_b128 v[210:213], v140 offset:3072
	s_waitcnt lgkmcnt(4)
	s_barrier
	s_waitcnt lgkmcnt(0)
	s_setprio 1
	v_mfma_f32_16x16x32_bf16 v[126:129], v[146:149], v[164:167], v[126:129]
	v_mfma_f32_16x16x32_bf16 v[122:125], v[154:157], v[164:167], v[122:125]
	v_mfma_f32_16x16x32_bf16 v[110:113], v[146:149], v[172:175], v[110:113]
	v_mfma_f32_16x16x32_bf16 v[106:109], v[154:157], v[172:175], v[106:109]
	v_mfma_f32_16x16x32_bf16 v[94:97], v[146:149], v[180:183], v[94:97]
	v_mfma_f32_16x16x32_bf16 v[90:93], v[154:157], v[180:183], v[90:93]
	v_mfma_f32_16x16x32_bf16 v[78:81], v[146:149], v[188:191], v[78:81]
	v_mfma_f32_16x16x32_bf16 v[74:77], v[154:157], v[188:191], v[74:77]
	v_mfma_f32_16x16x32_bf16 v[126:129], v[150:153], v[168:171], v[126:129]
	v_mfma_f32_16x16x32_bf16 v[122:125], v[160:163], v[168:171], v[122:125]
	v_mfma_f32_16x16x32_bf16 v[110:113], v[150:153], v[176:179], v[110:113]
	v_mfma_f32_16x16x32_bf16 v[106:109], v[160:163], v[176:179], v[106:109]
	v_mfma_f32_16x16x32_bf16 v[94:97], v[150:153], v[184:187], v[94:97]
	v_mfma_f32_16x16x32_bf16 v[90:93], v[160:163], v[184:187], v[90:93]
	v_mfma_f32_16x16x32_bf16 v[78:81], v[150:153], v[192:195], v[78:81]
	v_mfma_f32_16x16x32_bf16 v[74:77], v[160:163], v[192:195], v[74:77]
	v_mfma_f32_16x16x32_bf16 v[118:121], v[196:199], v[164:167], v[118:121]
	v_mfma_f32_16x16x32_bf16 v[114:117], v[204:207], v[164:167], v[114:117]
	v_mfma_f32_16x16x32_bf16 v[102:105], v[196:199], v[172:175], v[102:105]
	v_mfma_f32_16x16x32_bf16 v[98:101], v[204:207], v[172:175], v[98:101]
	v_mfma_f32_16x16x32_bf16 v[86:89], v[196:199], v[180:183], v[86:89]
	v_mfma_f32_16x16x32_bf16 v[82:85], v[204:207], v[180:183], v[82:85]
	v_mfma_f32_16x16x32_bf16 v[70:73], v[196:199], v[188:191], v[70:73]
	v_mfma_f32_16x16x32_bf16 v[66:69], v[204:207], v[188:191], v[66:69]
	v_mfma_f32_16x16x32_bf16 v[118:121], v[200:203], v[168:171], v[118:121]
	v_mfma_f32_16x16x32_bf16 v[114:117], v[210:213], v[168:171], v[114:117]
	v_mfma_f32_16x16x32_bf16 v[102:105], v[200:203], v[176:179], v[102:105]
	v_mfma_f32_16x16x32_bf16 v[98:101], v[210:213], v[176:179], v[98:101]
	v_mfma_f32_16x16x32_bf16 v[86:89], v[200:203], v[184:187], v[86:89]
	v_mfma_f32_16x16x32_bf16 v[82:85], v[210:213], v[184:187], v[82:85]
	v_mfma_f32_16x16x32_bf16 v[70:73], v[200:203], v[192:195], v[70:73]
	v_mfma_f32_16x16x32_bf16 v[66:69], v[210:213], v[192:195], v[66:69]
	s_setprio 0
	s_barrier
	s_add_i32 s38, s74, s56
	v_lshl_add_u64 v[140:141], s[48:49], 0, v[0:1]
	s_mov_b32 m0, s38
	v_lshl_add_u64 v[214:215], s[48:49], 0, v[130:131]
	global_load_lds_dwordx4 v[140:141], off
	s_add_i32 m0, s38, 0x2000
	s_nop 0
	global_load_lds_dwordx4 v[214:215], off
	s_mov_b32 m0, s9
	v_lshl_add_u64 v[216:217], s[50:51], 0, v[134:135]
	global_load_lds_dwordx4 v[216:217], off
	v_lshl_add_u64 v[224:225], s[50:51], 0, v[132:133]
	s_mov_b32 m0, s60
	s_nop 0
	global_load_lds_dwordx4 v[224:225], off
	ds_read_b128 v[164:167], v145 offset:16384
	ds_read_b128 v[168:171], v145 offset:17408
	ds_read_b128 v[172:175], v145 offset:18432
	ds_read_b128 v[176:179], v145 offset:19456
	ds_read_b128 v[180:183], v145 offset:20480
	ds_read_b128 v[184:187], v145 offset:21504
	ds_read_b128 v[188:191], v145 offset:22528
	ds_read_b128 v[192:195], v145 offset:23552
	s_waitcnt vmcnt(4)
	s_waitcnt lgkmcnt(0)
	s_barrier
	s_setprio 1
	v_mfma_f32_16x16x32_bf16 v[62:65], v[146:149], v[164:167], v[62:65]
	v_mfma_f32_16x16x32_bf16 v[58:61], v[154:157], v[164:167], v[58:61]
	v_mfma_f32_16x16x32_bf16 v[46:49], v[146:149], v[172:175], v[46:49]
	v_mfma_f32_16x16x32_bf16 v[42:45], v[154:157], v[172:175], v[42:45]
	v_mfma_f32_16x16x32_bf16 v[30:33], v[146:149], v[180:183], v[30:33]
	v_mfma_f32_16x16x32_bf16 v[26:29], v[154:157], v[180:183], v[26:29]
	v_mfma_f32_16x16x32_bf16 v[14:17], v[146:149], v[188:191], v[14:17]
	v_mfma_f32_16x16x32_bf16 v[10:13], v[154:157], v[188:191], v[10:13]
	v_mfma_f32_16x16x32_bf16 v[62:65], v[150:153], v[168:171], v[62:65]
	v_mfma_f32_16x16x32_bf16 v[58:61], v[160:163], v[168:171], v[58:61]
	v_mfma_f32_16x16x32_bf16 v[46:49], v[150:153], v[176:179], v[46:49]
	v_mfma_f32_16x16x32_bf16 v[42:45], v[160:163], v[176:179], v[42:45]
	v_mfma_f32_16x16x32_bf16 v[30:33], v[150:153], v[184:187], v[30:33]
	v_mfma_f32_16x16x32_bf16 v[26:29], v[160:163], v[184:187], v[26:29]
	v_mfma_f32_16x16x32_bf16 v[14:17], v[150:153], v[192:195], v[14:17]
	v_mfma_f32_16x16x32_bf16 v[10:13], v[160:163], v[192:195], v[10:13]
	v_mfma_f32_16x16x32_bf16 v[54:57], v[196:199], v[164:167], v[54:57]
	v_mfma_f32_16x16x32_bf16 v[50:53], v[204:207], v[164:167], v[50:53]
	v_mfma_f32_16x16x32_bf16 v[38:41], v[196:199], v[172:175], v[38:41]
	v_mfma_f32_16x16x32_bf16 v[34:37], v[204:207], v[172:175], v[34:37]
	v_mfma_f32_16x16x32_bf16 v[22:25], v[196:199], v[180:183], v[22:25]
	v_mfma_f32_16x16x32_bf16 v[18:21], v[204:207], v[180:183], v[18:21]
	v_mfma_f32_16x16x32_bf16 v[6:9], v[196:199], v[188:191], v[6:9]
	v_mfma_f32_16x16x32_bf16 v[2:5], v[204:207], v[188:191], v[2:5]
	v_mfma_f32_16x16x32_bf16 v[54:57], v[200:203], v[168:171], v[54:57]
	v_mfma_f32_16x16x32_bf16 v[50:53], v[210:213], v[168:171], v[50:53]
	v_mfma_f32_16x16x32_bf16 v[38:41], v[200:203], v[176:179], v[38:41]
	v_mfma_f32_16x16x32_bf16 v[34:37], v[210:213], v[176:179], v[34:37]
	v_mfma_f32_16x16x32_bf16 v[22:25], v[200:203], v[184:187], v[22:25]
	v_mfma_f32_16x16x32_bf16 v[18:21], v[210:213], v[184:187], v[18:21]
	v_mfma_f32_16x16x32_bf16 v[6:9], v[200:203], v[192:195], v[6:9]
	v_mfma_f32_16x16x32_bf16 v[2:5], v[210:213], v[192:195], v[2:5]
	s_setprio 0
	s_barrier
; #define PG8_STAGE(bufoff, gbase, voff) do { _Pragma("unroll") for (int _i = 0; _i < 2; ++_i) \
;         __builtin_amdgcn_global_load_lds((const unsigned*)((const char*)(gbase) + (voff)[_i]), (LAS unsigned*)(lds + (bufoff) + ldsw + _i * 8192), 16, 0, 0); } while (0)
; #define PG8_LDA(dst, b, h) do { _Pragma("unroll") for (int m = 0; m < 4; ++m) _Pragma("unroll") for (int k = 0; k < 2; ++k) dst[m][k] = *(const LAS bf16x8*)(lds + PG8_SA(b, h) + aoff + m * 2048 + k * 1024); } while (0)
; #define PG8_LDB(dst, b, h) do { _Pragma("unroll") for (int n = 0; n < 2; ++n) _Pragma("unroll") for (int k = 0; k < 2; ++k) dst[n][k] = *(const LAS bf16x8*)(lds + PG8_SB(b, h) + boff + n * 2048 + k * 1024); } while (0)
; #define PG8_MMA(ai, bj, At, Bt) do { __builtin_amdgcn_s_setprio(1); _Pragma("unroll") for (int m = 0; m < 4; ++m) _Pragma("unroll") for (int n = 0; n < 2; ++n) _Pragma("unroll") for (int k = 0; k < 2; ++k) \
;         acc[ai][bj][m][n] = __builtin_amdgcn_mfma_f32_16x16x32_bf16(Bt[n][k], At[m][k], acc[ai][bj][m][n], 0, 0, 0); __builtin_amdgcn_s_setprio(0); } while (0)
; #define PG8_WAIT_V(n) asm volatile("s_waitcnt vmcnt(" #n ")" ::: "memory")
; #define PG8_WAIT_L(n) asm volatile("s_waitcnt lgkmcnt(" #n ")" ::: "memory")
; #define PG8_BAR __builtin_amdgcn_s_barrier()
; #define PG8_SCHED __builtin_amdgcn_sched_barrier(0)
; template <class Epi, class Sched>
; __device__ __forceinline__ void gemm_phase(LAS unsigned char* lds, const Gemm g, const Sched& S, const Epi& E) {
;     ...
;             PG8_LDB(B0, 1, 0); PG8_SCHED; PG8_LDA(At, 1, 0); PG8_STAGE(PG8_SA(0, 1), a2 + hstep, voffA);
;             PG8_WAIT_L(8); PG8_BAR; PG8_WAIT_L(0); PG8_MMA(0, 0, At, B0); PG8_BAR; PG8_SCHED;
;             PG8_LDB(B1, 1, 1); PG8_STAGE(PG8_SB(1, 0), b3, voffB);
;             PG8_BAR; PG8_WAIT_L(0); PG8_MMA(0, 1, At, B1); PG8_BAR;
;             PG8_LDA(At, 1, 1); PG8_STAGE(PG8_SA(1, 0), a3, voffA);
;             PG8_BAR; PG8_WAIT_L(0); PG8_MMA(1, 0, At, B0); PG8_BAR; PG8_SCHED;
;             PG8_STAGE(PG8_SB(1, 1), b3 + hstep, voffB);
;             PG8_WAIT_V(6); PG8_BAR; PG8_MMA(1, 1, At, B1); PG8_BAR;
	s_add_u32 s38, s48, 0x80000
	s_addc_u32 s39, s49, 0
	s_add_i32 s74, s75, s56
	v_lshl_add_u64 v[146:147], s[38:39], 0, v[0:1]
	s_mov_b32 m0, s74
	s_nop 0
	global_load_lds_dwordx4 v[146:147], off
	v_lshl_add_u64 v[146:147], s[38:39], 0, v[130:131]
	s_add_i32 m0, s74, 0x2000
	s_nop 0
	global_load_lds_dwordx4 v[146:147], off
	s_add_u32 s38, s50, 0x80000
	s_addc_u32 s39, s51, 0
	s_mov_b32 m0, s61
	v_lshl_add_u64 v[196:197], s[38:39], 0, v[134:135]
	global_load_lds_dwordx4 v[196:197], off
	v_lshl_add_u64 v[196:197], s[38:39], 0, v[132:133]
	s_mov_b32 m0, s62
	s_nop 0
	global_load_lds_dwordx4 v[196:197], off
	s_add_i32 s74, 0, 0x18000
	v_add_u32_e32 v160, s74, v143
	ds_read_b128 v[146:149], v160
	ds_read_b128 v[150:153], v160 offset:1024
	ds_read_b128 v[154:157], v160 offset:2048
	ds_read_b128 v[160:163], v160 offset:3072
	ds_read_b128 v[164:167], v145 offset:32768
	ds_read_b128 v[168:171], v145 offset:33792
	ds_read_b128 v[172:175], v145 offset:34816
	ds_read_b128 v[176:179], v145 offset:35840
	ds_read_b128 v[180:183], v145 offset:36864
	ds_read_b128 v[184:187], v145 offset:37888
	ds_read_b128 v[188:191], v145 offset:38912
	ds_read_b128 v[192:195], v145 offset:39936
	s_add_i32 s50, 0, 0x1c000
	v_add_u32_e32 v210, s50, v143
	ds_read_b128 v[196:199], v210
	ds_read_b128 v[200:203], v210 offset:1024
	ds_read_b128 v[204:207], v210 offset:2048
	ds_read_b128 v[210:213], v210 offset:3072
	s_waitcnt lgkmcnt(4)
	s_barrier
	s_waitcnt lgkmcnt(0)
	s_setprio 1
	v_mfma_f32_16x16x32_bf16 v[126:129], v[146:149], v[164:167], v[126:129]
	v_mfma_f32_16x16x32_bf16 v[122:125], v[154:157], v[164:167], v[122:125]
	v_mfma_f32_16x16x32_bf16 v[110:113], v[146:149], v[172:175], v[110:113]
	v_mfma_f32_16x16x32_bf16 v[106:109], v[154:157], v[172:175], v[106:109]
	v_mfma_f32_16x16x32_bf16 v[94:97], v[146:149], v[180:183], v[94:97]
	v_mfma_f32_16x16x32_bf16 v[90:93], v[154:157], v[180:183], v[90:93]
	v_mfma_f32_16x16x32_bf16 v[78:81], v[146:149], v[188:191], v[78:81]
	v_mfma_f32_16x16x32_bf16 v[74:77], v[154:157], v[188:191], v[74:77]
	v_mfma_f32_16x16x32_bf16 v[126:129], v[150:153], v[168:171], v[126:129]
	v_mfma_f32_16x16x32_bf16 v[122:125], v[160:163], v[168:171], v[122:125]
	v_mfma_f32_16x16x32_bf16 v[110:113], v[150:153], v[176:179], v[110:113]
	v_mfma_f32_16x16x32_bf16 v[106:109], v[160:163], v[176:179], v[106:109]
	v_mfma_f32_16x16x32_bf16 v[94:97], v[150:153], v[184:187], v[94:97]
	v_mfma_f32_16x16x32_bf16 v[90:93], v[160:163], v[184:187], v[90:93]
	v_mfma_f32_16x16x32_bf16 v[78:81], v[150:153], v[192:195], v[78:81]
	v_mfma_f32_16x16x32_bf16 v[74:77], v[160:163], v[192:195], v[74:77]
	v_mfma_f32_16x16x32_bf16 v[118:121], v[196:199], v[164:167], v[118:121]
	v_mfma_f32_16x16x32_bf16 v[114:117], v[204:207], v[164:167], v[114:117]
	v_mfma_f32_16x16x32_bf16 v[102:105], v[196:199], v[172:175], v[102:105]
	v_mfma_f32_16x16x32_bf16 v[98:101], v[204:207], v[172:175], v[98:101]
	v_mfma_f32_16x16x32_bf16 v[86:89], v[196:199], v[180:183], v[86:89]
	v_mfma_f32_16x16x32_bf16 v[82:85], v[204:207], v[180:183], v[82:85]
	v_mfma_f32_16x16x32_bf16 v[70:73], v[196:199], v[188:191], v[70:73]
	v_mfma_f32_16x16x32_bf16 v[66:69], v[204:207], v[188:191], v[66:69]
	v_mfma_f32_16x16x32_bf16 v[118:121], v[200:203], v[168:171], v[118:121]
	v_mfma_f32_16x16x32_bf16 v[114:117], v[210:213], v[168:171], v[114:117]
	v_mfma_f32_16x16x32_bf16 v[102:105], v[200:203], v[176:179], v[102:105]
	v_mfma_f32_16x16x32_bf16 v[98:101], v[210:213], v[176:179], v[98:101]
	v_mfma_f32_16x16x32_bf16 v[86:89], v[200:203], v[184:187], v[86:89]
	v_mfma_f32_16x16x32_bf16 v[82:85], v[210:213], v[184:187], v[82:85]
	v_mfma_f32_16x16x32_bf16 v[70:73], v[200:203], v[192:195], v[70:73]
	v_mfma_f32_16x16x32_bf16 v[66:69], v[210:213], v[192:195], v[66:69]
	s_setprio 0
	s_barrier
	s_add_i32 s38, s74, s56
	v_lshl_add_u64 v[140:141], v[140:141], 0, s[36:37]
	s_mov_b32 m0, s38
	s_nop 0
	global_load_lds_dwordx4 v[140:141], off
	v_lshl_add_u64 v[140:141], v[214:215], 0, s[36:37]
	s_add_i32 m0, s38, 0x2000
	s_nop 0
	global_load_lds_dwordx4 v[140:141], off
	s_mov_b32 m0, s64
	v_lshl_add_u64 v[140:141], v[216:217], 0, s[36:37]
	global_load_lds_dwordx4 v[140:141], off
	v_lshl_add_u64 v[140:141], v[224:225], 0, s[36:37]
	s_mov_b32 m0, s65
	s_nop 0
	global_load_lds_dwordx4 v[140:141], off
	ds_read_b128 v[164:167], v145 offset:49152
	ds_read_b128 v[168:171], v145 offset:50176
	ds_read_b128 v[172:175], v145 offset:51200
	ds_read_b128 v[176:179], v145 offset:52224
	ds_read_b128 v[180:183], v145 offset:53248
	ds_read_b128 v[184:187], v145 offset:54272
	ds_read_b128 v[188:191], v145 offset:55296
	ds_read_b128 v[192:195], v145 offset:56320
	s_waitcnt vmcnt(4)
	s_waitcnt lgkmcnt(0)
	s_barrier
; __device__ __forceinline__ unsigned cvt_pk_bf16(float lo, float hi) { unsigned r; asm("v_cvt_pk_bf16_f32 %0, %1, %2" : "=v"(r) : "v"(lo), "v"(hi)); return r; }
; #define PG8_MMA(ai, bj, At, Bt) do { __builtin_amdgcn_s_setprio(1); _Pragma("unroll") for (int m = 0; m < 4; ++m) _Pragma("unroll") for (int n = 0; n < 2; ++n) _Pragma("unroll") for (int k = 0; k < 2; ++k) \
;         acc[ai][bj][m][n] = __builtin_amdgcn_mfma_f32_16x16x32_bf16(Bt[n][k], At[m][k], acc[ai][bj][m][n], 0, 0, 0); __builtin_amdgcn_s_setprio(0); } while (0)
; #define PG8_WAIT_V(n) asm volatile("s_waitcnt vmcnt(" #n ")" ::: "memory")
; #define PG8_BAR __builtin_amdgcn_s_barrier()
;     __device__ __forceinline__ void operator()(const f32x4 (&acc)[2][2][4][2], const Unit& u, int wr, int wc, int fr, int fq) const {
;     ...
;             for (int m = 0; m < 4; ++m) { bf16_t* rowp = O + (size_t)(row0 + ai * HALF + m * 16) * ldc + col0;
; #pragma unroll
;                 for (int bj = 0; bj < 2; ++bj) { f32x4 v0 = acc[ai][bj][m][0], v1 = acc[ai][bj][m][1];
;                     if (ACT == 1) {
; #pragma unroll
;                         for (int j = 0; j < 4; ++j) { float a = fmaxf(v0[j], 0.f), b = fmaxf(v1[j], 0.f); v0[j] = a * a; v1[j] = b * b; } }
;                     u32x4 w; w.x = cvt_pk_bf16(v0[0], v0[1]); w.y = cvt_pk_bf16(v0[2], v0[3]); w.z = cvt_pk_bf16(v1[0], v1[1]); w.w = cvt_pk_bf16(v1[2], v1[3]);
;                     if (ACT == 1) __builtin_nontemporal_store(w, (u32x4*)(rowp + bj * HALF));
;                     else *(u32x4*)(rowp + bj * HALF) = w; } }
; template <class Epi, class Sched>
; __device__ __forceinline__ void gemm_phase(LAS unsigned char* lds, const Gemm g, const Sched& S, const Epi& E) {
;     ...
;             PG8_WAIT_V(6); PG8_BAR; PG8_MMA(1, 1, At, B1); PG8_BAR;
;         }
;         E(acc, cur, wr, wc, fr, fq);
	s_setprio 1
	v_mfma_f32_16x16x32_bf16 v[62:65], v[146:149], v[164:167], v[62:65]
	v_mfma_f32_16x16x32_bf16 v[58:61], v[154:157], v[164:167], v[58:61]
	v_mfma_f32_16x16x32_bf16 v[46:49], v[146:149], v[172:175], v[46:49]
	v_mfma_f32_16x16x32_bf16 v[42:45], v[154:157], v[172:175], v[42:45]
	v_mfma_f32_16x16x32_bf16 v[30:33], v[146:149], v[180:183], v[30:33]
	v_mfma_f32_16x16x32_bf16 v[26:29], v[154:157], v[180:183], v[26:29]
	v_mfma_f32_16x16x32_bf16 v[14:17], v[146:149], v[188:191], v[14:17]
	v_mfma_f32_16x16x32_bf16 v[10:13], v[154:157], v[188:191], v[10:13]
	v_mfma_f32_16x16x32_bf16 v[62:65], v[150:153], v[168:171], v[62:65]
	v_mfma_f32_16x16x32_bf16 v[58:61], v[160:163], v[168:171], v[58:61]
	v_mfma_f32_16x16x32_bf16 v[46:49], v[150:153], v[176:179], v[46:49]
	v_mfma_f32_16x16x32_bf16 v[42:45], v[160:163], v[176:179], v[42:45]
	v_mfma_f32_16x16x32_bf16 v[30:33], v[150:153], v[184:187], v[30:33]
	v_mfma_f32_16x16x32_bf16 v[26:29], v[160:163], v[184:187], v[26:29]
	v_mfma_f32_16x16x32_bf16 v[14:17], v[150:153], v[192:195], v[14:17]
	v_mfma_f32_16x16x32_bf16 v[10:13], v[160:163], v[192:195], v[10:13]
	s_add_u32 s38, s48, 0x80080
	s_addc_u32 s39, s49, 0
	s_add_i32 s48, s50, s56
	v_lshl_add_u64 v[140:141], s[38:39], 0, v[0:1]
	s_mov_b32 m0, s48
	s_nop 0
	global_load_lds_dwordx4 v[140:141], off
	v_lshl_add_u64 v[140:141], s[38:39], 0, v[130:131]
	s_add_i32 m0, s48, 0x2000
	s_nop 0
	global_load_lds_dwordx4 v[140:141], off
	v_mfma_f32_16x16x32_bf16 v[54:57], v[196:199], v[164:167], v[54:57]
	v_mfma_f32_16x16x32_bf16 v[50:53], v[204:207], v[164:167], v[50:53]
	v_mfma_f32_16x16x32_bf16 v[38:41], v[196:199], v[172:175], v[38:41]
	v_mfma_f32_16x16x32_bf16 v[34:37], v[204:207], v[172:175], v[34:37]
	v_mfma_f32_16x16x32_bf16 v[22:25], v[196:199], v[180:183], v[22:25]
	v_mfma_f32_16x16x32_bf16 v[18:21], v[204:207], v[180:183], v[18:21]
	v_mfma_f32_16x16x32_bf16 v[6:9], v[196:199], v[188:191], v[6:9]
	v_mfma_f32_16x16x32_bf16 v[2:5], v[204:207], v[188:191], v[2:5]
	v_mfma_f32_16x16x32_bf16 v[54:57], v[200:203], v[168:171], v[54:57]
	v_mfma_f32_16x16x32_bf16 v[50:53], v[210:213], v[168:171], v[50:53]
	v_mfma_f32_16x16x32_bf16 v[38:41], v[200:203], v[176:179], v[38:41]
	v_mfma_f32_16x16x32_bf16 v[34:37], v[210:213], v[176:179], v[34:37]
	v_mfma_f32_16x16x32_bf16 v[22:25], v[200:203], v[184:187], v[22:25]
	v_mfma_f32_16x16x32_bf16 v[18:21], v[210:213], v[184:187], v[18:21]
	v_mfma_f32_16x16x32_bf16 v[6:9], v[200:203], v[192:195], v[6:9]
	v_mfma_f32_16x16x32_bf16 v[2:5], v[210:213], v[192:195], v[2:5]
	s_setprio 0
	s_add_i32 s73, s73, 2
	s_add_u32 s71, s71, 0x100
	s_addc_u32 s72, s72, 0
	s_add_u32 s46, s46, 0x100
	s_addc_u32 s47, s47, 0
	s_cmp_gt_u32 s73, 29
	s_barrier
	s_cbranch_scc0 .LBB0_73
	v_lshl_add_u32 v146, s8, 8, v142
	v_max_f32_e32 v122, v122, v122
	v_ashrrev_i32_e32 v147, 31, v146
	v_max_f32_e32 v122, 0, v122
	v_max_f32_e32 v123, v123, v123
	v_max_f32_e32 v124, v124, v124
	v_lshl_or_b32 v140, s68, 8, v144
	v_lshlrev_b64 v[148:149], 14, v[146:147]
	v_mul_f32_e32 v147, v122, v122
	v_max_f32_e32 v122, v127, v127
	v_max_f32_e32 v123, 0, v123
	v_max_f32_e32 v124, 0, v124
	v_ashrrev_i32_e32 v141, 31, v140
	v_max_f32_e32 v126, v126, v126
	v_max_f32_e32 v122, 0, v122
	v_mul_f32_e32 v127, v123, v123
	v_max_f32_e32 v123, v128, v128
	v_mul_f32_e32 v128, v124, v124
	v_max_f32_e32 v124, v129, v129
	v_max_f32_e32 v125, v125, v125
	v_lshl_add_u64 v[148:149], s[24:25], 0, v[148:149]
	v_lshlrev_b64 v[150:151], 1, v[140:141]
	v_max_f32_e32 v126, 0, v126
	v_mul_f32_e32 v122, v122, v122
	v_max_f32_e32 v123, 0, v123
	v_max_f32_e32 v124, 0, v124
	v_max_f32_e32 v125, 0, v125
	v_max_f32_e32 v114, v114, v114
	v_lshl_add_u64 v[140:141], v[148:149], 0, v[150:151]
	v_mul_f32_e32 v126, v126, v126
	v_mul_f32_e32 v123, v123, v123
	v_mul_f32_e32 v124, v124, v124
	v_mul_f32_e32 v125, v125, v125
	v_cvt_pk_bf16_f32 v122, v126, v122
	v_max_f32_e32 v114, 0, v114
	v_max_f32_e32 v115, v115, v115
	v_max_f32_e32 v116, v116, v116
	v_cvt_pk_bf16_f32 v123, v123, v124
	v_cvt_pk_bf16_f32 v124, v147, v127
	v_cvt_pk_bf16_f32 v125, v128, v125
	global_store_dwordx4 v[140:141], v[122:125], off nt
	v_max_f32_e32 v115, 0, v115
	v_max_f32_e32 v116, 0, v116
	v_mul_f32_e32 v122, v114, v114
	v_max_f32_e32 v114, v119, v119
	v_max_f32_e32 v118, v118, v118
	v_max_f32_e32 v114, 0, v114
	v_mul_f32_e32 v119, v115, v115
	v_max_f32_e32 v115, v120, v120
	v_mul_f32_e32 v120, v116, v116
	v_max_f32_e32 v116, v121, v121
	v_max_f32_e32 v117, v117, v117
	v_max_f32_e32 v118, 0, v118
	v_mul_f32_e32 v114, v114, v114
	v_max_f32_e32 v115, 0, v115
	v_max_f32_e32 v116, 0, v116
	v_max_f32_e32 v117, 0, v117
	v_mul_f32_e32 v118, v118, v118
	v_mul_f32_e32 v115, v115, v115
	v_mul_f32_e32 v116, v116, v116
	v_mul_f32_e32 v117, v117, v117
	v_cvt_pk_bf16_f32 v114, v118, v114
	v_max_f32_e32 v106, v106, v106
	v_cvt_pk_bf16_f32 v115, v115, v116
	v_cvt_pk_bf16_f32 v116, v122, v119
	v_cvt_pk_bf16_f32 v117, v120, v117
	global_store_dwordx4 v[140:141], v[114:117], off offset:256 nt
	v_max_f32_e32 v106, 0, v106
	v_max_f32_e32 v107, v107, v107
	v_or_b32_e32 v114, 16, v146
	v_max_f32_e32 v108, v108, v108
	v_ashrrev_i32_e32 v115, 31, v114
	v_mul_f32_e32 v116, v106, v106
	v_max_f32_e32 v106, v111, v111
	v_max_f32_e32 v107, 0, v107
	v_max_f32_e32 v108, 0, v108
	v_lshlrev_b64 v[114:115], 14, v[114:115]
	v_max_f32_e32 v110, v110, v110
	v_max_f32_e32 v106, 0, v106
	v_mul_f32_e32 v111, v107, v107
	v_max_f32_e32 v107, v112, v112
	v_mul_f32_e32 v112, v108, v108
	v_max_f32_e32 v108, v113, v113
	v_max_f32_e32 v109, v109, v109
	v_lshl_add_u64 v[114:115], s[24:25], 0, v[114:115]
	v_max_f32_e32 v110, 0, v110
	v_mul_f32_e32 v106, v106, v106
; __device__ __forceinline__ unsigned cvt_pk_bf16(float lo, float hi) { unsigned r; asm("v_cvt_pk_bf16_f32 %0, %1, %2" : "=v"(r) : "v"(lo), "v"(hi)); return r; }
;     __device__ __forceinline__ void operator()(const f32x4 (&acc)[2][2][4][2], const Unit& u, int wr, int wc, int fr, int fq) const {
;     ...
;             for (int m = 0; m < 4; ++m) { bf16_t* rowp = O + (size_t)(row0 + ai * HALF + m * 16) * ldc + col0;
; #pragma unroll
;                 for (int bj = 0; bj < 2; ++bj) { f32x4 v0 = acc[ai][bj][m][0], v1 = acc[ai][bj][m][1];
;                     if (ACT == 1) {
; #pragma unroll
;                         for (int j = 0; j < 4; ++j) { float a = fmaxf(v0[j], 0.f), b = fmaxf(v1[j], 0.f); v0[j] = a * a; v1[j] = b * b; } }
;                     u32x4 w; w.x = cvt_pk_bf16(v0[0], v0[1]); w.y = cvt_pk_bf16(v0[2], v0[3]); w.z = cvt_pk_bf16(v1[0], v1[1]); w.w = cvt_pk_bf16(v1[2], v1[3]);
;                     if (ACT == 1) __builtin_nontemporal_store(w, (u32x4*)(rowp + bj * HALF));
;                     else *(u32x4*)(rowp + bj * HALF) = w; } }
	v_max_f32_e32 v107, 0, v107
	v_max_f32_e32 v108, 0, v108
	v_max_f32_e32 v109, 0, v109
	v_max_f32_e32 v98, v98, v98
	v_lshl_add_u64 v[114:115], v[114:115], 0, v[150:151]
	v_mul_f32_e32 v110, v110, v110
	v_mul_f32_e32 v107, v107, v107
	v_mul_f32_e32 v108, v108, v108
	v_mul_f32_e32 v109, v109, v109
	v_cvt_pk_bf16_f32 v106, v110, v106
	v_max_f32_e32 v98, 0, v98
	v_max_f32_e32 v99, v99, v99
	v_max_f32_e32 v100, v100, v100
	v_cvt_pk_bf16_f32 v107, v107, v108
	v_cvt_pk_bf16_f32 v108, v116, v111
	v_cvt_pk_bf16_f32 v109, v112, v109
	global_store_dwordx4 v[114:115], v[106:109], off nt
	v_max_f32_e32 v99, 0, v99
	v_max_f32_e32 v100, 0, v100
	v_mul_f32_e32 v106, v98, v98
	v_max_f32_e32 v98, v103, v103
	v_max_f32_e32 v102, v102, v102
	v_max_f32_e32 v98, 0, v98
	v_mul_f32_e32 v103, v99, v99
	v_max_f32_e32 v99, v104, v104
	v_mul_f32_e32 v104, v100, v100
	v_max_f32_e32 v100, v105, v105
	v_max_f32_e32 v101, v101, v101
	v_max_f32_e32 v102, 0, v102
	v_mul_f32_e32 v98, v98, v98
	v_max_f32_e32 v99, 0, v99
	v_max_f32_e32 v100, 0, v100
	v_max_f32_e32 v101, 0, v101
	v_mul_f32_e32 v102, v102, v102
	v_mul_f32_e32 v99, v99, v99
	v_mul_f32_e32 v100, v100, v100
	v_mul_f32_e32 v101, v101, v101
	v_cvt_pk_bf16_f32 v98, v102, v98
	v_max_f32_e32 v90, v90, v90
	v_cvt_pk_bf16_f32 v99, v99, v100
	v_cvt_pk_bf16_f32 v100, v106, v103
	v_cvt_pk_bf16_f32 v101, v104, v101
	global_store_dwordx4 v[114:115], v[98:101], off offset:256 nt
	v_max_f32_e32 v90, 0, v90
	v_max_f32_e32 v91, v91, v91
	v_or_b32_e32 v98, 32, v146
	v_max_f32_e32 v92, v92, v92
	v_ashrrev_i32_e32 v99, 31, v98
	v_mul_f32_e32 v100, v90, v90
	v_max_f32_e32 v90, v95, v95
	v_max_f32_e32 v91, 0, v91
	v_max_f32_e32 v92, 0, v92
	v_lshlrev_b64 v[98:99], 14, v[98:99]
	v_max_f32_e32 v94, v94, v94
	v_max_f32_e32 v90, 0, v90
	v_mul_f32_e32 v95, v91, v91
	v_max_f32_e32 v91, v96, v96
	v_mul_f32_e32 v96, v92, v92
	v_max_f32_e32 v92, v97, v97
	v_max_f32_e32 v93, v93, v93
	v_lshl_add_u64 v[98:99], s[24:25], 0, v[98:99]
	v_max_f32_e32 v94, 0, v94
	v_mul_f32_e32 v90, v90, v90
	v_max_f32_e32 v91, 0, v91
	v_max_f32_e32 v92, 0, v92
	v_max_f32_e32 v93, 0, v93
	v_max_f32_e32 v82, v82, v82
	v_lshl_add_u64 v[98:99], v[98:99], 0, v[150:151]
	v_mul_f32_e32 v94, v94, v94
	v_mul_f32_e32 v91, v91, v91
	v_mul_f32_e32 v92, v92, v92
	v_mul_f32_e32 v93, v93, v93
	v_cvt_pk_bf16_f32 v90, v94, v90
	v_max_f32_e32 v82, 0, v82
	v_max_f32_e32 v83, v83, v83
	v_max_f32_e32 v84, v84, v84
	v_cvt_pk_bf16_f32 v91, v91, v92
	v_cvt_pk_bf16_f32 v92, v100, v95
	v_cvt_pk_bf16_f32 v93, v96, v93
	global_store_dwordx4 v[98:99], v[90:93], off nt
	v_max_f32_e32 v83, 0, v83
	v_max_f32_e32 v84, 0, v84
	v_mul_f32_e32 v90, v82, v82
	v_max_f32_e32 v82, v87, v87
	v_max_f32_e32 v86, v86, v86
	v_max_f32_e32 v82, 0, v82
	v_mul_f32_e32 v87, v83, v83
	v_max_f32_e32 v83, v88, v88
	v_mul_f32_e32 v88, v84, v84
	v_max_f32_e32 v84, v89, v89
	v_max_f32_e32 v85, v85, v85
	v_max_f32_e32 v86, 0, v86
	v_mul_f32_e32 v82, v82, v82
	v_max_f32_e32 v83, 0, v83
	v_max_f32_e32 v84, 0, v84
	v_max_f32_e32 v85, 0, v85
	v_mul_f32_e32 v86, v86, v86
	v_mul_f32_e32 v83, v83, v83
	v_mul_f32_e32 v84, v84, v84
	v_mul_f32_e32 v85, v85, v85
	v_cvt_pk_bf16_f32 v82, v86, v82
	v_max_f32_e32 v74, v74, v74
	v_cvt_pk_bf16_f32 v83, v83, v84
	v_cvt_pk_bf16_f32 v84, v90, v87
	v_cvt_pk_bf16_f32 v85, v88, v85
	global_store_dwordx4 v[98:99], v[82:85], off offset:256 nt
	v_max_f32_e32 v74, 0, v74
	v_max_f32_e32 v75, v75, v75
	v_or_b32_e32 v82, 48, v146
	v_max_f32_e32 v76, v76, v76
	v_ashrrev_i32_e32 v83, 31, v82
	v_mul_f32_e32 v84, v74, v74
	v_max_f32_e32 v74, v79, v79
	v_max_f32_e32 v75, 0, v75
	v_max_f32_e32 v76, 0, v76
	v_lshlrev_b64 v[82:83], 14, v[82:83]
	v_max_f32_e32 v78, v78, v78
	v_max_f32_e32 v74, 0, v74
	v_mul_f32_e32 v79, v75, v75
	v_max_f32_e32 v75, v80, v80
	v_mul_f32_e32 v80, v76, v76
	v_max_f32_e32 v76, v81, v81
	v_max_f32_e32 v77, v77, v77
	v_lshl_add_u64 v[82:83], s[24:25], 0, v[82:83]
	v_max_f32_e32 v78, 0, v78
	v_mul_f32_e32 v74, v74, v74
	v_max_f32_e32 v75, 0, v75
	v_max_f32_e32 v76, 0, v76
	v_max_f32_e32 v77, 0, v77
	v_max_f32_e32 v66, v66, v66
	v_max_f32_e32 v67, v67, v67
	v_max_f32_e32 v68, v68, v68
	v_lshl_add_u64 v[82:83], v[82:83], 0, v[150:151]
	v_mul_f32_e32 v78, v78, v78
	v_mul_f32_e32 v75, v75, v75
	v_mul_f32_e32 v76, v76, v76
	v_mul_f32_e32 v77, v77, v77
	v_cvt_pk_bf16_f32 v74, v78, v74
	v_max_f32_e32 v66, 0, v66
	v_max_f32_e32 v67, 0, v67
	v_max_f32_e32 v68, 0, v68
	v_cvt_pk_bf16_f32 v75, v75, v76
	v_cvt_pk_bf16_f32 v76, v84, v79
	v_cvt_pk_bf16_f32 v77, v80, v77
	global_store_dwordx4 v[82:83], v[74:77], off nt
	v_max_f32_e32 v69, v69, v69
	v_max_f32_e32 v70, v70, v70
	v_mul_f32_e32 v74, v66, v66
	v_max_f32_e32 v66, v71, v71
	v_mul_f32_e32 v71, v67, v67
	v_max_f32_e32 v67, v72, v72
	v_mul_f32_e32 v72, v68, v68
	v_max_f32_e32 v68, v73, v73
	v_max_f32_e32 v67, 0, v67
	v_max_f32_e32 v68, 0, v68
	v_max_f32_e32 v66, 0, v66
	v_mul_f32_e32 v67, v67, v67
	v_max_f32_e32 v69, 0, v69
	v_mul_f32_e32 v68, v68, v68
	v_max_f32_e32 v58, v58, v58
	v_max_f32_e32 v70, 0, v70
	v_mul_f32_e32 v66, v66, v66
	v_mul_f32_e32 v69, v69, v69
	v_cvt_pk_bf16_f32 v67, v67, v68
	v_cvt_pk_bf16_f32 v68, v74, v71
	v_max_f32_e32 v58, 0, v58
	v_max_f32_e32 v59, v59, v59
	v_max_f32_e32 v60, v60, v60
	v_mul_f32_e32 v70, v70, v70
	v_cvt_pk_bf16_f32 v66, v70, v66
	v_cvt_pk_bf16_f32 v69, v72, v69
	global_store_dwordx4 v[82:83], v[66:69], off offset:256 nt
	v_max_f32_e32 v62, v62, v62
	v_max_f32_e32 v59, 0, v59
	v_mul_f32_e32 v68, v58, v58
	v_max_f32_e32 v58, v63, v63
	v_max_f32_e32 v60, 0, v60
	v_max_f32_e32 v62, 0, v62
	v_max_f32_e32 v58, 0, v58
	v_mul_f32_e32 v63, v59, v59
	v_max_f32_e32 v59, v64, v64
	v_mul_f32_e32 v64, v60, v60
; __device__ __forceinline__ unsigned cvt_pk_bf16(float lo, float hi) { unsigned r; asm("v_cvt_pk_bf16_f32 %0, %1, %2" : "=v"(r) : "v"(lo), "v"(hi)); return r; }
;     __device__ __forceinline__ void operator()(const f32x4 (&acc)[2][2][4][2], const Unit& u, int wr, int wc, int fr, int fq) const {
;     ...
;             for (int m = 0; m < 4; ++m) { bf16_t* rowp = O + (size_t)(row0 + ai * HALF + m * 16) * ldc + col0;
; #pragma unroll
;                 for (int bj = 0; bj < 2; ++bj) { f32x4 v0 = acc[ai][bj][m][0], v1 = acc[ai][bj][m][1];
;                     if (ACT == 1) {
; #pragma unroll
;                         for (int j = 0; j < 4; ++j) { float a = fmaxf(v0[j], 0.f), b = fmaxf(v1[j], 0.f); v0[j] = a * a; v1[j] = b * b; } }
;                     u32x4 w; w.x = cvt_pk_bf16(v0[0], v0[1]); w.y = cvt_pk_bf16(v0[2], v0[3]); w.z = cvt_pk_bf16(v1[0], v1[1]); w.w = cvt_pk_bf16(v1[2], v1[3]);
;                     if (ACT == 1) __builtin_nontemporal_store(w, (u32x4*)(rowp + bj * HALF));
;                     else *(u32x4*)(rowp + bj * HALF) = w; } }
	v_max_f32_e32 v60, v65, v65
	v_mul_f32_e32 v62, v62, v62
	v_mul_f32_e32 v58, v58, v58
	v_max_f32_e32 v59, 0, v59
	v_max_f32_e32 v60, 0, v60
	v_max_f32_e32 v61, v61, v61
	s_mov_b32 s8, 0x200000
	v_mul_f32_e32 v59, v59, v59
	v_max_f32_e32 v61, 0, v61
	v_mul_f32_e32 v60, v60, v60
	v_cvt_pk_bf16_f32 v58, v62, v58
	v_add_co_u32_e32 v62, vcc, s8, v140
	v_max_f32_e32 v50, v50, v50
	v_max_f32_e32 v51, v51, v51
	v_max_f32_e32 v52, v52, v52
	v_mul_f32_e32 v61, v61, v61
	v_cvt_pk_bf16_f32 v59, v59, v60
	v_cvt_pk_bf16_f32 v60, v68, v63
	v_addc_co_u32_e32 v63, vcc, 0, v141, vcc
	v_max_f32_e32 v50, 0, v50
	v_max_f32_e32 v51, 0, v51
	v_max_f32_e32 v52, 0, v52
	v_cvt_pk_bf16_f32 v61, v64, v61
	global_store_dwordx4 v[62:63], v[58:61], off nt
	v_max_f32_e32 v53, v53, v53
	s_mov_b64 s[38:39], 0x200000
	v_mul_f32_e32 v58, v50, v50
	v_max_f32_e32 v50, v55, v55
	v_mul_f32_e32 v55, v51, v51
	v_max_f32_e32 v51, v56, v56
	v_mul_f32_e32 v56, v52, v52
	v_max_f32_e32 v52, v57, v57
	v_max_f32_e32 v51, 0, v51
	v_max_f32_e32 v52, 0, v52
	v_max_f32_e32 v54, v54, v54
	v_max_f32_e32 v50, 0, v50
	v_mul_f32_e32 v51, v51, v51
	v_max_f32_e32 v53, 0, v53
	v_mul_f32_e32 v52, v52, v52
	v_max_f32_e32 v42, v42, v42
	v_lshl_add_u64 v[66:67], v[140:141], 0, s[38:39]
	v_max_f32_e32 v54, 0, v54
	v_mul_f32_e32 v50, v50, v50
	v_mul_f32_e32 v53, v53, v53
	v_cvt_pk_bf16_f32 v51, v51, v52
	v_cvt_pk_bf16_f32 v52, v58, v55
	v_max_f32_e32 v42, 0, v42
	v_max_f32_e32 v43, v43, v43
	v_max_f32_e32 v44, v44, v44
	v_mul_f32_e32 v54, v54, v54
	v_cvt_pk_bf16_f32 v50, v54, v50
	v_cvt_pk_bf16_f32 v53, v56, v53
	global_store_dwordx4 v[66:67], v[50:53], off offset:256 nt
	v_max_f32_e32 v46, v46, v46
	v_max_f32_e32 v43, 0, v43
	v_mul_f32_e32 v52, v42, v42
	v_max_f32_e32 v42, v47, v47
	v_max_f32_e32 v44, 0, v44
	v_max_f32_e32 v46, 0, v46
	v_max_f32_e32 v42, 0, v42
	v_mul_f32_e32 v47, v43, v43
	v_max_f32_e32 v43, v48, v48
	v_mul_f32_e32 v48, v44, v44
	v_max_f32_e32 v44, v49, v49
	v_mul_f32_e32 v46, v46, v46
	v_mul_f32_e32 v42, v42, v42
	v_max_f32_e32 v43, 0, v43
	v_max_f32_e32 v44, 0, v44
	v_max_f32_e32 v45, v45, v45
	s_mov_b32 s8, 0x240000
	v_mul_f32_e32 v43, v43, v43
	v_max_f32_e32 v45, 0, v45
	v_mul_f32_e32 v44, v44, v44
	v_cvt_pk_bf16_f32 v42, v46, v42
	v_add_co_u32_e32 v46, vcc, s8, v140
	v_max_f32_e32 v34, v34, v34
	v_max_f32_e32 v35, v35, v35
	v_max_f32_e32 v36, v36, v36
	v_mul_f32_e32 v45, v45, v45
	v_cvt_pk_bf16_f32 v43, v43, v44
	v_cvt_pk_bf16_f32 v44, v52, v47
	v_addc_co_u32_e32 v47, vcc, 0, v141, vcc
	v_max_f32_e32 v34, 0, v34
	v_max_f32_e32 v35, 0, v35
	v_max_f32_e32 v36, 0, v36
	v_cvt_pk_bf16_f32 v45, v48, v45
	global_store_dwordx4 v[46:47], v[42:45], off nt
	v_max_f32_e32 v37, v37, v37
	s_mov_b64 s[38:39], 0x240000
	v_mul_f32_e32 v42, v34, v34
	v_max_f32_e32 v34, v39, v39
	v_mul_f32_e32 v39, v35, v35
	v_max_f32_e32 v35, v40, v40
	v_mul_f32_e32 v40, v36, v36
	v_max_f32_e32 v36, v41, v41
	v_max_f32_e32 v35, 0, v35
	v_max_f32_e32 v36, 0, v36
	v_max_f32_e32 v38, v38, v38
	v_max_f32_e32 v34, 0, v34
	v_mul_f32_e32 v35, v35, v35
	v_max_f32_e32 v37, 0, v37
	v_mul_f32_e32 v36, v36, v36
	v_max_f32_e32 v26, v26, v26
	v_lshl_add_u64 v[50:51], v[140:141], 0, s[38:39]
	v_max_f32_e32 v38, 0, v38
	v_mul_f32_e32 v34, v34, v34
	v_mul_f32_e32 v37, v37, v37
	v_cvt_pk_bf16_f32 v35, v35, v36
	v_cvt_pk_bf16_f32 v36, v42, v39
	v_max_f32_e32 v26, 0, v26
	v_max_f32_e32 v27, v27, v27
	v_max_f32_e32 v28, v28, v28
	v_mul_f32_e32 v38, v38, v38
	v_cvt_pk_bf16_f32 v34, v38, v34
	v_cvt_pk_bf16_f32 v37, v40, v37
	global_store_dwordx4 v[50:51], v[34:37], off offset:256 nt
	v_max_f32_e32 v30, v30, v30
	v_max_f32_e32 v27, 0, v27
	v_mul_f32_e32 v36, v26, v26
	v_max_f32_e32 v26, v31, v31
	v_max_f32_e32 v28, 0, v28
	v_max_f32_e32 v30, 0, v30
; __device__ __forceinline__ unsigned cvt_pk_bf16(float lo, float hi) { unsigned r; asm("v_cvt_pk_bf16_f32 %0, %1, %2" : "=v"(r) : "v"(lo), "v"(hi)); return r; }
; #define PG8_WAIT_V(n) asm volatile("s_waitcnt vmcnt(" #n ")" ::: "memory")
; #define PG8_BAR __builtin_amdgcn_s_barrier()
;     __device__ __forceinline__ void operator()(const f32x4 (&acc)[2][2][4][2], const Unit& u, int wr, int wc, int fr, int fq) const {
;     ...
;                 for (int bj = 0; bj < 2; ++bj) { f32x4 v0 = acc[ai][bj][m][0], v1 = acc[ai][bj][m][1];
;                     if (ACT == 1) {
; #pragma unroll
;                         for (int j = 0; j < 4; ++j) { float a = fmaxf(v0[j], 0.f), b = fmaxf(v1[j], 0.f); v0[j] = a * a; v1[j] = b * b; } }
;                     u32x4 w; w.x = cvt_pk_bf16(v0[0], v0[1]); w.y = cvt_pk_bf16(v0[2], v0[3]); w.z = cvt_pk_bf16(v1[0], v1[1]); w.w = cvt_pk_bf16(v1[2], v1[3]);
;                     if (ACT == 1) __builtin_nontemporal_store(w, (u32x4*)(rowp + bj * HALF));
;                     else *(u32x4*)(rowp + bj * HALF) = w; } }
; template <class Epi, class Sched>
; __device__ __forceinline__ void gemm_phase(LAS unsigned char* lds, const Gemm g, const Sched& S, const Epi& E) {
;     ...
;         E(acc, cur, wr, wc, fr, fq);
;         if (!has_next) break;
; #pragma unroll
;         for (int a = 0; a < 2; ++a)
; #pragma unroll
;             for (int b = 0; b < 2; ++b)
; #pragma unroll
;                 for (int m = 0; m < 4; ++m)
; #pragma unroll
;                     for (int n = 0; n < 2; ++n) acc[a][b][m][n] = (f32x4){0.f, 0.f, 0.f, 0.f};
;         cur = nxt; cA = nA; cB = nB; ++ui;
;     }
;     PG8_WAIT_V(0);
;     if (wr == 0) PG8_BAR;
;     PG8_BAR;
	v_max_f32_e32 v26, 0, v26
	v_mul_f32_e32 v31, v27, v27
	v_max_f32_e32 v27, v32, v32
	v_mul_f32_e32 v32, v28, v28
	v_max_f32_e32 v28, v33, v33
	v_mul_f32_e32 v30, v30, v30
	v_mul_f32_e32 v26, v26, v26
	v_max_f32_e32 v27, 0, v27
	v_max_f32_e32 v28, 0, v28
	v_max_f32_e32 v29, v29, v29
	s_mov_b32 s8, 0x280000
	v_mul_f32_e32 v27, v27, v27
	v_max_f32_e32 v29, 0, v29
	v_mul_f32_e32 v28, v28, v28
	v_cvt_pk_bf16_f32 v26, v30, v26
	v_add_co_u32_e32 v30, vcc, s8, v140
	v_max_f32_e32 v18, v18, v18
	v_max_f32_e32 v19, v19, v19
	v_max_f32_e32 v20, v20, v20
	v_mul_f32_e32 v29, v29, v29
	v_cvt_pk_bf16_f32 v27, v27, v28
	v_cvt_pk_bf16_f32 v28, v36, v31
	v_addc_co_u32_e32 v31, vcc, 0, v141, vcc
	v_max_f32_e32 v18, 0, v18
	v_max_f32_e32 v19, 0, v19
	v_max_f32_e32 v20, 0, v20
	v_cvt_pk_bf16_f32 v29, v32, v29
	global_store_dwordx4 v[30:31], v[26:29], off nt
	v_max_f32_e32 v21, v21, v21
	s_mov_b64 s[38:39], 0x280000
	v_mul_f32_e32 v26, v18, v18
	v_max_f32_e32 v18, v23, v23
	v_mul_f32_e32 v23, v19, v19
	v_max_f32_e32 v19, v24, v24
	v_mul_f32_e32 v24, v20, v20
	v_max_f32_e32 v20, v25, v25
	v_max_f32_e32 v19, 0, v19
	v_max_f32_e32 v20, 0, v20
	v_max_f32_e32 v22, v22, v22
	v_max_f32_e32 v18, 0, v18
	v_mul_f32_e32 v19, v19, v19
	v_max_f32_e32 v21, 0, v21
	v_mul_f32_e32 v20, v20, v20
	v_max_f32_e32 v10, v10, v10
	v_lshl_add_u64 v[34:35], v[140:141], 0, s[38:39]
	v_max_f32_e32 v22, 0, v22
	v_mul_f32_e32 v18, v18, v18
	v_mul_f32_e32 v21, v21, v21
	v_cvt_pk_bf16_f32 v19, v19, v20
	v_cvt_pk_bf16_f32 v20, v26, v23
	v_max_f32_e32 v10, 0, v10
	v_max_f32_e32 v11, v11, v11
	v_max_f32_e32 v12, v12, v12
	v_mul_f32_e32 v22, v22, v22
	v_cvt_pk_bf16_f32 v18, v22, v18
	v_cvt_pk_bf16_f32 v21, v24, v21
	global_store_dwordx4 v[34:35], v[18:21], off offset:256 nt
	v_max_f32_e32 v14, v14, v14
	v_max_f32_e32 v11, 0, v11
	v_mul_f32_e32 v20, v10, v10
	v_max_f32_e32 v10, v15, v15
	v_max_f32_e32 v12, 0, v12
	v_max_f32_e32 v14, 0, v14
	v_max_f32_e32 v10, 0, v10
	v_mul_f32_e32 v15, v11, v11
	v_max_f32_e32 v11, v16, v16
	v_mul_f32_e32 v16, v12, v12
	v_max_f32_e32 v12, v17, v17
	v_mul_f32_e32 v14, v14, v14
	v_mul_f32_e32 v10, v10, v10
	v_max_f32_e32 v11, 0, v11
	v_max_f32_e32 v12, 0, v12
	v_max_f32_e32 v13, v13, v13
	s_mov_b32 s8, 0x2c0000
	v_mul_f32_e32 v11, v11, v11
	v_max_f32_e32 v13, 0, v13
	v_mul_f32_e32 v12, v12, v12
	v_cvt_pk_bf16_f32 v10, v14, v10
	v_add_co_u32_e32 v14, vcc, s8, v140
	v_max_f32_e32 v2, v2, v2
	v_max_f32_e32 v3, v3, v3
	v_max_f32_e32 v4, v4, v4
	v_mul_f32_e32 v13, v13, v13
	v_cvt_pk_bf16_f32 v11, v11, v12
	v_cvt_pk_bf16_f32 v12, v20, v15
	v_addc_co_u32_e32 v15, vcc, 0, v141, vcc
	v_max_f32_e32 v2, 0, v2
	v_max_f32_e32 v3, 0, v3
	v_max_f32_e32 v4, 0, v4
	v_cvt_pk_bf16_f32 v13, v16, v13
	global_store_dwordx4 v[14:15], v[10:13], off nt
	v_max_f32_e32 v5, v5, v5
	s_mov_b64 s[38:39], 0x2c0000
	v_mul_f32_e32 v10, v2, v2
	v_max_f32_e32 v2, v7, v7
	v_mul_f32_e32 v7, v3, v3
	v_max_f32_e32 v3, v8, v8
	v_mul_f32_e32 v8, v4, v4
	v_max_f32_e32 v4, v9, v9
	v_max_f32_e32 v6, v6, v6
	v_max_f32_e32 v2, 0, v2
	v_max_f32_e32 v3, 0, v3
	v_max_f32_e32 v4, 0, v4
	v_max_f32_e32 v5, 0, v5
	v_lshl_add_u64 v[18:19], v[140:141], 0, s[38:39]
	v_max_f32_e32 v6, 0, v6
	v_mul_f32_e32 v2, v2, v2
	v_mul_f32_e32 v3, v3, v3
	v_mul_f32_e32 v4, v4, v4
	v_mul_f32_e32 v5, v5, v5
	s_and_b64 vcc, exec, s[40:41]
	s_mov_b32 s68, s26
	s_mov_b32 s8, s28
	s_mov_b64 s[46:47], s[44:45]
	s_mov_b64 s[48:49], s[42:43]
	v_mul_f32_e32 v6, v6, v6
	v_cvt_pk_bf16_f32 v2, v6, v2
	v_cvt_pk_bf16_f32 v3, v3, v4
	v_cvt_pk_bf16_f32 v4, v10, v7
	v_cvt_pk_bf16_f32 v5, v8, v5
	global_store_dwordx4 v[18:19], v[2:5], off offset:256 nt
	s_cbranch_vccz .LBB0_70
	s_waitcnt vmcnt(0)
	s_cmpk_gt_u32 s52, 0xff
	s_cbranch_scc1 .LBB0_77
	s_barrier

; #define PG8_STAGE(bufoff, gbase, voff) do { _Pragma("unroll") for (int _i = 0; _i < 2; ++_i) \
;         __builtin_amdgcn_global_load_lds((const unsigned*)((const char*)(gbase) + (voff)[_i]), (LAS unsigned*)(lds + (bufoff) + ldsw + _i * 8192), 16, 0, 0); } while (0)
; #define PG8_LDA(dst, b, h) do { _Pragma("unroll") for (int m = 0; m < 4; ++m) _Pragma("unroll") for (int k = 0; k < 2; ++k) dst[m][k] = *(const LAS bf16x8*)(lds + PG8_SA(b, h) + aoff + m * 2048 + k * 1024); } while (0)
; #define PG8_LDB(dst, b, h) do { _Pragma("unroll") for (int n = 0; n < 2; ++n) _Pragma("unroll") for (int k = 0; k < 2; ++k) dst[n][k] = *(const LAS bf16x8*)(lds + PG8_SB(b, h) + boff + n * 2048 + k * 1024); } while (0)
; #define PG8_MMA(ai, bj, At, Bt) do { __builtin_amdgcn_s_setprio(1); _Pragma("unroll") for (int m = 0; m < 4; ++m) _Pragma("unroll") for (int n = 0; n < 2; ++n) _Pragma("unroll") for (int k = 0; k < 2; ++k) \
;         acc[ai][bj][m][n] = __builtin_amdgcn_mfma_f32_16x16x32_bf16(Bt[n][k], At[m][k], acc[ai][bj][m][n], 0, 0, 0); __builtin_amdgcn_s_setprio(0); } while (0)
; #define PG8_WAIT_L(n) asm volatile("s_waitcnt lgkmcnt(" #n ")" ::: "memory")
; #define PG8_BAR __builtin_amdgcn_s_barrier()
; #define PG8_SCHED __builtin_amdgcn_sched_barrier(0)
; template <class Epi, class Sched>
; __device__ __forceinline__ void gemm_phase(LAS unsigned char* lds, const Gemm g, const Sched& S, const Epi& E) {
;     ...
;             const bool last = (t == nt - 2);
;             const char* a1 = cA + (size_t)(t + 1) * kstep;
;             const char* a2 = last ? nA : cA + (size_t)(t + 2) * kstep; const char* b2 = last ? nB : cB + (size_t)(t + 2) * kstep;
;             const char* a3 = a2 + kstep; const char* b3 = b2 + kstep;
;             PG8_LDB(B0, 0, 0); PG8_SCHED; PG8_LDA(At, 0, 0); PG8_STAGE(PG8_SA(1, 1), a1 + hstep, voffA);
;             PG8_WAIT_L(8); PG8_BAR; PG8_WAIT_L(0); PG8_MMA(0, 0, At, B0); PG8_BAR; PG8_SCHED;
;             PG8_LDB(B1, 0, 1); PG8_STAGE(PG8_SB(0, 0), b2, voffB);
;             PG8_BAR; PG8_WAIT_L(0); PG8_MMA(0, 1, At, B1); PG8_BAR;
;             PG8_LDA(At, 0, 1); PG8_STAGE(PG8_SA(0, 0), a2, voffA);
;             PG8_BAR; PG8_WAIT_L(0); PG8_MMA(1, 0, At, B0); PG8_BAR; PG8_SCHED;
.LBB0_99:
	s_add_u32 s56, s28, 0x100
	s_addc_u32 s57, s29, 0
	s_cmp_eq_u32 s81, 28
	s_cselect_b32 s61, s51, s57
	s_cselect_b32 s60, s77, s56
	s_cselect_b32 s59, s49, s80
	s_cselect_b32 s58, s78, s79
	v_lshl_add_u64 v[156:157], s[28:29], 0, v[150:151]
	s_add_i32 m0, s9, 0xc000
	s_nop 0
	global_load_lds_dwordx4 v[156:157], off
	v_lshl_add_u64 v[156:157], s[28:29], 0, v[148:149]
	s_add_i32 m0, s9, 0xe000
	s_nop 0
	global_load_lds_dwordx4 v[156:157], off
	s_add_i32 s38, 0, 0x10000
	v_add_u32_e32 v110, s38, v169
	ds_read_b128 v[98:101], v110
	ds_read_b128 v[102:105], v110 offset:1024
	ds_read_b128 v[106:109], v110 offset:2048
	ds_read_b128 v[110:113], v110 offset:3072
	ds_read_b128 v[152:155], v171
	ds_read_b128 v[160:163], v171 offset:1024
	ds_read_b128 v[164:167], v171 offset:2048
	ds_read_b128 v[172:175], v171 offset:3072
	ds_read_b128 v[176:179], v171 offset:4096
	ds_read_b128 v[180:183], v171 offset:5120
	ds_read_b128 v[184:187], v171 offset:6144
	ds_read_b128 v[188:191], v171 offset:7168
	s_add_i32 s39, 0, 0x14000
	v_add_u32_e32 v156, s39, v169
	ds_read_b128 v[192:195], v156
	ds_read_b128 v[196:199], v156 offset:1024
	ds_read_b128 v[200:203], v156 offset:2048
	ds_read_b128 v[204:207], v156 offset:3072
	s_waitcnt lgkmcnt(4)
	s_barrier
	s_waitcnt lgkmcnt(0)
	s_setprio 1
	v_mfma_f32_16x16x32_bf16 v[142:145], v[98:101], v[152:155], v[142:145]
	v_mfma_f32_16x16x32_bf16 v[138:141], v[106:109], v[152:155], v[138:141]
	v_mfma_f32_16x16x32_bf16 v[126:129], v[98:101], v[164:167], v[126:129]
	v_mfma_f32_16x16x32_bf16 v[122:125], v[106:109], v[164:167], v[122:125]
	v_mfma_f32_16x16x32_bf16 v[94:97], v[98:101], v[176:179], v[94:97]
	v_mfma_f32_16x16x32_bf16 v[90:93], v[106:109], v[176:179], v[90:93]
	v_mfma_f32_16x16x32_bf16 v[86:89], v[98:101], v[184:187], v[86:89]
	v_mfma_f32_16x16x32_bf16 v[82:85], v[106:109], v[184:187], v[82:85]
	v_mfma_f32_16x16x32_bf16 v[142:145], v[102:105], v[160:163], v[142:145]
	v_mfma_f32_16x16x32_bf16 v[138:141], v[110:113], v[160:163], v[138:141]
	v_mfma_f32_16x16x32_bf16 v[126:129], v[102:105], v[172:175], v[126:129]
	v_mfma_f32_16x16x32_bf16 v[122:125], v[110:113], v[172:175], v[122:125]
	v_mfma_f32_16x16x32_bf16 v[94:97], v[102:105], v[180:183], v[94:97]
	v_mfma_f32_16x16x32_bf16 v[90:93], v[110:113], v[180:183], v[90:93]
	v_mfma_f32_16x16x32_bf16 v[86:89], v[102:105], v[188:191], v[86:89]
	v_mfma_f32_16x16x32_bf16 v[82:85], v[110:113], v[188:191], v[82:85]
	v_mfma_f32_16x16x32_bf16 v[134:137], v[192:195], v[152:155], v[134:137]
	v_mfma_f32_16x16x32_bf16 v[130:133], v[200:203], v[152:155], v[130:133]
	v_mfma_f32_16x16x32_bf16 v[118:121], v[192:195], v[164:167], v[118:121]
	v_mfma_f32_16x16x32_bf16 v[114:117], v[200:203], v[164:167], v[114:117]
	v_mfma_f32_16x16x32_bf16 v[78:81], v[192:195], v[176:179], v[78:81]
	v_mfma_f32_16x16x32_bf16 v[74:77], v[200:203], v[176:179], v[74:77]
	v_mfma_f32_16x16x32_bf16 v[70:73], v[192:195], v[184:187], v[70:73]
	v_mfma_f32_16x16x32_bf16 v[66:69], v[200:203], v[184:187], v[66:69]
	v_mfma_f32_16x16x32_bf16 v[134:137], v[196:199], v[160:163], v[134:137]
	v_mfma_f32_16x16x32_bf16 v[130:133], v[204:207], v[160:163], v[130:133]
	v_mfma_f32_16x16x32_bf16 v[118:121], v[196:199], v[172:175], v[118:121]
	v_mfma_f32_16x16x32_bf16 v[114:117], v[204:207], v[172:175], v[114:117]
	v_mfma_f32_16x16x32_bf16 v[78:81], v[196:199], v[180:183], v[78:81]
	v_mfma_f32_16x16x32_bf16 v[74:77], v[204:207], v[180:183], v[74:77]
	v_mfma_f32_16x16x32_bf16 v[70:73], v[196:199], v[188:191], v[70:73]
	v_mfma_f32_16x16x32_bf16 v[66:69], v[204:207], v[188:191], v[66:69]
	s_setprio 0
	s_barrier
	s_add_i32 s28, s38, s67
	v_lshl_add_u64 v[156:157], s[58:59], 0, v[0:1]
	s_mov_b32 m0, s28
	v_lshl_add_u64 v[210:211], s[58:59], 0, v[146:147]
	global_load_lds_dwordx4 v[156:157], off
	s_add_i32 m0, s28, 0x2000
	s_nop 0
	global_load_lds_dwordx4 v[210:211], off
	s_mov_b32 m0, s9
	v_lshl_add_u64 v[212:213], s[60:61], 0, v[0:1]
	global_load_lds_dwordx4 v[212:213], off
	v_lshl_add_u64 v[214:215], s[60:61], 0, v[146:147]
	s_mov_b32 m0, s68
	s_nop 0
	global_load_lds_dwordx4 v[214:215], off
	ds_read_b128 v[152:155], v171 offset:16384
	ds_read_b128 v[160:163], v171 offset:17408
	ds_read_b128 v[164:167], v171 offset:18432
	ds_read_b128 v[172:175], v171 offset:19456
	ds_read_b128 v[176:179], v171 offset:20480
	ds_read_b128 v[180:183], v171 offset:21504
	ds_read_b128 v[184:187], v171 offset:22528
	ds_read_b128 v[188:191], v171 offset:23552
	s_waitcnt vmcnt(4)
	s_waitcnt lgkmcnt(0)
	s_barrier
	s_setprio 1
	v_mfma_f32_16x16x32_bf16 v[62:65], v[98:101], v[152:155], v[62:65]
	v_mfma_f32_16x16x32_bf16 v[58:61], v[106:109], v[152:155], v[58:61]
	v_mfma_f32_16x16x32_bf16 v[46:49], v[98:101], v[164:167], v[46:49]
	v_mfma_f32_16x16x32_bf16 v[42:45], v[106:109], v[164:167], v[42:45]
	v_mfma_f32_16x16x32_bf16 v[30:33], v[98:101], v[176:179], v[30:33]
	v_mfma_f32_16x16x32_bf16 v[26:29], v[106:109], v[176:179], v[26:29]
	v_mfma_f32_16x16x32_bf16 v[22:25], v[98:101], v[184:187], v[22:25]
	v_mfma_f32_16x16x32_bf16 v[18:21], v[106:109], v[184:187], v[18:21]
	v_mfma_f32_16x16x32_bf16 v[62:65], v[102:105], v[160:163], v[62:65]
	v_mfma_f32_16x16x32_bf16 v[58:61], v[110:113], v[160:163], v[58:61]
	v_mfma_f32_16x16x32_bf16 v[46:49], v[102:105], v[172:175], v[46:49]
	v_mfma_f32_16x16x32_bf16 v[42:45], v[110:113], v[172:175], v[42:45]
	v_mfma_f32_16x16x32_bf16 v[30:33], v[102:105], v[180:183], v[30:33]
	v_mfma_f32_16x16x32_bf16 v[26:29], v[110:113], v[180:183], v[26:29]
	v_mfma_f32_16x16x32_bf16 v[22:25], v[102:105], v[188:191], v[22:25]
	v_mfma_f32_16x16x32_bf16 v[18:21], v[110:113], v[188:191], v[18:21]
	v_mfma_f32_16x16x32_bf16 v[54:57], v[192:195], v[152:155], v[54:57]
	v_mfma_f32_16x16x32_bf16 v[50:53], v[200:203], v[152:155], v[50:53]
	v_mfma_f32_16x16x32_bf16 v[38:41], v[192:195], v[164:167], v[38:41]
	v_mfma_f32_16x16x32_bf16 v[34:37], v[200:203], v[164:167], v[34:37]
	v_mfma_f32_16x16x32_bf16 v[14:17], v[192:195], v[176:179], v[14:17]
	v_mfma_f32_16x16x32_bf16 v[10:13], v[200:203], v[176:179], v[10:13]
	v_mfma_f32_16x16x32_bf16 v[6:9], v[192:195], v[184:187], v[6:9]
	v_mfma_f32_16x16x32_bf16 v[2:5], v[200:203], v[184:187], v[2:5]
	v_mfma_f32_16x16x32_bf16 v[54:57], v[196:199], v[160:163], v[54:57]
	v_mfma_f32_16x16x32_bf16 v[50:53], v[204:207], v[160:163], v[50:53]
	v_mfma_f32_16x16x32_bf16 v[38:41], v[196:199], v[172:175], v[38:41]
	v_mfma_f32_16x16x32_bf16 v[34:37], v[204:207], v[172:175], v[34:37]
	v_mfma_f32_16x16x32_bf16 v[14:17], v[196:199], v[180:183], v[14:17]
	v_mfma_f32_16x16x32_bf16 v[10:13], v[204:207], v[180:183], v[10:13]
	v_mfma_f32_16x16x32_bf16 v[6:9], v[196:199], v[188:191], v[6:9]
	v_mfma_f32_16x16x32_bf16 v[2:5], v[204:207], v[188:191], v[2:5]
	s_setprio 0
	s_barrier
; #define PG8_STAGE(bufoff, gbase, voff) do { _Pragma("unroll") for (int _i = 0; _i < 2; ++_i) \
;         __builtin_amdgcn_global_load_lds((const unsigned*)((const char*)(gbase) + (voff)[_i]), (LAS unsigned*)(lds + (bufoff) + ldsw + _i * 8192), 16, 0, 0); } while (0)
; #define PG8_LDA(dst, b, h) do { _Pragma("unroll") for (int m = 0; m < 4; ++m) _Pragma("unroll") for (int k = 0; k < 2; ++k) dst[m][k] = *(const LAS bf16x8*)(lds + PG8_SA(b, h) + aoff + m * 2048 + k * 1024); } while (0)
; #define PG8_LDB(dst, b, h) do { _Pragma("unroll") for (int n = 0; n < 2; ++n) _Pragma("unroll") for (int k = 0; k < 2; ++k) dst[n][k] = *(const LAS bf16x8*)(lds + PG8_SB(b, h) + boff + n * 2048 + k * 1024); } while (0)
; #define PG8_MMA(ai, bj, At, Bt) do { __builtin_amdgcn_s_setprio(1); _Pragma("unroll") for (int m = 0; m < 4; ++m) _Pragma("unroll") for (int n = 0; n < 2; ++n) _Pragma("unroll") for (int k = 0; k < 2; ++k) \
;         acc[ai][bj][m][n] = __builtin_amdgcn_mfma_f32_16x16x32_bf16(Bt[n][k], At[m][k], acc[ai][bj][m][n], 0, 0, 0); __builtin_amdgcn_s_setprio(0); } while (0)
; #define PG8_WAIT_V(n) asm volatile("s_waitcnt vmcnt(" #n ")" ::: "memory")
; #define PG8_WAIT_L(n) asm volatile("s_waitcnt lgkmcnt(" #n ")" ::: "memory")
; #define PG8_BAR __builtin_amdgcn_s_barrier()
; #define PG8_SCHED __builtin_amdgcn_sched_barrier(0)
; template <class Epi, class Sched>
; __device__ __forceinline__ void gemm_phase(LAS unsigned char* lds, const Gemm g, const Sched& S, const Epi& E) {
;     ...
;             PG8_STAGE(PG8_SB(0, 1), b2 + hstep, voffB);
;             PG8_WAIT_V(6); PG8_BAR; PG8_MMA(1, 1, At, B1); PG8_BAR;
;             PG8_LDB(B0, 1, 0); PG8_SCHED; PG8_LDA(At, 1, 0); PG8_STAGE(PG8_SA(0, 1), a2 + hstep, voffA);
;             PG8_WAIT_L(8); PG8_BAR; PG8_WAIT_L(0); PG8_MMA(0, 0, At, B0); PG8_BAR; PG8_SCHED;
	s_add_u32 s28, s58, 0x80000
	s_addc_u32 s29, s59, 0
	s_add_i32 s38, s39, s67
	v_lshl_add_u64 v[98:99], s[28:29], 0, v[0:1]
	s_mov_b32 m0, s38
	s_nop 0
	global_load_lds_dwordx4 v[98:99], off
	v_lshl_add_u64 v[98:99], s[28:29], 0, v[146:147]
	s_add_i32 m0, s38, 0x2000
	s_nop 0
	global_load_lds_dwordx4 v[98:99], off
	s_add_u32 s28, s60, 0x80000
	s_addc_u32 s29, s61, 0
	s_mov_b32 m0, s69
	v_lshl_add_u64 v[192:193], s[28:29], 0, v[0:1]
	global_load_lds_dwordx4 v[192:193], off
	v_lshl_add_u64 v[192:193], s[28:29], 0, v[146:147]
	s_mov_b32 m0, s70
	s_nop 0
	global_load_lds_dwordx4 v[192:193], off
	s_add_i32 s38, 0, 0x18000
	v_add_u32_e32 v110, s38, v169
	ds_read_b128 v[98:101], v110
	ds_read_b128 v[102:105], v110 offset:1024
	ds_read_b128 v[106:109], v110 offset:2048
	ds_read_b128 v[110:113], v110 offset:3072
	ds_read_b128 v[152:155], v171 offset:32768
	ds_read_b128 v[160:163], v171 offset:33792
	ds_read_b128 v[164:167], v171 offset:34816
	ds_read_b128 v[172:175], v171 offset:35840
	ds_read_b128 v[176:179], v171 offset:36864
	ds_read_b128 v[180:183], v171 offset:37888
	ds_read_b128 v[184:187], v171 offset:38912
	ds_read_b128 v[188:191], v171 offset:39936
	s_add_i32 s39, 0, 0x1c000
	v_add_u32_e32 v204, s39, v169
	ds_read_b128 v[192:195], v204
	ds_read_b128 v[196:199], v204 offset:1024
	ds_read_b128 v[200:203], v204 offset:2048
	ds_read_b128 v[204:207], v204 offset:3072
	s_waitcnt lgkmcnt(4)
	s_barrier
	s_waitcnt lgkmcnt(0)
	s_setprio 1
	v_mfma_f32_16x16x32_bf16 v[142:145], v[98:101], v[152:155], v[142:145]
	v_mfma_f32_16x16x32_bf16 v[138:141], v[106:109], v[152:155], v[138:141]
	v_mfma_f32_16x16x32_bf16 v[126:129], v[98:101], v[164:167], v[126:129]
	v_mfma_f32_16x16x32_bf16 v[122:125], v[106:109], v[164:167], v[122:125]
	v_mfma_f32_16x16x32_bf16 v[94:97], v[98:101], v[176:179], v[94:97]
	v_mfma_f32_16x16x32_bf16 v[90:93], v[106:109], v[176:179], v[90:93]
	v_mfma_f32_16x16x32_bf16 v[86:89], v[98:101], v[184:187], v[86:89]
	v_mfma_f32_16x16x32_bf16 v[82:85], v[106:109], v[184:187], v[82:85]
	v_mfma_f32_16x16x32_bf16 v[142:145], v[102:105], v[160:163], v[142:145]
	v_mfma_f32_16x16x32_bf16 v[138:141], v[110:113], v[160:163], v[138:141]
	v_mfma_f32_16x16x32_bf16 v[126:129], v[102:105], v[172:175], v[126:129]
	v_mfma_f32_16x16x32_bf16 v[122:125], v[110:113], v[172:175], v[122:125]
	v_mfma_f32_16x16x32_bf16 v[94:97], v[102:105], v[180:183], v[94:97]
	v_mfma_f32_16x16x32_bf16 v[90:93], v[110:113], v[180:183], v[90:93]
	v_mfma_f32_16x16x32_bf16 v[86:89], v[102:105], v[188:191], v[86:89]
	v_mfma_f32_16x16x32_bf16 v[82:85], v[110:113], v[188:191], v[82:85]
	v_mfma_f32_16x16x32_bf16 v[134:137], v[192:195], v[152:155], v[134:137]
	v_mfma_f32_16x16x32_bf16 v[130:133], v[200:203], v[152:155], v[130:133]
	v_mfma_f32_16x16x32_bf16 v[118:121], v[192:195], v[164:167], v[118:121]
	v_mfma_f32_16x16x32_bf16 v[114:117], v[200:203], v[164:167], v[114:117]
	v_mfma_f32_16x16x32_bf16 v[78:81], v[192:195], v[176:179], v[78:81]
	v_mfma_f32_16x16x32_bf16 v[74:77], v[200:203], v[176:179], v[74:77]
	v_mfma_f32_16x16x32_bf16 v[70:73], v[192:195], v[184:187], v[70:73]
	v_mfma_f32_16x16x32_bf16 v[66:69], v[200:203], v[184:187], v[66:69]
	v_mfma_f32_16x16x32_bf16 v[134:137], v[196:199], v[160:163], v[134:137]
	v_mfma_f32_16x16x32_bf16 v[130:133], v[204:207], v[160:163], v[130:133]
	v_mfma_f32_16x16x32_bf16 v[118:121], v[196:199], v[172:175], v[118:121]
	v_mfma_f32_16x16x32_bf16 v[114:117], v[204:207], v[172:175], v[114:117]
	v_mfma_f32_16x16x32_bf16 v[78:81], v[196:199], v[180:183], v[78:81]
	v_mfma_f32_16x16x32_bf16 v[74:77], v[204:207], v[180:183], v[74:77]
	v_mfma_f32_16x16x32_bf16 v[70:73], v[196:199], v[188:191], v[70:73]
	v_mfma_f32_16x16x32_bf16 v[66:69], v[204:207], v[188:191], v[66:69]
	s_setprio 0
	s_barrier
; #define PG8_STAGE(bufoff, gbase, voff) do { _Pragma("unroll") for (int _i = 0; _i < 2; ++_i) \
;         __builtin_amdgcn_global_load_lds((const unsigned*)((const char*)(gbase) + (voff)[_i]), (LAS unsigned*)(lds + (bufoff) + ldsw + _i * 8192), 16, 0, 0); } while (0)
; #define PG8_LDA(dst, b, h) do { _Pragma("unroll") for (int m = 0; m < 4; ++m) _Pragma("unroll") for (int k = 0; k < 2; ++k) dst[m][k] = *(const LAS bf16x8*)(lds + PG8_SA(b, h) + aoff + m * 2048 + k * 1024); } while (0)
; #define PG8_LDB(dst, b, h) do { _Pragma("unroll") for (int n = 0; n < 2; ++n) _Pragma("unroll") for (int k = 0; k < 2; ++k) dst[n][k] = *(const LAS bf16x8*)(lds + PG8_SB(b, h) + boff + n * 2048 + k * 1024); } while (0)
; #define PG8_MMA(ai, bj, At, Bt) do { __builtin_amdgcn_s_setprio(1); _Pragma("unroll") for (int m = 0; m < 4; ++m) _Pragma("unroll") for (int n = 0; n < 2; ++n) _Pragma("unroll") for (int k = 0; k < 2; ++k) \
;         acc[ai][bj][m][n] = __builtin_amdgcn_mfma_f32_16x16x32_bf16(Bt[n][k], At[m][k], acc[ai][bj][m][n], 0, 0, 0); __builtin_amdgcn_s_setprio(0); } while (0)
; #define PG8_WAIT_V(n) asm volatile("s_waitcnt vmcnt(" #n ")" ::: "memory")
; #define PG8_WAIT_L(n) asm volatile("s_waitcnt lgkmcnt(" #n ")" ::: "memory")
; #define PG8_BAR __builtin_amdgcn_s_barrier()
; #define PG8_SCHED __builtin_amdgcn_sched_barrier(0)
; template <class Epi, class Sched>
; __device__ __forceinline__ void gemm_phase(LAS unsigned char* lds, const Gemm g, const Sched& S, const Epi& E) {
;     ...
;             PG8_LDB(B1, 1, 1); PG8_STAGE(PG8_SB(1, 0), b3, voffB);
;             PG8_BAR; PG8_WAIT_L(0); PG8_MMA(0, 1, At, B1); PG8_BAR;
;             PG8_LDA(At, 1, 1); PG8_STAGE(PG8_SA(1, 0), a3, voffA);
;             PG8_BAR; PG8_WAIT_L(0); PG8_MMA(1, 0, At, B0); PG8_BAR; PG8_SCHED;
;             PG8_STAGE(PG8_SB(1, 1), b3 + hstep, voffB);
;             PG8_WAIT_V(6); PG8_BAR; PG8_MMA(1, 1, At, B1); PG8_BAR;
	s_add_i32 s28, s38, s67
	v_lshl_add_u64 v[156:157], v[156:157], 0, s[36:37]
	s_mov_b32 m0, s28
	s_nop 0
	global_load_lds_dwordx4 v[156:157], off
	v_lshl_add_u64 v[156:157], v[210:211], 0, s[36:37]
	s_add_i32 m0, s28, 0x2000
	s_nop 0
	global_load_lds_dwordx4 v[156:157], off
	s_mov_b32 m0, s72
	v_lshl_add_u64 v[156:157], v[212:213], 0, s[36:37]
	global_load_lds_dwordx4 v[156:157], off
	v_lshl_add_u64 v[156:157], v[214:215], 0, s[36:37]
	s_mov_b32 m0, s73
	s_nop 0
	global_load_lds_dwordx4 v[156:157], off
	ds_read_b128 v[152:155], v171 offset:49152
	ds_read_b128 v[160:163], v171 offset:50176
	ds_read_b128 v[164:167], v171 offset:51200
	ds_read_b128 v[172:175], v171 offset:52224
	ds_read_b128 v[176:179], v171 offset:53248
	ds_read_b128 v[180:183], v171 offset:54272
	ds_read_b128 v[184:187], v171 offset:55296
	ds_read_b128 v[188:191], v171 offset:56320
	s_waitcnt vmcnt(4)
	s_waitcnt lgkmcnt(0)
	s_barrier
	s_setprio 1
	v_mfma_f32_16x16x32_bf16 v[62:65], v[98:101], v[152:155], v[62:65]
	v_mfma_f32_16x16x32_bf16 v[58:61], v[106:109], v[152:155], v[58:61]
	v_mfma_f32_16x16x32_bf16 v[46:49], v[98:101], v[164:167], v[46:49]
	v_mfma_f32_16x16x32_bf16 v[42:45], v[106:109], v[164:167], v[42:45]
	v_mfma_f32_16x16x32_bf16 v[30:33], v[98:101], v[176:179], v[30:33]
	v_mfma_f32_16x16x32_bf16 v[26:29], v[106:109], v[176:179], v[26:29]
	v_mfma_f32_16x16x32_bf16 v[22:25], v[98:101], v[184:187], v[22:25]
	v_mfma_f32_16x16x32_bf16 v[18:21], v[106:109], v[184:187], v[18:21]
	v_mfma_f32_16x16x32_bf16 v[62:65], v[102:105], v[160:163], v[62:65]
	v_mfma_f32_16x16x32_bf16 v[58:61], v[110:113], v[160:163], v[58:61]
	v_mfma_f32_16x16x32_bf16 v[46:49], v[102:105], v[172:175], v[46:49]
	v_mfma_f32_16x16x32_bf16 v[42:45], v[110:113], v[172:175], v[42:45]
	v_mfma_f32_16x16x32_bf16 v[30:33], v[102:105], v[180:183], v[30:33]
	v_mfma_f32_16x16x32_bf16 v[26:29], v[110:113], v[180:183], v[26:29]
	v_mfma_f32_16x16x32_bf16 v[22:25], v[102:105], v[188:191], v[22:25]
	v_mfma_f32_16x16x32_bf16 v[18:21], v[110:113], v[188:191], v[18:21]
	s_add_u32 s28, s58, 0x80080
	s_addc_u32 s29, s59, 0
	s_add_i32 s38, s39, s67
	v_lshl_add_u64 v[98:99], s[28:29], 0, v[0:1]
	s_mov_b32 m0, s38
	s_nop 0
	global_load_lds_dwordx4 v[98:99], off
	v_lshl_add_u64 v[98:99], s[28:29], 0, v[146:147]
	s_add_i32 m0, s38, 0x2000
	s_nop 0
	global_load_lds_dwordx4 v[98:99], off
	v_mfma_f32_16x16x32_bf16 v[54:57], v[192:195], v[152:155], v[54:57]
	v_mfma_f32_16x16x32_bf16 v[50:53], v[200:203], v[152:155], v[50:53]
	v_mfma_f32_16x16x32_bf16 v[38:41], v[192:195], v[164:167], v[38:41]
	v_mfma_f32_16x16x32_bf16 v[34:37], v[200:203], v[164:167], v[34:37]
	v_mfma_f32_16x16x32_bf16 v[14:17], v[192:195], v[176:179], v[14:17]
	v_mfma_f32_16x16x32_bf16 v[10:13], v[200:203], v[176:179], v[10:13]
	v_mfma_f32_16x16x32_bf16 v[6:9], v[192:195], v[184:187], v[6:9]
	v_mfma_f32_16x16x32_bf16 v[2:5], v[200:203], v[184:187], v[2:5]
	v_mfma_f32_16x16x32_bf16 v[54:57], v[196:199], v[160:163], v[54:57]
	v_mfma_f32_16x16x32_bf16 v[50:53], v[204:207], v[160:163], v[50:53]
	v_mfma_f32_16x16x32_bf16 v[38:41], v[196:199], v[172:175], v[38:41]
	v_mfma_f32_16x16x32_bf16 v[34:37], v[204:207], v[172:175], v[34:37]
	v_mfma_f32_16x16x32_bf16 v[14:17], v[196:199], v[180:183], v[14:17]
	v_mfma_f32_16x16x32_bf16 v[10:13], v[204:207], v[180:183], v[10:13]
	v_mfma_f32_16x16x32_bf16 v[6:9], v[196:199], v[188:191], v[6:9]
	v_mfma_f32_16x16x32_bf16 v[2:5], v[204:207], v[188:191], v[2:5]
	s_setprio 0
	s_add_i32 s81, s81, 2
	s_add_u32 s79, s79, 0x100
	s_addc_u32 s80, s80, 0
	s_cmp_gt_u32 s81, 29
	s_mov_b64 s[28:29], s[56:57]
	s_barrier
	s_cbranch_scc0 .LBB0_99
	s_cmp_lt_i32 s8, 64
	s_cselect_b64 s[58:59], -1, 0
	s_cmp_gt_i32 s8, 63
	s_cbranch_scc0 .LBB0_90
	s_mov_b64 s[60:61], 0x18000
	s_mov_b64 s[28:29], s[46:47]
	s_mov_b64 s[56:57], s[24:25]
	s_branch .LBB0_91

; #define PG8_STAGE(bufoff, gbase, voff) do { _Pragma("unroll") for (int _i = 0; _i < 2; ++_i) \
;         __builtin_amdgcn_global_load_lds((const unsigned*)((const char*)(gbase) + (voff)[_i]), (LAS unsigned*)(lds + (bufoff) + ldsw + _i * 8192), 16, 0, 0); } while (0)
; #define PG8_LDA(dst, b, h) do { _Pragma("unroll") for (int m = 0; m < 4; ++m) _Pragma("unroll") for (int k = 0; k < 2; ++k) dst[m][k] = *(const LAS bf16x8*)(lds + PG8_SA(b, h) + aoff + m * 2048 + k * 1024); } while (0)
; #define PG8_LDB(dst, b, h) do { _Pragma("unroll") for (int n = 0; n < 2; ++n) _Pragma("unroll") for (int k = 0; k < 2; ++k) dst[n][k] = *(const LAS bf16x8*)(lds + PG8_SB(b, h) + boff + n * 2048 + k * 1024); } while (0)
; #define PG8_MMA(ai, bj, At, Bt) do { __builtin_amdgcn_s_setprio(1); _Pragma("unroll") for (int m = 0; m < 4; ++m) _Pragma("unroll") for (int n = 0; n < 2; ++n) _Pragma("unroll") for (int k = 0; k < 2; ++k) \
;         acc[ai][bj][m][n] = __builtin_amdgcn_mfma_f32_16x16x32_bf16(Bt[n][k], At[m][k], acc[ai][bj][m][n], 0, 0, 0); __builtin_amdgcn_s_setprio(0); } while (0)
; #define PG8_WAIT_L(n) asm volatile("s_waitcnt lgkmcnt(" #n ")" ::: "memory")
; #define PG8_BAR __builtin_amdgcn_s_barrier()
; #define PG8_SCHED __builtin_amdgcn_sched_barrier(0)
; template <class Epi, class Sched>
; __device__ __forceinline__ void gemm_phase(LAS unsigned char* lds, const Gemm g, const Sched& S, const Epi& E) {
;     ...
;             const bool last = (t == nt - 2);
;             const char* a1 = cA + (size_t)(t + 1) * kstep;
;             const char* a2 = last ? nA : cA + (size_t)(t + 2) * kstep; const char* b2 = last ? nB : cB + (size_t)(t + 2) * kstep;
;             const char* a3 = a2 + kstep; const char* b3 = b2 + kstep;
;             PG8_LDB(B0, 0, 0); PG8_SCHED; PG8_LDA(At, 0, 0); PG8_STAGE(PG8_SA(1, 1), a1 + hstep, voffA);
;             PG8_WAIT_L(8); PG8_BAR; PG8_WAIT_L(0); PG8_MMA(0, 0, At, B0); PG8_BAR; PG8_SCHED;
;             PG8_LDB(B1, 0, 1); PG8_STAGE(PG8_SB(0, 0), b2, voffB);
;             PG8_BAR; PG8_WAIT_L(0); PG8_MMA(0, 1, At, B1); PG8_BAR;
;             PG8_LDA(At, 0, 1); PG8_STAGE(PG8_SA(0, 0), a2, voffA);
;             PG8_BAR; PG8_WAIT_L(0); PG8_MMA(1, 0, At, B0); PG8_BAR; PG8_SCHED;
.LBB0_113:
	s_add_u32 s54, s52, 0x100
	s_addc_u32 s55, s53, 0
	s_cmp_eq_u32 s73, 4
	s_cselect_b32 s59, s11, s55
	s_cselect_b32 s58, s29, s54
	s_cselect_b32 s57, s41, s72
	s_cselect_b32 s56, s45, s71
	v_lshl_add_u64 v[156:157], s[52:53], 0, v[134:135]
	s_add_i32 m0, s25, 0xc000
	s_nop 0
	global_load_lds_dwordx4 v[156:157], off
	v_lshl_add_u64 v[156:157], s[52:53], 0, v[132:133]
	s_add_i32 m0, s25, 0xe000
	s_nop 0
	global_load_lds_dwordx4 v[156:157], off
	s_add_i32 s38, 0, 0x10000
	v_add_u32_e32 v152, s38, v137
	ds_read_b128 v[140:143], v152
	ds_read_b128 v[144:147], v152 offset:1024
	ds_read_b128 v[148:151], v152 offset:2048
	ds_read_b128 v[152:155], v152 offset:3072
	ds_read_b128 v[160:163], v139
	ds_read_b128 v[164:167], v139 offset:1024
	ds_read_b128 v[168:171], v139 offset:2048
	ds_read_b128 v[172:175], v139 offset:3072
	ds_read_b128 v[176:179], v139 offset:4096
	ds_read_b128 v[180:183], v139 offset:5120
	ds_read_b128 v[184:187], v139 offset:6144
	ds_read_b128 v[188:191], v139 offset:7168
	s_add_i32 s52, 0, 0x14000
	v_add_u32_e32 v156, s52, v137
	ds_read_b128 v[192:195], v156
	ds_read_b128 v[196:199], v156 offset:1024
	ds_read_b128 v[200:203], v156 offset:2048
	ds_read_b128 v[204:207], v156 offset:3072
	s_waitcnt lgkmcnt(4)
	s_barrier
	s_waitcnt lgkmcnt(0)
	s_setprio 1
	v_mfma_f32_16x16x32_bf16 v[126:129], v[140:143], v[160:163], v[126:129]
	v_mfma_f32_16x16x32_bf16 v[122:125], v[148:151], v[160:163], v[122:125]
	v_mfma_f32_16x16x32_bf16 v[118:121], v[140:143], v[168:171], v[118:121]
	v_mfma_f32_16x16x32_bf16 v[114:117], v[148:151], v[168:171], v[114:117]
	v_mfma_f32_16x16x32_bf16 v[106:109], v[140:143], v[176:179], v[106:109]
	v_mfma_f32_16x16x32_bf16 v[98:101], v[148:151], v[176:179], v[98:101]
	v_mfma_f32_16x16x32_bf16 v[90:93], v[140:143], v[184:187], v[90:93]
	v_mfma_f32_16x16x32_bf16 v[82:85], v[148:151], v[184:187], v[82:85]
	v_mfma_f32_16x16x32_bf16 v[126:129], v[144:147], v[164:167], v[126:129]
	v_mfma_f32_16x16x32_bf16 v[122:125], v[152:155], v[164:167], v[122:125]
	v_mfma_f32_16x16x32_bf16 v[118:121], v[144:147], v[172:175], v[118:121]
	v_mfma_f32_16x16x32_bf16 v[114:117], v[152:155], v[172:175], v[114:117]
	v_mfma_f32_16x16x32_bf16 v[106:109], v[144:147], v[180:183], v[106:109]
	v_mfma_f32_16x16x32_bf16 v[98:101], v[152:155], v[180:183], v[98:101]
	v_mfma_f32_16x16x32_bf16 v[90:93], v[144:147], v[188:191], v[90:93]
	v_mfma_f32_16x16x32_bf16 v[82:85], v[152:155], v[188:191], v[82:85]
	v_mfma_f32_16x16x32_bf16 v[110:113], v[192:195], v[160:163], v[110:113]
	v_mfma_f32_16x16x32_bf16 v[102:105], v[200:203], v[160:163], v[102:105]
	v_mfma_f32_16x16x32_bf16 v[94:97], v[192:195], v[168:171], v[94:97]
	v_mfma_f32_16x16x32_bf16 v[86:89], v[200:203], v[168:171], v[86:89]
	v_mfma_f32_16x16x32_bf16 v[78:81], v[192:195], v[176:179], v[78:81]
	v_mfma_f32_16x16x32_bf16 v[74:77], v[200:203], v[176:179], v[74:77]
	v_mfma_f32_16x16x32_bf16 v[70:73], v[192:195], v[184:187], v[70:73]
	v_mfma_f32_16x16x32_bf16 v[66:69], v[200:203], v[184:187], v[66:69]
	v_mfma_f32_16x16x32_bf16 v[110:113], v[196:199], v[164:167], v[110:113]
	v_mfma_f32_16x16x32_bf16 v[102:105], v[204:207], v[164:167], v[102:105]
	v_mfma_f32_16x16x32_bf16 v[94:97], v[196:199], v[172:175], v[94:97]
	v_mfma_f32_16x16x32_bf16 v[86:89], v[204:207], v[172:175], v[86:89]
	v_mfma_f32_16x16x32_bf16 v[78:81], v[196:199], v[180:183], v[78:81]
	v_mfma_f32_16x16x32_bf16 v[74:77], v[204:207], v[180:183], v[74:77]
	v_mfma_f32_16x16x32_bf16 v[70:73], v[196:199], v[188:191], v[70:73]
	v_mfma_f32_16x16x32_bf16 v[66:69], v[204:207], v[188:191], v[66:69]
	s_setprio 0
	s_barrier
	s_add_i32 s38, s38, s65
	v_lshl_add_u64 v[156:157], s[56:57], 0, v[0:1]
	s_mov_b32 m0, s38
	v_lshl_add_u64 v[210:211], s[56:57], 0, v[130:131]
	global_load_lds_dwordx4 v[156:157], off
	s_add_i32 m0, s38, 0x2000
	s_nop 0
	global_load_lds_dwordx4 v[210:211], off
	s_mov_b32 m0, s25
	v_lshl_add_u64 v[212:213], s[58:59], 0, v[0:1]
	global_load_lds_dwordx4 v[212:213], off
	v_lshl_add_u64 v[214:215], s[58:59], 0, v[130:131]
	s_mov_b32 m0, s27
	s_nop 0
	global_load_lds_dwordx4 v[214:215], off
	ds_read_b128 v[160:163], v139 offset:16384
	ds_read_b128 v[164:167], v139 offset:17408
	ds_read_b128 v[168:171], v139 offset:18432
	ds_read_b128 v[172:175], v139 offset:19456
	ds_read_b128 v[176:179], v139 offset:20480
	ds_read_b128 v[180:183], v139 offset:21504
	ds_read_b128 v[184:187], v139 offset:22528
	ds_read_b128 v[188:191], v139 offset:23552
	s_waitcnt vmcnt(4)
	s_waitcnt lgkmcnt(0)
	s_barrier
	s_setprio 1
	v_mfma_f32_16x16x32_bf16 v[62:65], v[140:143], v[160:163], v[62:65]
	v_mfma_f32_16x16x32_bf16 v[58:61], v[148:151], v[160:163], v[58:61]
	v_mfma_f32_16x16x32_bf16 v[54:57], v[140:143], v[168:171], v[54:57]
	v_mfma_f32_16x16x32_bf16 v[50:53], v[148:151], v[168:171], v[50:53]
	v_mfma_f32_16x16x32_bf16 v[38:41], v[140:143], v[176:179], v[38:41]
	v_mfma_f32_16x16x32_bf16 v[34:37], v[148:151], v[176:179], v[34:37]
	v_mfma_f32_16x16x32_bf16 v[22:25], v[140:143], v[184:187], v[22:25]
	v_mfma_f32_16x16x32_bf16 v[18:21], v[148:151], v[184:187], v[18:21]
	v_mfma_f32_16x16x32_bf16 v[62:65], v[144:147], v[164:167], v[62:65]
	v_mfma_f32_16x16x32_bf16 v[58:61], v[152:155], v[164:167], v[58:61]
	v_mfma_f32_16x16x32_bf16 v[54:57], v[144:147], v[172:175], v[54:57]
	v_mfma_f32_16x16x32_bf16 v[50:53], v[152:155], v[172:175], v[50:53]
	v_mfma_f32_16x16x32_bf16 v[38:41], v[144:147], v[180:183], v[38:41]
	v_mfma_f32_16x16x32_bf16 v[34:37], v[152:155], v[180:183], v[34:37]
	v_mfma_f32_16x16x32_bf16 v[22:25], v[144:147], v[188:191], v[22:25]
	v_mfma_f32_16x16x32_bf16 v[18:21], v[152:155], v[188:191], v[18:21]
	v_mfma_f32_16x16x32_bf16 v[46:49], v[192:195], v[160:163], v[46:49]
	v_mfma_f32_16x16x32_bf16 v[42:45], v[200:203], v[160:163], v[42:45]
	v_mfma_f32_16x16x32_bf16 v[30:33], v[192:195], v[168:171], v[30:33]
	v_mfma_f32_16x16x32_bf16 v[26:29], v[200:203], v[168:171], v[26:29]
	v_mfma_f32_16x16x32_bf16 v[14:17], v[192:195], v[176:179], v[14:17]
	v_mfma_f32_16x16x32_bf16 v[10:13], v[200:203], v[176:179], v[10:13]
	v_mfma_f32_16x16x32_bf16 v[6:9], v[192:195], v[184:187], v[6:9]
	v_mfma_f32_16x16x32_bf16 v[2:5], v[200:203], v[184:187], v[2:5]
	v_mfma_f32_16x16x32_bf16 v[46:49], v[196:199], v[164:167], v[46:49]
	v_mfma_f32_16x16x32_bf16 v[42:45], v[204:207], v[164:167], v[42:45]
	v_mfma_f32_16x16x32_bf16 v[30:33], v[196:199], v[172:175], v[30:33]
	v_mfma_f32_16x16x32_bf16 v[26:29], v[204:207], v[172:175], v[26:29]
	v_mfma_f32_16x16x32_bf16 v[14:17], v[196:199], v[180:183], v[14:17]
	v_mfma_f32_16x16x32_bf16 v[10:13], v[204:207], v[180:183], v[10:13]
	v_mfma_f32_16x16x32_bf16 v[6:9], v[196:199], v[188:191], v[6:9]
	v_mfma_f32_16x16x32_bf16 v[2:5], v[204:207], v[188:191], v[2:5]
	s_setprio 0
	s_barrier
; #define PG8_STAGE(bufoff, gbase, voff) do { _Pragma("unroll") for (int _i = 0; _i < 2; ++_i) \
;         __builtin_amdgcn_global_load_lds((const unsigned*)((const char*)(gbase) + (voff)[_i]), (LAS unsigned*)(lds + (bufoff) + ldsw + _i * 8192), 16, 0, 0); } while (0)
; #define PG8_LDA(dst, b, h) do { _Pragma("unroll") for (int m = 0; m < 4; ++m) _Pragma("unroll") for (int k = 0; k < 2; ++k) dst[m][k] = *(const LAS bf16x8*)(lds + PG8_SA(b, h) + aoff + m * 2048 + k * 1024); } while (0)
; #define PG8_LDB(dst, b, h) do { _Pragma("unroll") for (int n = 0; n < 2; ++n) _Pragma("unroll") for (int k = 0; k < 2; ++k) dst[n][k] = *(const LAS bf16x8*)(lds + PG8_SB(b, h) + boff + n * 2048 + k * 1024); } while (0)
; #define PG8_MMA(ai, bj, At, Bt) do { __builtin_amdgcn_s_setprio(1); _Pragma("unroll") for (int m = 0; m < 4; ++m) _Pragma("unroll") for (int n = 0; n < 2; ++n) _Pragma("unroll") for (int k = 0; k < 2; ++k) \
;         acc[ai][bj][m][n] = __builtin_amdgcn_mfma_f32_16x16x32_bf16(Bt[n][k], At[m][k], acc[ai][bj][m][n], 0, 0, 0); __builtin_amdgcn_s_setprio(0); } while (0)
; #define PG8_WAIT_V(n) asm volatile("s_waitcnt vmcnt(" #n ")" ::: "memory")
; #define PG8_WAIT_L(n) asm volatile("s_waitcnt lgkmcnt(" #n ")" ::: "memory")
; #define PG8_BAR __builtin_amdgcn_s_barrier()
; #define PG8_SCHED __builtin_amdgcn_sched_barrier(0)
; template <class Epi, class Sched>
; __device__ __forceinline__ void gemm_phase(LAS unsigned char* lds, const Gemm g, const Sched& S, const Epi& E) {
;     ...
;             PG8_STAGE(PG8_SB(0, 1), b2 + hstep, voffB);
;             PG8_WAIT_V(6); PG8_BAR; PG8_MMA(1, 1, At, B1); PG8_BAR;
;             PG8_LDB(B0, 1, 0); PG8_SCHED; PG8_LDA(At, 1, 0); PG8_STAGE(PG8_SA(0, 1), a2 + hstep, voffA);
;             PG8_WAIT_L(8); PG8_BAR; PG8_WAIT_L(0); PG8_MMA(0, 0, At, B0); PG8_BAR; PG8_SCHED;
;             PG8_LDB(B1, 1, 1); PG8_STAGE(PG8_SB(1, 0), b3, voffB);
;             PG8_BAR; PG8_WAIT_L(0); PG8_MMA(0, 1, At, B1); PG8_BAR;
;             PG8_LDA(At, 1, 1); PG8_STAGE(PG8_SA(1, 0), a3, voffA);
	s_add_u32 s38, s56, 0x80000
	s_addc_u32 s39, s57, 0
	s_add_i32 s52, s52, s65
	v_lshl_add_u64 v[140:141], s[38:39], 0, v[0:1]
	s_mov_b32 m0, s52
	s_nop 0
	global_load_lds_dwordx4 v[140:141], off
	v_lshl_add_u64 v[140:141], s[38:39], 0, v[130:131]
	s_add_i32 m0, s52, 0x2000
	s_nop 0
	global_load_lds_dwordx4 v[140:141], off
	s_add_u32 s38, s58, 0x80000
	s_addc_u32 s39, s59, 0
	s_mov_b32 m0, s66
	v_lshl_add_u64 v[192:193], s[38:39], 0, v[0:1]
	global_load_lds_dwordx4 v[192:193], off
	v_lshl_add_u64 v[192:193], s[38:39], 0, v[130:131]
	s_mov_b32 m0, s67
	s_nop 0
	global_load_lds_dwordx4 v[192:193], off
	s_add_i32 s52, 0, 0x18000
	v_add_u32_e32 v152, s52, v137
	ds_read_b128 v[140:143], v152
	ds_read_b128 v[144:147], v152 offset:1024
	ds_read_b128 v[148:151], v152 offset:2048
	ds_read_b128 v[152:155], v152 offset:3072
	ds_read_b128 v[160:163], v139 offset:32768
	ds_read_b128 v[164:167], v139 offset:33792
	ds_read_b128 v[168:171], v139 offset:34816
	ds_read_b128 v[172:175], v139 offset:35840
	ds_read_b128 v[176:179], v139 offset:36864
	ds_read_b128 v[180:183], v139 offset:37888
	ds_read_b128 v[184:187], v139 offset:38912
	ds_read_b128 v[188:191], v139 offset:39936
	s_add_i32 s53, 0, 0x1c000
	v_add_u32_e32 v204, s53, v137
	ds_read_b128 v[192:195], v204
	ds_read_b128 v[196:199], v204 offset:1024
	ds_read_b128 v[200:203], v204 offset:2048
	ds_read_b128 v[204:207], v204 offset:3072
	s_waitcnt lgkmcnt(4)
	s_barrier
	s_waitcnt lgkmcnt(0)
	s_setprio 1
	v_mfma_f32_16x16x32_bf16 v[126:129], v[140:143], v[160:163], v[126:129]
	v_mfma_f32_16x16x32_bf16 v[122:125], v[148:151], v[160:163], v[122:125]
	v_mfma_f32_16x16x32_bf16 v[118:121], v[140:143], v[168:171], v[118:121]
	v_mfma_f32_16x16x32_bf16 v[114:117], v[148:151], v[168:171], v[114:117]
	v_mfma_f32_16x16x32_bf16 v[106:109], v[140:143], v[176:179], v[106:109]
	v_mfma_f32_16x16x32_bf16 v[98:101], v[148:151], v[176:179], v[98:101]
	v_mfma_f32_16x16x32_bf16 v[90:93], v[140:143], v[184:187], v[90:93]
	v_mfma_f32_16x16x32_bf16 v[82:85], v[148:151], v[184:187], v[82:85]
	v_mfma_f32_16x16x32_bf16 v[126:129], v[144:147], v[164:167], v[126:129]
	v_mfma_f32_16x16x32_bf16 v[122:125], v[152:155], v[164:167], v[122:125]
	v_mfma_f32_16x16x32_bf16 v[118:121], v[144:147], v[172:175], v[118:121]
	v_mfma_f32_16x16x32_bf16 v[114:117], v[152:155], v[172:175], v[114:117]
	v_mfma_f32_16x16x32_bf16 v[106:109], v[144:147], v[180:183], v[106:109]
	v_mfma_f32_16x16x32_bf16 v[98:101], v[152:155], v[180:183], v[98:101]
	v_mfma_f32_16x16x32_bf16 v[90:93], v[144:147], v[188:191], v[90:93]
	v_mfma_f32_16x16x32_bf16 v[82:85], v[152:155], v[188:191], v[82:85]
	v_mfma_f32_16x16x32_bf16 v[110:113], v[192:195], v[160:163], v[110:113]
	v_mfma_f32_16x16x32_bf16 v[102:105], v[200:203], v[160:163], v[102:105]
	v_mfma_f32_16x16x32_bf16 v[94:97], v[192:195], v[168:171], v[94:97]
	v_mfma_f32_16x16x32_bf16 v[86:89], v[200:203], v[168:171], v[86:89]
	v_mfma_f32_16x16x32_bf16 v[78:81], v[192:195], v[176:179], v[78:81]
	v_mfma_f32_16x16x32_bf16 v[74:77], v[200:203], v[176:179], v[74:77]
	v_mfma_f32_16x16x32_bf16 v[70:73], v[192:195], v[184:187], v[70:73]
	v_mfma_f32_16x16x32_bf16 v[66:69], v[200:203], v[184:187], v[66:69]
	v_mfma_f32_16x16x32_bf16 v[110:113], v[196:199], v[164:167], v[110:113]
	v_mfma_f32_16x16x32_bf16 v[102:105], v[204:207], v[164:167], v[102:105]
	v_mfma_f32_16x16x32_bf16 v[94:97], v[196:199], v[172:175], v[94:97]
	v_mfma_f32_16x16x32_bf16 v[86:89], v[204:207], v[172:175], v[86:89]
	v_mfma_f32_16x16x32_bf16 v[78:81], v[196:199], v[180:183], v[78:81]
	v_mfma_f32_16x16x32_bf16 v[74:77], v[204:207], v[180:183], v[74:77]
	v_mfma_f32_16x16x32_bf16 v[70:73], v[196:199], v[188:191], v[70:73]
	v_mfma_f32_16x16x32_bf16 v[66:69], v[204:207], v[188:191], v[66:69]
	s_setprio 0
	s_barrier
	s_add_i32 s38, s52, s65
	v_lshl_add_u64 v[156:157], v[156:157], 0, s[36:37]
	s_mov_b32 m0, s38
	s_nop 0
	global_load_lds_dwordx4 v[156:157], off
	v_lshl_add_u64 v[156:157], v[210:211], 0, s[36:37]
	s_add_i32 m0, s38, 0x2000
	s_nop 0
	global_load_lds_dwordx4 v[156:157], off
	s_mov_b32 m0, s68
	v_lshl_add_u64 v[156:157], v[212:213], 0, s[36:37]
	global_load_lds_dwordx4 v[156:157], off
	v_lshl_add_u64 v[156:157], v[214:215], 0, s[36:37]
	s_mov_b32 m0, s69
	s_nop 0
	global_load_lds_dwordx4 v[156:157], off
	ds_read_b128 v[160:163], v139 offset:49152
	ds_read_b128 v[164:167], v139 offset:50176
	ds_read_b128 v[168:171], v139 offset:51200
	ds_read_b128 v[172:175], v139 offset:52224
	ds_read_b128 v[176:179], v139 offset:53248
	ds_read_b128 v[180:183], v139 offset:54272
	ds_read_b128 v[184:187], v139 offset:55296
	ds_read_b128 v[188:191], v139 offset:56320
	s_waitcnt vmcnt(4)
	s_waitcnt lgkmcnt(0)
	s_barrier
; #define PG8_STAGE(bufoff, gbase, voff) do { _Pragma("unroll") for (int _i = 0; _i < 2; ++_i) \
;         __builtin_amdgcn_global_load_lds((const unsigned*)((const char*)(gbase) + (voff)[_i]), (LAS unsigned*)(lds + (bufoff) + ldsw + _i * 8192), 16, 0, 0); } while (0)
; #define PG8_MMA(ai, bj, At, Bt) do { __builtin_amdgcn_s_setprio(1); _Pragma("unroll") for (int m = 0; m < 4; ++m) _Pragma("unroll") for (int n = 0; n < 2; ++n) _Pragma("unroll") for (int k = 0; k < 2; ++k) \
;         acc[ai][bj][m][n] = __builtin_amdgcn_mfma_f32_16x16x32_bf16(Bt[n][k], At[m][k], acc[ai][bj][m][n], 0, 0, 0); __builtin_amdgcn_s_setprio(0); } while (0)
; #define PG8_WAIT_V(n) asm volatile("s_waitcnt vmcnt(" #n ")" ::: "memory")
; #define PG8_WAIT_L(n) asm volatile("s_waitcnt lgkmcnt(" #n ")" ::: "memory")
; #define PG8_BAR __builtin_amdgcn_s_barrier()
;     __device__ __forceinline__ void operator()(const f32x4 (&acc)[2][2][4][2], const Unit& u, int wr, int wc, int fr, int fq) const {
;         const int row0 = u.pm * BM + wr * 64 + fr, col0 = u.pn * BM + wc * 32 + 4 * fq;
;         float* base = part + (size_t)u.ks * Mp * ldc;
; #pragma unroll
;         for (int ai = 0; ai < 2; ++ai)
; #pragma unroll
;             for (int m = 0; m < 4; ++m) { float* rowp = base + (size_t)(row0 + ai * HALF + m * 16) * ldc + col0;
; #pragma unroll
;                 for (int bj = 0; bj < 2; ++bj)
; #pragma unroll
;                     for (int n = 0; n < 2; ++n) *(f32x4*)(rowp + bj * HALF + n * 16) = acc[ai][bj][m][n]; }
;     }
; template <class Epi, class Sched>
; __device__ __forceinline__ void gemm_phase(LAS unsigned char* lds, const Gemm g, const Sched& S, const Epi& E) {
;     ...
;             PG8_BAR; PG8_WAIT_L(0); PG8_MMA(1, 0, At, B0); PG8_BAR; PG8_SCHED;
;             PG8_STAGE(PG8_SB(1, 1), b3 + hstep, voffB);
;             PG8_WAIT_V(6); PG8_BAR; PG8_MMA(1, 1, At, B1); PG8_BAR;
;         }
;         E(acc, cur, wr, wc, fr, fq);
;         if (!has_next) break;
; #pragma unroll
;         for (int a = 0; a < 2; ++a)
; #pragma unroll
;             for (int b = 0; b < 2; ++b)
; #pragma unroll
;                 for (int m = 0; m < 4; ++m)
; #pragma unroll
;                     for (int n = 0; n < 2; ++n) acc[a][b][m][n] = (f32x4){0.f, 0.f, 0.f, 0.f};
;         cur = nxt; cA = nA; cB = nB; ++ui;
;     }
;     PG8_WAIT_V(0);
;     if (wr == 0) PG8_BAR;
;     PG8_BAR;
	s_setprio 1
	v_mfma_f32_16x16x32_bf16 v[62:65], v[140:143], v[160:163], v[62:65]
	v_mfma_f32_16x16x32_bf16 v[58:61], v[148:151], v[160:163], v[58:61]
	v_mfma_f32_16x16x32_bf16 v[54:57], v[140:143], v[168:171], v[54:57]
	v_mfma_f32_16x16x32_bf16 v[50:53], v[148:151], v[168:171], v[50:53]
	v_mfma_f32_16x16x32_bf16 v[38:41], v[140:143], v[176:179], v[38:41]
	v_mfma_f32_16x16x32_bf16 v[34:37], v[148:151], v[176:179], v[34:37]
	v_mfma_f32_16x16x32_bf16 v[22:25], v[140:143], v[184:187], v[22:25]
	v_mfma_f32_16x16x32_bf16 v[18:21], v[148:151], v[184:187], v[18:21]
	v_mfma_f32_16x16x32_bf16 v[62:65], v[144:147], v[164:167], v[62:65]
	v_mfma_f32_16x16x32_bf16 v[58:61], v[152:155], v[164:167], v[58:61]
	v_mfma_f32_16x16x32_bf16 v[54:57], v[144:147], v[172:175], v[54:57]
	v_mfma_f32_16x16x32_bf16 v[50:53], v[152:155], v[172:175], v[50:53]
	v_mfma_f32_16x16x32_bf16 v[38:41], v[144:147], v[180:183], v[38:41]
	v_mfma_f32_16x16x32_bf16 v[34:37], v[152:155], v[180:183], v[34:37]
	v_mfma_f32_16x16x32_bf16 v[22:25], v[144:147], v[188:191], v[22:25]
	v_mfma_f32_16x16x32_bf16 v[18:21], v[152:155], v[188:191], v[18:21]
	s_add_u32 s38, s56, 0x80080
	s_addc_u32 s39, s57, 0
	s_add_i32 s52, s53, s65
	v_lshl_add_u64 v[140:141], s[38:39], 0, v[0:1]
	s_mov_b32 m0, s52
	s_nop 0
	global_load_lds_dwordx4 v[140:141], off
	v_lshl_add_u64 v[140:141], s[38:39], 0, v[130:131]
	s_add_i32 m0, s52, 0x2000
	s_nop 0
	global_load_lds_dwordx4 v[140:141], off
	v_mfma_f32_16x16x32_bf16 v[46:49], v[192:195], v[160:163], v[46:49]
	v_mfma_f32_16x16x32_bf16 v[42:45], v[200:203], v[160:163], v[42:45]
	v_mfma_f32_16x16x32_bf16 v[30:33], v[192:195], v[168:171], v[30:33]
	v_mfma_f32_16x16x32_bf16 v[26:29], v[200:203], v[168:171], v[26:29]
	v_mfma_f32_16x16x32_bf16 v[14:17], v[192:195], v[176:179], v[14:17]
	v_mfma_f32_16x16x32_bf16 v[10:13], v[200:203], v[176:179], v[10:13]
	v_mfma_f32_16x16x32_bf16 v[6:9], v[192:195], v[184:187], v[6:9]
	v_mfma_f32_16x16x32_bf16 v[2:5], v[200:203], v[184:187], v[2:5]
	v_mfma_f32_16x16x32_bf16 v[46:49], v[196:199], v[164:167], v[46:49]
	v_mfma_f32_16x16x32_bf16 v[42:45], v[204:207], v[164:167], v[42:45]
	v_mfma_f32_16x16x32_bf16 v[30:33], v[196:199], v[172:175], v[30:33]
	v_mfma_f32_16x16x32_bf16 v[26:29], v[204:207], v[172:175], v[26:29]
	v_mfma_f32_16x16x32_bf16 v[14:17], v[196:199], v[180:183], v[14:17]
	v_mfma_f32_16x16x32_bf16 v[10:13], v[204:207], v[180:183], v[10:13]
	v_mfma_f32_16x16x32_bf16 v[6:9], v[196:199], v[188:191], v[6:9]
	v_mfma_f32_16x16x32_bf16 v[2:5], v[204:207], v[188:191], v[2:5]
	s_setprio 0
	s_add_i32 s73, s73, 2
	s_add_u32 s71, s71, 0x100
	s_addc_u32 s72, s72, 0
	s_cmp_gt_u32 s73, 5
	s_mov_b64 s[52:53], s[54:55]
	s_barrier
	s_cbranch_scc0 .LBB0_113
	s_ashr_i32 s11, s10, 31
	s_lshl_b64 s[10:11], s[10:11], 24
	v_lshl_or_b32 v140, s26, 8, v138
	s_add_u32 s10, s8, s10
	v_lshl_add_u32 v142, s24, 8, v136
	s_addc_u32 s11, s9, s11
	v_ashrrev_i32_e32 v141, 31, v140
	v_ashrrev_i32_e32 v143, 31, v142
	v_lshl_add_u64 v[140:141], v[140:141], 2, s[10:11]
	v_lshlrev_b64 v[144:145], 13, v[142:143]
	v_lshl_add_u64 v[144:145], v[140:141], 0, v[144:145]
	global_store_dwordx4 v[144:145], v[126:129], off
	global_store_dwordx4 v[144:145], v[122:125], off offset:64
	global_store_dwordx4 v[144:145], v[110:113], off offset:512
	global_store_dwordx4 v[144:145], v[102:105], off offset:576
	s_mov_b64 s[10:11], 0x100000
	s_mov_b32 s26, s40
	v_or_b32_e32 v102, 16, v142
	v_ashrrev_i32_e32 v103, 31, v102
	v_lshlrev_b64 v[102:103], 13, v[102:103]
	v_lshl_add_u64 v[102:103], v[140:141], 0, v[102:103]
	global_store_dwordx4 v[102:103], v[118:121], off
	global_store_dwordx4 v[102:103], v[114:117], off offset:64
	global_store_dwordx4 v[102:103], v[94:97], off offset:512
	global_store_dwordx4 v[102:103], v[86:89], off offset:576
	s_mov_b32 s24, s44
	s_mov_b64 s[54:55], s[50:51]
	v_or_b32_e32 v86, 32, v142
	v_ashrrev_i32_e32 v87, 31, v86
	v_lshlrev_b64 v[86:87], 13, v[86:87]
	v_lshl_add_u64 v[86:87], v[140:141], 0, v[86:87]
	global_store_dwordx4 v[86:87], v[106:109], off
	global_store_dwordx4 v[86:87], v[98:101], off offset:64
	global_store_dwordx4 v[86:87], v[78:81], off offset:512
	global_store_dwordx4 v[86:87], v[74:77], off offset:576
	s_mov_b64 s[52:53], s[48:49]
	s_nop 0
	v_or_b32_e32 v74, 48, v142
	v_ashrrev_i32_e32 v75, 31, v74
	v_lshlrev_b64 v[74:75], 13, v[74:75]
	v_lshl_add_u64 v[74:75], v[140:141], 0, v[74:75]
	global_store_dwordx4 v[74:75], v[90:93], off
	global_store_dwordx4 v[74:75], v[82:85], off offset:64
	global_store_dwordx4 v[74:75], v[70:73], off offset:512
	global_store_dwordx4 v[74:75], v[66:69], off offset:576
	s_nop 1
	v_add_co_u32_e32 v68, vcc, s93, v144
	v_lshl_add_u64 v[66:67], v[144:145], 0, s[10:11]
	s_nop 0
	v_addc_co_u32_e32 v69, vcc, 0, v145, vcc
	s_mov_b64 s[10:11], 0x120000
	global_store_dwordx4 v[68:69], v[62:65], off
	global_store_dwordx4 v[66:67], v[58:61], off offset:64
	global_store_dwordx4 v[66:67], v[46:49], off offset:512
	global_store_dwordx4 v[66:67], v[42:45], off offset:576
	s_nop 1
	v_lshl_add_u64 v[42:43], v[144:145], 0, s[10:11]
	s_mov_b32 s10, 0x120000
	v_add_co_u32_e32 v44, vcc, s10, v144
	s_mov_b64 s[10:11], 0x140000
	s_nop 0
	v_addc_co_u32_e32 v45, vcc, 0, v145, vcc
	global_store_dwordx4 v[44:45], v[54:57], off
	global_store_dwordx4 v[42:43], v[50:53], off offset:64
	global_store_dwordx4 v[42:43], v[30:33], off offset:512
	global_store_dwordx4 v[42:43], v[26:29], off offset:576
	s_nop 1
	v_lshl_add_u64 v[26:27], v[144:145], 0, s[10:11]
	s_mov_b32 s10, 0x140000
	v_add_co_u32_e32 v28, vcc, s10, v144
	s_mov_b64 s[10:11], 0x160000
	s_nop 0
	v_addc_co_u32_e32 v29, vcc, 0, v145, vcc
	global_store_dwordx4 v[28:29], v[38:41], off
	global_store_dwordx4 v[26:27], v[34:37], off offset:64
	global_store_dwordx4 v[26:27], v[14:17], off offset:512
	global_store_dwordx4 v[26:27], v[10:13], off offset:576
	s_nop 1
	v_add_co_u32_e32 v12, vcc, 0x160000, v144
	v_lshl_add_u64 v[10:11], v[144:145], 0, s[10:11]
	s_nop 0
	v_addc_co_u32_e32 v13, vcc, 0, v145, vcc
	s_and_b64 vcc, exec, s[46:47]
	s_mov_b32 s10, s28
	global_store_dwordx4 v[12:13], v[22:25], off
	global_store_dwordx4 v[10:11], v[18:21], off offset:64
	global_store_dwordx4 v[10:11], v[6:9], off offset:512
	global_store_dwordx4 v[10:11], v[2:5], off offset:576
	s_cbranch_vccz .LBB0_110
	s_waitcnt vmcnt(0)
	s_cmpk_gt_u32 s60, 0xff
	s_cbranch_scc1 .LBB0_117
	s_barrier

; #define PG8_STAGE(bufoff, gbase, voff) do { _Pragma("unroll") for (int _i = 0; _i < 2; ++_i) \
;         __builtin_amdgcn_global_load_lds((const unsigned*)((const char*)(gbase) + (voff)[_i]), (LAS unsigned*)(lds + (bufoff) + ldsw + _i * 8192), 16, 0, 0); } while (0)
; #define PG8_LDA(dst, b, h) do { _Pragma("unroll") for (int m = 0; m < 4; ++m) _Pragma("unroll") for (int k = 0; k < 2; ++k) dst[m][k] = *(const LAS bf16x8*)(lds + PG8_SA(b, h) + aoff + m * 2048 + k * 1024); } while (0)
; #define PG8_LDB(dst, b, h) do { _Pragma("unroll") for (int n = 0; n < 2; ++n) _Pragma("unroll") for (int k = 0; k < 2; ++k) dst[n][k] = *(const LAS bf16x8*)(lds + PG8_SB(b, h) + boff + n * 2048 + k * 1024); } while (0)
; #define PG8_MMA(ai, bj, At, Bt) do { __builtin_amdgcn_s_setprio(1); _Pragma("unroll") for (int m = 0; m < 4; ++m) _Pragma("unroll") for (int n = 0; n < 2; ++n) _Pragma("unroll") for (int k = 0; k < 2; ++k) \
;         acc[ai][bj][m][n] = __builtin_amdgcn_mfma_f32_16x16x32_bf16(Bt[n][k], At[m][k], acc[ai][bj][m][n], 0, 0, 0); __builtin_amdgcn_s_setprio(0); } while (0)
; #define PG8_WAIT_L(n) asm volatile("s_waitcnt lgkmcnt(" #n ")" ::: "memory")
; #define PG8_BAR __builtin_amdgcn_s_barrier()
; #define PG8_SCHED __builtin_amdgcn_sched_barrier(0)
; template <class Epi, class Sched>
; __device__ __forceinline__ void gemm_phase(LAS unsigned char* lds, const Gemm g, const Sched& S, const Epi& E) {
;     ...
;             const bool last = (t == nt - 2);
;             const char* a1 = cA + (size_t)(t + 1) * kstep;
;             const char* a2 = last ? nA : cA + (size_t)(t + 2) * kstep; const char* b2 = last ? nB : cB + (size_t)(t + 2) * kstep;
;             const char* a3 = a2 + kstep; const char* b3 = b2 + kstep;
;             PG8_LDB(B0, 0, 0); PG8_SCHED; PG8_LDA(At, 0, 0); PG8_STAGE(PG8_SA(1, 1), a1 + hstep, voffA);
;             PG8_WAIT_L(8); PG8_BAR; PG8_WAIT_L(0); PG8_MMA(0, 0, At, B0); PG8_BAR; PG8_SCHED;
;             PG8_LDB(B1, 0, 1); PG8_STAGE(PG8_SB(0, 0), b2, voffB);
;             PG8_BAR; PG8_WAIT_L(0); PG8_MMA(0, 1, At, B1); PG8_BAR;
;             PG8_LDA(At, 0, 1); PG8_STAGE(PG8_SA(0, 0), a2, voffA);
;             PG8_BAR; PG8_WAIT_L(0); PG8_MMA(1, 0, At, B0); PG8_BAR; PG8_SCHED;
.LBB0_354:
	s_add_u32 s38, s50, 0xfff80080
	s_addc_u32 s39, s51, -1
	s_cmp_eq_u32 s70, 28
	s_cselect_b32 s55, s9, s39
	s_cselect_b32 s54, s66, s38
	s_cselect_b32 s53, s43, s69
	s_cselect_b32 s52, s67, s68
	v_lshl_add_u64 v[156:157], s[50:51], 0, v[138:139]
	s_add_i32 m0, s29, 0xc000
	s_nop 0
	global_load_lds_dwordx4 v[156:157], off
	v_lshl_add_u64 v[156:157], s[50:51], 0, v[136:137]
	s_add_i32 m0, s29, 0xe000
	s_nop 0
	global_load_lds_dwordx4 v[156:157], off
	s_add_i32 s71, 0, 0x10000
	v_add_u32_e32 v156, s71, v145
	ds_read_b128 v[140:143], v156
	ds_read_b128 v[148:151], v156 offset:1024
	ds_read_b128 v[152:155], v156 offset:2048
	ds_read_b128 v[160:163], v156 offset:3072
	ds_read_b128 v[164:167], v147
	ds_read_b128 v[168:171], v147 offset:1024
	ds_read_b128 v[172:175], v147 offset:2048
	ds_read_b128 v[176:179], v147 offset:3072
	ds_read_b128 v[180:183], v147 offset:4096
	ds_read_b128 v[184:187], v147 offset:5120
	ds_read_b128 v[188:191], v147 offset:6144
	ds_read_b128 v[192:195], v147 offset:7168
	s_add_i32 s38, 0, 0x14000
	v_add_u32_e32 v156, s38, v145
	ds_read_b128 v[196:199], v156
	ds_read_b128 v[200:203], v156 offset:1024
	ds_read_b128 v[204:207], v156 offset:2048
	ds_read_b128 v[210:213], v156 offset:3072
	s_waitcnt lgkmcnt(4)
	s_barrier
	s_waitcnt lgkmcnt(0)
	s_setprio 1
	v_mfma_f32_16x16x32_bf16 v[126:129], v[140:143], v[164:167], v[126:129]
	v_mfma_f32_16x16x32_bf16 v[122:125], v[152:155], v[164:167], v[122:125]
	v_mfma_f32_16x16x32_bf16 v[118:121], v[140:143], v[172:175], v[118:121]
	v_mfma_f32_16x16x32_bf16 v[110:113], v[152:155], v[172:175], v[110:113]
	v_mfma_f32_16x16x32_bf16 v[102:105], v[140:143], v[180:183], v[102:105]
	v_mfma_f32_16x16x32_bf16 v[94:97], v[152:155], v[180:183], v[94:97]
	v_mfma_f32_16x16x32_bf16 v[86:89], v[140:143], v[188:191], v[86:89]
	v_mfma_f32_16x16x32_bf16 v[78:81], v[152:155], v[188:191], v[78:81]
	v_mfma_f32_16x16x32_bf16 v[126:129], v[148:151], v[168:171], v[126:129]
	v_mfma_f32_16x16x32_bf16 v[122:125], v[160:163], v[168:171], v[122:125]
	v_mfma_f32_16x16x32_bf16 v[118:121], v[148:151], v[176:179], v[118:121]
	v_mfma_f32_16x16x32_bf16 v[110:113], v[160:163], v[176:179], v[110:113]
	v_mfma_f32_16x16x32_bf16 v[102:105], v[148:151], v[184:187], v[102:105]
	v_mfma_f32_16x16x32_bf16 v[94:97], v[160:163], v[184:187], v[94:97]
	v_mfma_f32_16x16x32_bf16 v[86:89], v[148:151], v[192:195], v[86:89]
	v_mfma_f32_16x16x32_bf16 v[78:81], v[160:163], v[192:195], v[78:81]
	v_mfma_f32_16x16x32_bf16 v[114:117], v[196:199], v[164:167], v[114:117]
	v_mfma_f32_16x16x32_bf16 v[106:109], v[204:207], v[164:167], v[106:109]
	v_mfma_f32_16x16x32_bf16 v[98:101], v[196:199], v[172:175], v[98:101]
	v_mfma_f32_16x16x32_bf16 v[90:93], v[204:207], v[172:175], v[90:93]
	v_mfma_f32_16x16x32_bf16 v[82:85], v[196:199], v[180:183], v[82:85]
	v_mfma_f32_16x16x32_bf16 v[74:77], v[204:207], v[180:183], v[74:77]
	v_mfma_f32_16x16x32_bf16 v[70:73], v[196:199], v[188:191], v[70:73]
	v_mfma_f32_16x16x32_bf16 v[66:69], v[204:207], v[188:191], v[66:69]
	v_mfma_f32_16x16x32_bf16 v[114:117], v[200:203], v[168:171], v[114:117]
	v_mfma_f32_16x16x32_bf16 v[106:109], v[210:213], v[168:171], v[106:109]
	v_mfma_f32_16x16x32_bf16 v[98:101], v[200:203], v[176:179], v[98:101]
	v_mfma_f32_16x16x32_bf16 v[90:93], v[210:213], v[176:179], v[90:93]
	v_mfma_f32_16x16x32_bf16 v[82:85], v[200:203], v[184:187], v[82:85]
	v_mfma_f32_16x16x32_bf16 v[74:77], v[210:213], v[184:187], v[74:77]
	v_mfma_f32_16x16x32_bf16 v[70:73], v[200:203], v[192:195], v[70:73]
	v_mfma_f32_16x16x32_bf16 v[66:69], v[210:213], v[192:195], v[66:69]
	s_setprio 0
	s_barrier
	s_add_i32 s39, s71, s56
	v_lshl_add_u64 v[156:157], s[52:53], 0, v[0:1]
	s_mov_b32 m0, s39
	v_lshl_add_u64 v[214:215], s[52:53], 0, v[134:135]
	global_load_lds_dwordx4 v[156:157], off
	s_add_i32 m0, s39, 0x2000
	s_nop 0
	global_load_lds_dwordx4 v[214:215], off
	s_mov_b32 m0, s29
	v_lshl_add_u64 v[216:217], s[54:55], 0, v[130:131]
	global_load_lds_dwordx4 v[216:217], off
	v_lshl_add_u64 v[224:225], s[54:55], 0, v[132:133]
	s_mov_b32 m0, s41
	s_nop 0
	global_load_lds_dwordx4 v[224:225], off
	ds_read_b128 v[164:167], v147 offset:16384
	ds_read_b128 v[168:171], v147 offset:17408
	ds_read_b128 v[172:175], v147 offset:18432
	ds_read_b128 v[176:179], v147 offset:19456
	ds_read_b128 v[180:183], v147 offset:20480
	ds_read_b128 v[184:187], v147 offset:21504
	ds_read_b128 v[188:191], v147 offset:22528
	ds_read_b128 v[192:195], v147 offset:23552
	s_waitcnt vmcnt(4)
	s_waitcnt lgkmcnt(0)
	s_barrier
	s_setprio 1
	v_mfma_f32_16x16x32_bf16 v[62:65], v[140:143], v[164:167], v[62:65]
	v_mfma_f32_16x16x32_bf16 v[58:61], v[152:155], v[164:167], v[58:61]
	v_mfma_f32_16x16x32_bf16 v[54:57], v[140:143], v[172:175], v[54:57]
	v_mfma_f32_16x16x32_bf16 v[46:49], v[152:155], v[172:175], v[46:49]
	v_mfma_f32_16x16x32_bf16 v[38:41], v[140:143], v[180:183], v[38:41]
	v_mfma_f32_16x16x32_bf16 v[30:33], v[152:155], v[180:183], v[30:33]
	v_mfma_f32_16x16x32_bf16 v[22:25], v[140:143], v[188:191], v[22:25]
	v_mfma_f32_16x16x32_bf16 v[14:17], v[152:155], v[188:191], v[14:17]
	v_mfma_f32_16x16x32_bf16 v[62:65], v[148:151], v[168:171], v[62:65]
	v_mfma_f32_16x16x32_bf16 v[58:61], v[160:163], v[168:171], v[58:61]
	v_mfma_f32_16x16x32_bf16 v[54:57], v[148:151], v[176:179], v[54:57]
	v_mfma_f32_16x16x32_bf16 v[46:49], v[160:163], v[176:179], v[46:49]
	v_mfma_f32_16x16x32_bf16 v[38:41], v[148:151], v[184:187], v[38:41]
	v_mfma_f32_16x16x32_bf16 v[30:33], v[160:163], v[184:187], v[30:33]
	v_mfma_f32_16x16x32_bf16 v[22:25], v[148:151], v[192:195], v[22:25]
	v_mfma_f32_16x16x32_bf16 v[14:17], v[160:163], v[192:195], v[14:17]
	v_mfma_f32_16x16x32_bf16 v[50:53], v[196:199], v[164:167], v[50:53]
	v_mfma_f32_16x16x32_bf16 v[42:45], v[204:207], v[164:167], v[42:45]
	v_mfma_f32_16x16x32_bf16 v[34:37], v[196:199], v[172:175], v[34:37]
	v_mfma_f32_16x16x32_bf16 v[26:29], v[204:207], v[172:175], v[26:29]
	v_mfma_f32_16x16x32_bf16 v[18:21], v[196:199], v[180:183], v[18:21]
	v_mfma_f32_16x16x32_bf16 v[10:13], v[204:207], v[180:183], v[10:13]
	v_mfma_f32_16x16x32_bf16 v[6:9], v[196:199], v[188:191], v[6:9]
	v_mfma_f32_16x16x32_bf16 v[2:5], v[204:207], v[188:191], v[2:5]
	v_mfma_f32_16x16x32_bf16 v[50:53], v[200:203], v[168:171], v[50:53]
	v_mfma_f32_16x16x32_bf16 v[42:45], v[210:213], v[168:171], v[42:45]
	v_mfma_f32_16x16x32_bf16 v[34:37], v[200:203], v[176:179], v[34:37]
	v_mfma_f32_16x16x32_bf16 v[26:29], v[210:213], v[176:179], v[26:29]
	v_mfma_f32_16x16x32_bf16 v[18:21], v[200:203], v[184:187], v[18:21]
	v_mfma_f32_16x16x32_bf16 v[10:13], v[210:213], v[184:187], v[10:13]
	v_mfma_f32_16x16x32_bf16 v[6:9], v[200:203], v[192:195], v[6:9]
	v_mfma_f32_16x16x32_bf16 v[2:5], v[210:213], v[192:195], v[2:5]
	s_setprio 0
	s_barrier
; #define PG8_STAGE(bufoff, gbase, voff) do { _Pragma("unroll") for (int _i = 0; _i < 2; ++_i) \
;         __builtin_amdgcn_global_load_lds((const unsigned*)((const char*)(gbase) + (voff)[_i]), (LAS unsigned*)(lds + (bufoff) + ldsw + _i * 8192), 16, 0, 0); } while (0)
; #define PG8_LDA(dst, b, h) do { _Pragma("unroll") for (int m = 0; m < 4; ++m) _Pragma("unroll") for (int k = 0; k < 2; ++k) dst[m][k] = *(const LAS bf16x8*)(lds + PG8_SA(b, h) + aoff + m * 2048 + k * 1024); } while (0)
; #define PG8_LDB(dst, b, h) do { _Pragma("unroll") for (int n = 0; n < 2; ++n) _Pragma("unroll") for (int k = 0; k < 2; ++k) dst[n][k] = *(const LAS bf16x8*)(lds + PG8_SB(b, h) + boff + n * 2048 + k * 1024); } while (0)
; #define PG8_MMA(ai, bj, At, Bt) do { __builtin_amdgcn_s_setprio(1); _Pragma("unroll") for (int m = 0; m < 4; ++m) _Pragma("unroll") for (int n = 0; n < 2; ++n) _Pragma("unroll") for (int k = 0; k < 2; ++k) \
;         acc[ai][bj][m][n] = __builtin_amdgcn_mfma_f32_16x16x32_bf16(Bt[n][k], At[m][k], acc[ai][bj][m][n], 0, 0, 0); __builtin_amdgcn_s_setprio(0); } while (0)
; #define PG8_WAIT_V(n) asm volatile("s_waitcnt vmcnt(" #n ")" ::: "memory")
; #define PG8_WAIT_L(n) asm volatile("s_waitcnt lgkmcnt(" #n ")" ::: "memory")
; #define PG8_BAR __builtin_amdgcn_s_barrier()
; #define PG8_SCHED __builtin_amdgcn_sched_barrier(0)
; template <class Epi, class Sched>
; __device__ __forceinline__ void gemm_phase(LAS unsigned char* lds, const Gemm g, const Sched& S, const Epi& E) {
;     ...
;             PG8_STAGE(PG8_SB(0, 1), b2 + hstep, voffB);
;             PG8_WAIT_V(6); PG8_BAR; PG8_MMA(1, 1, At, B1); PG8_BAR;
;             PG8_LDB(B0, 1, 0); PG8_SCHED; PG8_LDA(At, 1, 0); PG8_STAGE(PG8_SA(0, 1), a2 + hstep, voffA);
;             PG8_WAIT_L(8); PG8_BAR; PG8_WAIT_L(0); PG8_MMA(0, 0, At, B0); PG8_BAR; PG8_SCHED;
;             PG8_LDB(B1, 1, 1); PG8_STAGE(PG8_SB(1, 0), b3, voffB);
;             PG8_BAR; PG8_WAIT_L(0); PG8_MMA(0, 1, At, B1); PG8_BAR;
;             PG8_LDA(At, 1, 1); PG8_STAGE(PG8_SA(1, 0), a3, voffA);
	s_add_u32 s72, s52, 0x80000
	s_addc_u32 s73, s53, 0
	s_add_i32 s38, s38, s56
	v_lshl_add_u64 v[140:141], s[72:73], 0, v[0:1]
	s_mov_b32 m0, s38
	s_nop 0
	global_load_lds_dwordx4 v[140:141], off
	v_lshl_add_u64 v[140:141], s[72:73], 0, v[134:135]
	s_add_i32 m0, s38, 0x2000
	s_nop 0
	global_load_lds_dwordx4 v[140:141], off
	s_add_u32 s54, s54, 0x80000
	s_addc_u32 s55, s55, 0
	s_mov_b32 m0, s57
	v_lshl_add_u64 v[196:197], s[54:55], 0, v[130:131]
	global_load_lds_dwordx4 v[196:197], off
	v_lshl_add_u64 v[196:197], s[54:55], 0, v[132:133]
	s_mov_b32 m0, s58
	s_nop 0
	global_load_lds_dwordx4 v[196:197], off
	s_add_i32 s38, 0, 0x18000
	v_add_u32_e32 v160, s38, v145
	ds_read_b128 v[140:143], v160
	ds_read_b128 v[148:151], v160 offset:1024
	ds_read_b128 v[152:155], v160 offset:2048
	ds_read_b128 v[160:163], v160 offset:3072
	ds_read_b128 v[164:167], v147 offset:32768
	ds_read_b128 v[168:171], v147 offset:33792
	ds_read_b128 v[172:175], v147 offset:34816
	ds_read_b128 v[176:179], v147 offset:35840
	ds_read_b128 v[180:183], v147 offset:36864
	ds_read_b128 v[184:187], v147 offset:37888
	ds_read_b128 v[188:191], v147 offset:38912
	ds_read_b128 v[192:195], v147 offset:39936
	s_add_i32 s39, 0, 0x1c000
	v_add_u32_e32 v210, s39, v145
	ds_read_b128 v[196:199], v210
	ds_read_b128 v[200:203], v210 offset:1024
	ds_read_b128 v[204:207], v210 offset:2048
	ds_read_b128 v[210:213], v210 offset:3072
	s_waitcnt lgkmcnt(4)
	s_barrier
	s_waitcnt lgkmcnt(0)
	s_setprio 1
	v_mfma_f32_16x16x32_bf16 v[126:129], v[140:143], v[164:167], v[126:129]
	v_mfma_f32_16x16x32_bf16 v[122:125], v[152:155], v[164:167], v[122:125]
	v_mfma_f32_16x16x32_bf16 v[118:121], v[140:143], v[172:175], v[118:121]
	v_mfma_f32_16x16x32_bf16 v[110:113], v[152:155], v[172:175], v[110:113]
	v_mfma_f32_16x16x32_bf16 v[102:105], v[140:143], v[180:183], v[102:105]
	v_mfma_f32_16x16x32_bf16 v[94:97], v[152:155], v[180:183], v[94:97]
	v_mfma_f32_16x16x32_bf16 v[86:89], v[140:143], v[188:191], v[86:89]
	v_mfma_f32_16x16x32_bf16 v[78:81], v[152:155], v[188:191], v[78:81]
	v_mfma_f32_16x16x32_bf16 v[126:129], v[148:151], v[168:171], v[126:129]
	v_mfma_f32_16x16x32_bf16 v[122:125], v[160:163], v[168:171], v[122:125]
	v_mfma_f32_16x16x32_bf16 v[118:121], v[148:151], v[176:179], v[118:121]
	v_mfma_f32_16x16x32_bf16 v[110:113], v[160:163], v[176:179], v[110:113]
	v_mfma_f32_16x16x32_bf16 v[102:105], v[148:151], v[184:187], v[102:105]
	v_mfma_f32_16x16x32_bf16 v[94:97], v[160:163], v[184:187], v[94:97]
	v_mfma_f32_16x16x32_bf16 v[86:89], v[148:151], v[192:195], v[86:89]
	v_mfma_f32_16x16x32_bf16 v[78:81], v[160:163], v[192:195], v[78:81]
	v_mfma_f32_16x16x32_bf16 v[114:117], v[196:199], v[164:167], v[114:117]
	v_mfma_f32_16x16x32_bf16 v[106:109], v[204:207], v[164:167], v[106:109]
	v_mfma_f32_16x16x32_bf16 v[98:101], v[196:199], v[172:175], v[98:101]
	v_mfma_f32_16x16x32_bf16 v[90:93], v[204:207], v[172:175], v[90:93]
	v_mfma_f32_16x16x32_bf16 v[82:85], v[196:199], v[180:183], v[82:85]
	v_mfma_f32_16x16x32_bf16 v[74:77], v[204:207], v[180:183], v[74:77]
	v_mfma_f32_16x16x32_bf16 v[70:73], v[196:199], v[188:191], v[70:73]
	v_mfma_f32_16x16x32_bf16 v[66:69], v[204:207], v[188:191], v[66:69]
	v_mfma_f32_16x16x32_bf16 v[114:117], v[200:203], v[168:171], v[114:117]
	v_mfma_f32_16x16x32_bf16 v[106:109], v[210:213], v[168:171], v[106:109]
	v_mfma_f32_16x16x32_bf16 v[98:101], v[200:203], v[176:179], v[98:101]
	v_mfma_f32_16x16x32_bf16 v[90:93], v[210:213], v[176:179], v[90:93]
	v_mfma_f32_16x16x32_bf16 v[82:85], v[200:203], v[184:187], v[82:85]
	v_mfma_f32_16x16x32_bf16 v[74:77], v[210:213], v[184:187], v[74:77]
	v_mfma_f32_16x16x32_bf16 v[70:73], v[200:203], v[192:195], v[70:73]
	v_mfma_f32_16x16x32_bf16 v[66:69], v[210:213], v[192:195], v[66:69]
	s_setprio 0
	s_barrier
	s_add_i32 s38, s38, s56
	v_lshl_add_u64 v[156:157], v[156:157], 0, s[36:37]
	s_mov_b32 m0, s38
	s_nop 0
	global_load_lds_dwordx4 v[156:157], off
	v_lshl_add_u64 v[156:157], v[214:215], 0, s[36:37]
	s_add_i32 m0, s38, 0x2000
	s_nop 0
	global_load_lds_dwordx4 v[156:157], off
	s_mov_b32 m0, s59
	v_lshl_add_u64 v[156:157], v[216:217], 0, s[36:37]
	global_load_lds_dwordx4 v[156:157], off
	v_lshl_add_u64 v[156:157], v[224:225], 0, s[36:37]
	s_mov_b32 m0, s60
	s_nop 0
	global_load_lds_dwordx4 v[156:157], off
	ds_read_b128 v[164:167], v147 offset:49152
	ds_read_b128 v[168:171], v147 offset:50176
	ds_read_b128 v[172:175], v147 offset:51200
	ds_read_b128 v[176:179], v147 offset:52224
	ds_read_b128 v[180:183], v147 offset:53248
	ds_read_b128 v[184:187], v147 offset:54272
	ds_read_b128 v[188:191], v147 offset:55296
	ds_read_b128 v[192:195], v147 offset:56320
	s_waitcnt vmcnt(4)
	s_waitcnt lgkmcnt(0)
	s_barrier
; #define PG8_STAGE(bufoff, gbase, voff) do { _Pragma("unroll") for (int _i = 0; _i < 2; ++_i) \
;         __builtin_amdgcn_global_load_lds((const unsigned*)((const char*)(gbase) + (voff)[_i]), (LAS unsigned*)(lds + (bufoff) + ldsw + _i * 8192), 16, 0, 0); } while (0)
; #define PG8_MMA(ai, bj, At, Bt) do { __builtin_amdgcn_s_setprio(1); _Pragma("unroll") for (int m = 0; m < 4; ++m) _Pragma("unroll") for (int n = 0; n < 2; ++n) _Pragma("unroll") for (int k = 0; k < 2; ++k) \
;         acc[ai][bj][m][n] = __builtin_amdgcn_mfma_f32_16x16x32_bf16(Bt[n][k], At[m][k], acc[ai][bj][m][n], 0, 0, 0); __builtin_amdgcn_s_setprio(0); } while (0)
; #define PG8_WAIT_V(n) asm volatile("s_waitcnt vmcnt(" #n ")" ::: "memory")
; #define PG8_WAIT_L(n) asm volatile("s_waitcnt lgkmcnt(" #n ")" ::: "memory")
; #define PG8_BAR __builtin_amdgcn_s_barrier()
; #define PG8_SCHED __builtin_amdgcn_sched_barrier(0)
; template <class Epi, class Sched>
; __device__ __forceinline__ void gemm_phase(LAS unsigned char* lds, const Gemm g, const Sched& S, const Epi& E) {
;     ...
;             PG8_BAR; PG8_WAIT_L(0); PG8_MMA(1, 0, At, B0); PG8_BAR; PG8_SCHED;
;             PG8_STAGE(PG8_SB(1, 1), b3 + hstep, voffB);
;             PG8_WAIT_V(6); PG8_BAR; PG8_MMA(1, 1, At, B1); PG8_BAR;
	s_setprio 1
	v_mfma_f32_16x16x32_bf16 v[62:65], v[140:143], v[164:167], v[62:65]
	v_mfma_f32_16x16x32_bf16 v[58:61], v[152:155], v[164:167], v[58:61]
	v_mfma_f32_16x16x32_bf16 v[54:57], v[140:143], v[172:175], v[54:57]
	v_mfma_f32_16x16x32_bf16 v[46:49], v[152:155], v[172:175], v[46:49]
	v_mfma_f32_16x16x32_bf16 v[38:41], v[140:143], v[180:183], v[38:41]
	v_mfma_f32_16x16x32_bf16 v[30:33], v[152:155], v[180:183], v[30:33]
	v_mfma_f32_16x16x32_bf16 v[22:25], v[140:143], v[188:191], v[22:25]
	v_mfma_f32_16x16x32_bf16 v[14:17], v[152:155], v[188:191], v[14:17]
	v_mfma_f32_16x16x32_bf16 v[62:65], v[148:151], v[168:171], v[62:65]
	v_mfma_f32_16x16x32_bf16 v[58:61], v[160:163], v[168:171], v[58:61]
	v_mfma_f32_16x16x32_bf16 v[54:57], v[148:151], v[176:179], v[54:57]
	v_mfma_f32_16x16x32_bf16 v[46:49], v[160:163], v[176:179], v[46:49]
	v_mfma_f32_16x16x32_bf16 v[38:41], v[148:151], v[184:187], v[38:41]
	v_mfma_f32_16x16x32_bf16 v[30:33], v[160:163], v[184:187], v[30:33]
	v_mfma_f32_16x16x32_bf16 v[22:25], v[148:151], v[192:195], v[22:25]
	v_mfma_f32_16x16x32_bf16 v[14:17], v[160:163], v[192:195], v[14:17]
	s_add_u32 s52, s52, 0x80080
	s_addc_u32 s53, s53, 0
	s_add_i32 s38, s39, s56
	v_lshl_add_u64 v[140:141], s[52:53], 0, v[0:1]
	s_mov_b32 m0, s38
	s_nop 0
	global_load_lds_dwordx4 v[140:141], off
	v_lshl_add_u64 v[140:141], s[52:53], 0, v[134:135]
	s_add_i32 m0, s38, 0x2000
	s_nop 0
	global_load_lds_dwordx4 v[140:141], off
	v_mfma_f32_16x16x32_bf16 v[50:53], v[196:199], v[164:167], v[50:53]
	v_mfma_f32_16x16x32_bf16 v[42:45], v[204:207], v[164:167], v[42:45]
	v_mfma_f32_16x16x32_bf16 v[34:37], v[196:199], v[172:175], v[34:37]
	v_mfma_f32_16x16x32_bf16 v[26:29], v[204:207], v[172:175], v[26:29]
	v_mfma_f32_16x16x32_bf16 v[18:21], v[196:199], v[180:183], v[18:21]
	v_mfma_f32_16x16x32_bf16 v[10:13], v[204:207], v[180:183], v[10:13]
	v_mfma_f32_16x16x32_bf16 v[6:9], v[196:199], v[188:191], v[6:9]
	v_mfma_f32_16x16x32_bf16 v[2:5], v[204:207], v[188:191], v[2:5]
	v_mfma_f32_16x16x32_bf16 v[50:53], v[200:203], v[168:171], v[50:53]
	v_mfma_f32_16x16x32_bf16 v[42:45], v[210:213], v[168:171], v[42:45]
	v_mfma_f32_16x16x32_bf16 v[34:37], v[200:203], v[176:179], v[34:37]
	v_mfma_f32_16x16x32_bf16 v[26:29], v[210:213], v[176:179], v[26:29]
	v_mfma_f32_16x16x32_bf16 v[18:21], v[200:203], v[184:187], v[18:21]
	v_mfma_f32_16x16x32_bf16 v[10:13], v[210:213], v[184:187], v[10:13]
	v_mfma_f32_16x16x32_bf16 v[6:9], v[200:203], v[192:195], v[6:9]
	v_mfma_f32_16x16x32_bf16 v[2:5], v[210:213], v[192:195], v[2:5]
	s_setprio 0
	s_add_i32 s70, s70, 2
	s_add_u32 s68, s68, 0x100
	s_addc_u32 s69, s69, 0
	s_add_u32 s50, s50, 0x100
	s_addc_u32 s51, s51, 0
	s_cmp_gt_u32 s70, 29
	s_barrier
	s_cbranch_scc0 .LBB0_354
; __device__ __forceinline__ unsigned cvt_pk_bf16(float lo, float hi) { unsigned r; asm("v_cvt_pk_bf16_f32 %0, %1, %2" : "=v"(r) : "v"(lo), "v"(hi)); return r; }
; #define PG8_WAIT_V(n) asm volatile("s_waitcnt vmcnt(" #n ")" ::: "memory")
; #define PG8_BAR __builtin_amdgcn_s_barrier()
;     __device__ __forceinline__ void operator()(const f32x4 (&acc)[2][2][4][2], const Unit& u, int wr, int wc, int fr, int fq) const {
;         const int row0 = u.pm * BM + wr * 64 + fr, col0 = u.pn * BM + wc * 32 + 8 * fq;
; #pragma unroll
;         for (int ai = 0; ai < 2; ++ai)
; #pragma unroll
;             for (int m = 0; m < 4; ++m) { bf16_t* rowp = O + (size_t)(row0 + ai * HALF + m * 16) * ldc + col0;
; #pragma unroll
;                 for (int bj = 0; bj < 2; ++bj) { f32x4 v0 = acc[ai][bj][m][0], v1 = acc[ai][bj][m][1];
;                     if (ACT == 1) {
; #pragma unroll
;                         for (int j = 0; j < 4; ++j) { float a = fmaxf(v0[j], 0.f), b = fmaxf(v1[j], 0.f); v0[j] = a * a; v1[j] = b * b; } }
;                     u32x4 w; w.x = cvt_pk_bf16(v0[0], v0[1]); w.y = cvt_pk_bf16(v0[2], v0[3]); w.z = cvt_pk_bf16(v1[0], v1[1]); w.w = cvt_pk_bf16(v1[2], v1[3]);
;                     if (ACT == 1) __builtin_nontemporal_store(w, (u32x4*)(rowp + bj * HALF));
;                     else *(u32x4*)(rowp + bj * HALF) = w; } }
;     }
; template <class Epi, class Sched>
; __device__ __forceinline__ void gemm_phase(LAS unsigned char* lds, const Gemm g, const Sched& S, const Epi& E) {
;     ...
;         E(acc, cur, wr, wc, fr, fq);
;         if (!has_next) break;
; #pragma unroll
;         for (int a = 0; a < 2; ++a)
; #pragma unroll
;             for (int b = 0; b < 2; ++b)
; #pragma unroll
;                 for (int m = 0; m < 4; ++m)
; #pragma unroll
;                     for (int n = 0; n < 2; ++n) acc[a][b][m][n] = (f32x4){0.f, 0.f, 0.f, 0.f};
;         cur = nxt; cA = nA; cB = nB; ++ui;
;     }
;     PG8_WAIT_V(0);
;     if (wr == 0) PG8_BAR;
;     PG8_BAR;
	s_load_dwordx2 s[50:51], s[0:1], 0xc0
	v_lshl_add_u32 v150, s28, 8, v144
	v_lshl_or_b32 v142, s40, 8, v146
	v_ashrrev_i32_e32 v143, 31, v142
	v_cvt_pk_bf16_f32 v70, v70, v71
	s_waitcnt lgkmcnt(0)
	v_mov_b64_e32 v[140:141], s[50:51]
	v_cvt_pk_bf16_f32 v71, v72, v73
	v_cvt_pk_bf16_f32 v72, v66, v67
	v_add_u32_e32 v66, 0x80, v150
	v_mad_i64_i32 v[148:149], s[50:51], v150, s17, v[140:141]
	v_lshlrev_b64 v[142:143], 1, v[142:143]
	v_cvt_pk_bf16_f32 v114, v114, v115
	v_cvt_pk_bf16_f32 v115, v116, v117
	v_cvt_pk_bf16_f32 v116, v106, v107
	v_or_b32_e32 v106, 16, v150
	v_mad_i64_i32 v[66:67], s[50:51], v66, s17, v[140:141]
	v_cvt_pk_bf16_f32 v50, v50, v51
	v_cvt_pk_bf16_f32 v51, v52, v53
	v_cvt_pk_bf16_f32 v52, v42, v43
	v_add_u32_e32 v42, 0x90, v150
	v_lshl_add_u64 v[148:149], v[148:149], 0, v[142:143]
	v_mad_i64_i32 v[106:107], s[50:51], v106, s17, v[140:141]
	v_cvt_pk_bf16_f32 v98, v98, v99
	v_cvt_pk_bf16_f32 v99, v100, v101
	v_cvt_pk_bf16_f32 v100, v90, v91
	v_or_b32_e32 v90, 32, v150
	v_lshl_add_u64 v[66:67], v[66:67], 0, v[142:143]
	v_mad_i64_i32 v[42:43], s[50:51], v42, s17, v[140:141]
	v_cvt_pk_bf16_f32 v34, v34, v35
	v_cvt_pk_bf16_f32 v35, v36, v37
	v_cvt_pk_bf16_f32 v36, v26, v27
	v_add_u32_e32 v26, 0xa0, v150
	v_cvt_pk_bf16_f32 v117, v108, v109
	global_store_dwordx4 v[148:149], v[114:117], off offset:256
	v_mad_i64_i32 v[90:91], s[50:51], v90, s17, v[140:141]
	s_nop 0
	v_lshl_add_u64 v[114:115], v[106:107], 0, v[142:143]
	v_cvt_pk_bf16_f32 v82, v82, v83
	v_cvt_pk_bf16_f32 v83, v84, v85
	v_cvt_pk_bf16_f32 v84, v74, v75
	v_or_b32_e32 v74, 48, v150
	v_cvt_pk_bf16_f32 v53, v44, v45
	global_store_dwordx4 v[66:67], v[50:53], off offset:256
	v_mad_i64_i32 v[26:27], s[50:51], v26, s17, v[140:141]
	s_nop 0
	v_lshl_add_u64 v[50:51], v[42:43], 0, v[142:143]
	v_cvt_pk_bf16_f32 v18, v18, v19
	v_cvt_pk_bf16_f32 v19, v20, v21
	v_cvt_pk_bf16_f32 v20, v10, v11
	v_add_u32_e32 v10, 0xb0, v150
	v_cvt_pk_bf16_f32 v101, v92, v93
	global_store_dwordx4 v[114:115], v[98:101], off offset:256
	v_mad_i64_i32 v[74:75], s[50:51], v74, s17, v[140:141]
	s_nop 0
	v_lshl_add_u64 v[98:99], v[90:91], 0, v[142:143]
	v_cvt_pk_bf16_f32 v37, v28, v29
	global_store_dwordx4 v[50:51], v[34:37], off offset:256
	v_mad_i64_i32 v[10:11], s[50:51], v10, s17, v[140:141]
	s_nop 0
	v_lshl_add_u64 v[34:35], v[26:27], 0, v[142:143]
	v_cvt_pk_bf16_f32 v85, v76, v77
	global_store_dwordx4 v[98:99], v[82:85], off offset:256
	v_cvt_pk_bf16_f32 v21, v12, v13
	global_store_dwordx4 v[34:35], v[18:21], off offset:256
	s_and_b64 vcc, exec, s[46:47]
	v_lshl_add_u64 v[82:83], v[74:75], 0, v[142:143]
	v_lshl_add_u64 v[18:19], v[10:11], 0, v[142:143]
	s_mov_b32 s40, s42
	s_mov_b32 s28, s8
	s_mov_b32 s43, s42
	s_mov_b32 s46, s8
	s_mov_b64 s[50:51], s[48:49]
	s_mov_b64 s[52:53], s[44:45]
	v_cvt_pk_bf16_f32 v126, v126, v127
	v_cvt_pk_bf16_f32 v127, v128, v129
	v_cvt_pk_bf16_f32 v128, v122, v123
	v_cvt_pk_bf16_f32 v129, v124, v125
	global_store_dwordx4 v[148:149], v[126:129], off
	v_cvt_pk_bf16_f32 v106, v118, v119
	v_cvt_pk_bf16_f32 v107, v120, v121
	v_cvt_pk_bf16_f32 v108, v110, v111
	v_cvt_pk_bf16_f32 v109, v112, v113
	global_store_dwordx4 v[114:115], v[106:109], off
	v_cvt_pk_bf16_f32 v90, v102, v103
	v_cvt_pk_bf16_f32 v91, v104, v105
	v_cvt_pk_bf16_f32 v92, v94, v95
	v_cvt_pk_bf16_f32 v93, v96, v97
	global_store_dwordx4 v[98:99], v[90:93], off
	v_cvt_pk_bf16_f32 v74, v86, v87
	v_cvt_pk_bf16_f32 v75, v88, v89
	v_cvt_pk_bf16_f32 v76, v78, v79
	v_cvt_pk_bf16_f32 v77, v80, v81
	global_store_dwordx4 v[82:83], v[74:77], off
	v_cvt_pk_bf16_f32 v73, v68, v69
	global_store_dwordx4 v[82:83], v[70:73], off offset:256
	v_cvt_pk_bf16_f32 v62, v62, v63
	v_cvt_pk_bf16_f32 v63, v64, v65
	v_cvt_pk_bf16_f32 v64, v58, v59
	v_cvt_pk_bf16_f32 v65, v60, v61
	global_store_dwordx4 v[66:67], v[62:65], off
	v_cvt_pk_bf16_f32 v42, v54, v55
	v_cvt_pk_bf16_f32 v43, v56, v57
	v_cvt_pk_bf16_f32 v44, v46, v47
	v_cvt_pk_bf16_f32 v45, v48, v49
	global_store_dwordx4 v[50:51], v[42:45], off
	v_cvt_pk_bf16_f32 v26, v38, v39
	v_cvt_pk_bf16_f32 v27, v40, v41
	v_cvt_pk_bf16_f32 v28, v30, v31
	v_cvt_pk_bf16_f32 v29, v32, v33
	global_store_dwordx4 v[34:35], v[26:29], off
	v_cvt_pk_bf16_f32 v10, v22, v23
	v_cvt_pk_bf16_f32 v11, v24, v25
	v_cvt_pk_bf16_f32 v12, v14, v15
	v_cvt_pk_bf16_f32 v13, v16, v17
	global_store_dwordx4 v[18:19], v[10:13], off
	v_cvt_pk_bf16_f32 v6, v6, v7
	v_cvt_pk_bf16_f32 v7, v8, v9
	v_cvt_pk_bf16_f32 v8, v2, v3
	v_cvt_pk_bf16_f32 v9, v4, v5
	global_store_dwordx4 v[18:19], v[6:9], off offset:256
	s_cbranch_vccz .LBB0_346
	s_waitcnt vmcnt(0)
	s_cmpk_gt_u32 s25, 0xff
	s_cbranch_scc1 .LBB0_358
	s_barrier
